# GEMM loops: vmcnt(8) and lgkmcnt(0) waits in front of each phase barrier merged into one s_waitcnt (64 sites)
# speedup vs baseline: 1.0026x; 1.0026x over previous
; #define PG8_STAGE(bufoff, gbase, voff) do { _Pragma("unroll") for (int _i = 0; _i < 2; ++_i) \
;         __builtin_amdgcn_global_load_lds((const unsigned*)((const char*)(gbase) + (voff)[_i]), (LAS unsigned*)(lds + (bufoff) + ldsw + _i * 8192), 16, 0, 0); } while (0)
; #define PG8_LDA(dst, b, h) do { _Pragma("unroll") for (int m = 0; m < 4; ++m) _Pragma("unroll") for (int k = 0; k < 2; ++k) dst[m][k] = *(const LAS bf16x8*)(lds + PG8_SA(b, h) + aoff + m * 2048 + k * 1024); } while (0)
; #define PG8_LDB(dst, b, h) do { _Pragma("unroll") for (int n = 0; n < 2; ++n) _Pragma("unroll") for (int k = 0; k < 2; ++k) dst[n][k] = *(const LAS bf16x8*)(lds + PG8_SB(b, h) + boff + n * 2048 + k * 1024); } while (0)
; #define PG8_WAIT_V(n) asm volatile("s_waitcnt vmcnt(" #n ")" ::: "memory")
; #define PG8_WAIT_L(n) asm volatile("s_waitcnt lgkmcnt(" #n ")" ::: "memory")
; #define PG8_BAR __builtin_amdgcn_s_barrier()
; #define PG8_SCHED __builtin_amdgcn_sched_barrier(0)
; template <class Epi, class Sched, bool SWAPD = false>
; __device__ __forceinline__ void gemm_phase(LAS unsigned char* lds, const Gemm g, const Sched& S, const Epi& E) {
;     ...
;         for (int t = 0; t < nt; t += 2) {
;             const bool last = (t == nt - 2);
;             const char* a1 = cA + (size_t)(t + 1) * kstepA;
;             const char* a2 = last ? nA : cA + (size_t)(t + 2) * kstepA; const char* b2 = last ? nB : cB + (size_t)(t + 2) * kstep;
;             const char* a3 = a2 + kstepA; const char* b3 = b2 + kstep;
;             PG8_LDB(B0, 0, 0); PG8_LDB(B1, 0, 1); PG8_SCHED; PG8_LDA(At, 0, 0); PG8_STAGE(PG8_SA(1, 1), a1 + hstepA, voffA);
;             PG8_WAIT_V(8); PG8_WAIT_L(0); PG8_BAR; PG8_MMA(0, 0, At, B0); PG8_MMA(0, 1, At, B1); PG8_BAR; PG8_SCHED;
;             PG8_LDA(At, 0, 1); PG8_STAGE(PG8_SB(0, 0), b2, voffB); PG8_STAGE(PG8_SB(0, 1), b2 + hstepB, voffB); PG8_STAGE(PG8_SA(0, 0), a2, voffA);
;             PG8_WAIT_V(8); PG8_WAIT_L(0); PG8_BAR; PG8_MMA(1, 0, At, B0); PG8_MMA(1, 1, At, B1); PG8_BAR; PG8_SCHED;
.LBB0_256:
	ds_read_b128 v[148:151], v145
	ds_read_b128 v[152:155], v145 offset:1024
	ds_read_b128 v[156:159], v145 offset:2048
	ds_read_b128 v[160:163], v145 offset:3072
	ds_read_b128 v[164:167], v146
	ds_read_b128 v[168:171], v146 offset:1024
	ds_read_b128 v[172:175], v146 offset:2048
	ds_read_b128 v[176:179], v146 offset:3072
	s_add_u32 s46, s44, 0xfffc0080
	s_addc_u32 s47, s45, -1
	s_cmp_eq_u32 s68, 12
	s_cselect_b32 s51, s13, s47
	s_cselect_b32 s50, s23, s46
	s_cselect_b32 s47, s64, s67
	s_cselect_b32 s46, s65, s66
	v_lshl_add_u64 v[140:141], s[44:45], 0, v[132:133]
	s_add_i32 m0, s31, 0xc000
	ds_read_b128 v[180:183], v147
	ds_read_b128 v[184:187], v147 offset:1024
	ds_read_b128 v[188:191], v147 offset:2048
	ds_read_b128 v[192:195], v147 offset:3072
	ds_read_b128 v[196:199], v147 offset:4096
	ds_read_b128 v[200:203], v147 offset:5120
	ds_read_b128 v[208:211], v147 offset:6144
	ds_read_b128 v[212:215], v147 offset:7168
	global_load_lds_dwordx4 v[140:141], off
	v_lshl_add_u64 v[140:141], s[44:45], 0, v[134:135]
	s_add_i32 m0, s31, 0xe000
	s_nop 0
	global_load_lds_dwordx4 v[140:141], off
	s_waitcnt vmcnt(8) lgkmcnt(0)
	s_barrier
	s_setprio 1
	v_mfma_f32_16x16x32_bf16 v[124:127], v[148:151], v[180:183], v[124:127]
	v_mfma_f32_16x16x32_bf16 v[116:119], v[156:159], v[180:183], v[116:119]
	v_mfma_f32_16x16x32_bf16 v[108:111], v[148:151], v[188:191], v[108:111]
	v_mfma_f32_16x16x32_bf16 v[100:103], v[156:159], v[188:191], v[100:103]
	v_mfma_f32_16x16x32_bf16 v[92:95], v[148:151], v[196:199], v[92:95]
	v_mfma_f32_16x16x32_bf16 v[84:87], v[156:159], v[196:199], v[84:87]
	v_mfma_f32_16x16x32_bf16 v[76:79], v[148:151], v[208:211], v[76:79]
	v_mfma_f32_16x16x32_bf16 v[68:71], v[156:159], v[208:211], v[68:71]
	v_mfma_f32_16x16x32_bf16 v[124:127], v[152:155], v[184:187], v[124:127]
	v_mfma_f32_16x16x32_bf16 v[116:119], v[160:163], v[184:187], v[116:119]
	v_mfma_f32_16x16x32_bf16 v[108:111], v[152:155], v[192:195], v[108:111]
	v_mfma_f32_16x16x32_bf16 v[100:103], v[160:163], v[192:195], v[100:103]
	v_mfma_f32_16x16x32_bf16 v[92:95], v[152:155], v[200:203], v[92:95]
	v_mfma_f32_16x16x32_bf16 v[84:87], v[160:163], v[200:203], v[84:87]
	v_mfma_f32_16x16x32_bf16 v[76:79], v[152:155], v[212:215], v[76:79]
	v_mfma_f32_16x16x32_bf16 v[68:71], v[160:163], v[212:215], v[68:71]
	s_setprio 0
	s_setprio 1
	v_mfma_f32_16x16x32_bf16 v[120:123], v[164:167], v[180:183], v[120:123]
	v_mfma_f32_16x16x32_bf16 v[112:115], v[172:175], v[180:183], v[112:115]
	v_mfma_f32_16x16x32_bf16 v[104:107], v[164:167], v[188:191], v[104:107]
	v_mfma_f32_16x16x32_bf16 v[96:99], v[172:175], v[188:191], v[96:99]
	v_mfma_f32_16x16x32_bf16 v[88:91], v[164:167], v[196:199], v[88:91]
	v_mfma_f32_16x16x32_bf16 v[80:83], v[172:175], v[196:199], v[80:83]
	v_mfma_f32_16x16x32_bf16 v[72:75], v[164:167], v[208:211], v[72:75]
	v_mfma_f32_16x16x32_bf16 v[64:67], v[172:175], v[208:211], v[64:67]
	v_mfma_f32_16x16x32_bf16 v[120:123], v[168:171], v[184:187], v[120:123]
	v_mfma_f32_16x16x32_bf16 v[112:115], v[176:179], v[184:187], v[112:115]
	v_mfma_f32_16x16x32_bf16 v[104:107], v[168:171], v[192:195], v[104:107]
	v_mfma_f32_16x16x32_bf16 v[96:99], v[176:179], v[192:195], v[96:99]
	v_mfma_f32_16x16x32_bf16 v[88:91], v[168:171], v[200:203], v[88:91]
	v_mfma_f32_16x16x32_bf16 v[80:83], v[176:179], v[200:203], v[80:83]
	v_mfma_f32_16x16x32_bf16 v[72:75], v[168:171], v[212:215], v[72:75]
	v_mfma_f32_16x16x32_bf16 v[64:67], v[176:179], v[212:215], v[64:67]
	s_setprio 0
	s_barrier
	s_add_i32 s69, s54, s11
	v_lshl_add_u64 v[140:141], s[46:47], 0, v[130:131]
	s_mov_b32 m0, s69
	ds_read_b128 v[180:183], v147 offset:16384
	ds_read_b128 v[184:187], v147 offset:17408
	ds_read_b128 v[188:191], v147 offset:18432
	ds_read_b128 v[192:195], v147 offset:19456
	ds_read_b128 v[196:199], v147 offset:20480
	ds_read_b128 v[200:203], v147 offset:21504
	ds_read_b128 v[208:211], v147 offset:22528
	ds_read_b128 v[212:215], v147 offset:23552
	global_load_lds_dwordx4 v[140:141], off
	s_add_i32 m0, s69, 0x2000
	s_add_u32 s72, s46, 0x40000
	v_lshl_add_u64 v[204:205], s[46:47], 0, v[128:129]
	s_addc_u32 s73, s47, 0
	s_add_i32 s69, s55, s11
	global_load_lds_dwordx4 v[204:205], off
	v_lshl_add_u64 v[216:217], s[72:73], 0, v[130:131]
	s_mov_b32 m0, s69
	v_lshl_add_u64 v[218:219], s[50:51], 0, v[128:129]
	global_load_lds_dwordx4 v[216:217], off
	v_lshl_add_u64 v[216:217], s[72:73], 0, v[128:129]
	s_add_i32 m0, s69, 0x2000
	s_nop 0
	global_load_lds_dwordx4 v[216:217], off
	v_lshl_add_u64 v[216:217], s[50:51], 0, v[130:131]
	s_mov_b32 m0, s31
	s_nop 0
	global_load_lds_dwordx4 v[216:217], off
	s_mov_b32 m0, s33
	s_nop 0
	global_load_lds_dwordx4 v[218:219], off
	s_waitcnt vmcnt(8) lgkmcnt(0)
	s_barrier
; #define PG8_STAGE(bufoff, gbase, voff) do { _Pragma("unroll") for (int _i = 0; _i < 2; ++_i) \
;         __builtin_amdgcn_global_load_lds((const unsigned*)((const char*)(gbase) + (voff)[_i]), (LAS unsigned*)(lds + (bufoff) + ldsw + _i * 8192), 16, 0, 0); } while (0)
; #define PG8_LDA(dst, b, h) do { _Pragma("unroll") for (int m = 0; m < 4; ++m) _Pragma("unroll") for (int k = 0; k < 2; ++k) dst[m][k] = *(const LAS bf16x8*)(lds + PG8_SA(b, h) + aoff + m * 2048 + k * 1024); } while (0)
; #define PG8_LDB(dst, b, h) do { _Pragma("unroll") for (int n = 0; n < 2; ++n) _Pragma("unroll") for (int k = 0; k < 2; ++k) dst[n][k] = *(const LAS bf16x8*)(lds + PG8_SB(b, h) + boff + n * 2048 + k * 1024); } while (0)
; #define PG8_WAIT_V(n) asm volatile("s_waitcnt vmcnt(" #n ")" ::: "memory")
; #define PG8_WAIT_L(n) asm volatile("s_waitcnt lgkmcnt(" #n ")" ::: "memory")
; #define PG8_BAR __builtin_amdgcn_s_barrier()
; #define PG8_SCHED __builtin_amdgcn_sched_barrier(0)
; template <class Epi, class Sched, bool SWAPD = false>
; __device__ __forceinline__ void gemm_phase(LAS unsigned char* lds, const Gemm g, const Sched& S, const Epi& E) {
;     ...
;             PG8_WAIT_V(8); PG8_WAIT_L(0); PG8_BAR; PG8_MMA(1, 0, At, B0); PG8_MMA(1, 1, At, B1); PG8_BAR; PG8_SCHED;
;             PG8_LDB(B0, 1, 0); PG8_LDB(B1, 1, 1); PG8_SCHED; PG8_LDA(At, 1, 0); PG8_STAGE(PG8_SA(0, 1), a2 + hstepA, voffA);
;             PG8_WAIT_V(8); PG8_WAIT_L(0); PG8_BAR; PG8_MMA(0, 0, At, B0); PG8_MMA(0, 1, At, B1); PG8_BAR; PG8_SCHED;
	s_setprio 1
	v_mfma_f32_16x16x32_bf16 v[60:63], v[148:151], v[180:183], v[60:63]
	v_mfma_f32_16x16x32_bf16 v[52:55], v[156:159], v[180:183], v[52:55]
	v_mfma_f32_16x16x32_bf16 v[44:47], v[148:151], v[188:191], v[44:47]
	v_mfma_f32_16x16x32_bf16 v[36:39], v[156:159], v[188:191], v[36:39]
	v_mfma_f32_16x16x32_bf16 v[28:31], v[148:151], v[196:199], v[28:31]
	v_mfma_f32_16x16x32_bf16 v[20:23], v[156:159], v[196:199], v[20:23]
	v_mfma_f32_16x16x32_bf16 v[12:15], v[148:151], v[208:211], v[12:15]
	v_mfma_f32_16x16x32_bf16 v[4:7], v[156:159], v[208:211], v[4:7]
	v_mfma_f32_16x16x32_bf16 v[60:63], v[152:155], v[184:187], v[60:63]
	v_mfma_f32_16x16x32_bf16 v[52:55], v[160:163], v[184:187], v[52:55]
	v_mfma_f32_16x16x32_bf16 v[44:47], v[152:155], v[192:195], v[44:47]
	v_mfma_f32_16x16x32_bf16 v[36:39], v[160:163], v[192:195], v[36:39]
	v_mfma_f32_16x16x32_bf16 v[28:31], v[152:155], v[200:203], v[28:31]
	v_mfma_f32_16x16x32_bf16 v[20:23], v[160:163], v[200:203], v[20:23]
	v_mfma_f32_16x16x32_bf16 v[12:15], v[152:155], v[212:215], v[12:15]
	v_mfma_f32_16x16x32_bf16 v[4:7], v[160:163], v[212:215], v[4:7]
	s_setprio 0
	s_setprio 1
	v_mfma_f32_16x16x32_bf16 v[56:59], v[164:167], v[180:183], v[56:59]
	v_mfma_f32_16x16x32_bf16 v[48:51], v[172:175], v[180:183], v[48:51]
	v_mfma_f32_16x16x32_bf16 v[40:43], v[164:167], v[188:191], v[40:43]
	v_mfma_f32_16x16x32_bf16 v[32:35], v[172:175], v[188:191], v[32:35]
	v_mfma_f32_16x16x32_bf16 v[24:27], v[164:167], v[196:199], v[24:27]
	v_mfma_f32_16x16x32_bf16 v[16:19], v[172:175], v[196:199], v[16:19]
	v_mfma_f32_16x16x32_bf16 v[8:11], v[164:167], v[208:211], v[8:11]
	v_mfma_f32_16x16x32_bf16 v[0:3], v[172:175], v[208:211], v[0:3]
	v_mfma_f32_16x16x32_bf16 v[56:59], v[168:171], v[184:187], v[56:59]
	v_mfma_f32_16x16x32_bf16 v[48:51], v[176:179], v[184:187], v[48:51]
	v_mfma_f32_16x16x32_bf16 v[40:43], v[168:171], v[192:195], v[40:43]
	v_mfma_f32_16x16x32_bf16 v[32:35], v[176:179], v[192:195], v[32:35]
	v_mfma_f32_16x16x32_bf16 v[24:27], v[168:171], v[200:203], v[24:27]
	v_mfma_f32_16x16x32_bf16 v[16:19], v[176:179], v[200:203], v[16:19]
	v_mfma_f32_16x16x32_bf16 v[8:11], v[168:171], v[212:215], v[8:11]
	v_mfma_f32_16x16x32_bf16 v[0:3], v[176:179], v[212:215], v[0:3]
	s_setprio 0
	s_barrier
	s_add_i32 s69, 0, 0x18000
	s_add_i32 s72, 0, 0x1c000
	v_add_u32_e32 v160, s69, v143
	v_add_u32_e32 v176, s72, v143
	ds_read_b128 v[148:151], v160
	ds_read_b128 v[152:155], v160 offset:1024
	ds_read_b128 v[156:159], v160 offset:2048
	ds_read_b128 v[160:163], v160 offset:3072
	ds_read_b128 v[164:167], v176
	ds_read_b128 v[168:171], v176 offset:1024
	ds_read_b128 v[172:175], v176 offset:2048
	ds_read_b128 v[176:179], v176 offset:3072
	s_add_u32 s50, s50, 0x40000
	s_addc_u32 s51, s51, 0
	s_mov_b32 m0, s34
	v_lshl_add_u64 v[220:221], s[50:51], 0, v[130:131]
	ds_read_b128 v[180:183], v147 offset:32768
	ds_read_b128 v[184:187], v147 offset:33792
	ds_read_b128 v[188:191], v147 offset:34816
	ds_read_b128 v[192:195], v147 offset:35840
	ds_read_b128 v[196:199], v147 offset:36864
	ds_read_b128 v[200:203], v147 offset:37888
	ds_read_b128 v[208:211], v147 offset:38912
	ds_read_b128 v[212:215], v147 offset:39936
	global_load_lds_dwordx4 v[220:221], off
	v_lshl_add_u64 v[220:221], s[50:51], 0, v[128:129]
	s_mov_b32 m0, s35
	s_nop 0
	global_load_lds_dwordx4 v[220:221], off
	s_waitcnt vmcnt(8) lgkmcnt(0)
	s_barrier
	s_setprio 1
	v_mfma_f32_16x16x32_bf16 v[124:127], v[148:151], v[180:183], v[124:127]
	v_mfma_f32_16x16x32_bf16 v[116:119], v[156:159], v[180:183], v[116:119]
	v_mfma_f32_16x16x32_bf16 v[108:111], v[148:151], v[188:191], v[108:111]
	v_mfma_f32_16x16x32_bf16 v[100:103], v[156:159], v[188:191], v[100:103]
	v_mfma_f32_16x16x32_bf16 v[92:95], v[148:151], v[196:199], v[92:95]
	v_mfma_f32_16x16x32_bf16 v[84:87], v[156:159], v[196:199], v[84:87]
	v_mfma_f32_16x16x32_bf16 v[76:79], v[148:151], v[208:211], v[76:79]
	v_mfma_f32_16x16x32_bf16 v[68:71], v[156:159], v[208:211], v[68:71]
	v_mfma_f32_16x16x32_bf16 v[124:127], v[152:155], v[184:187], v[124:127]
	v_mfma_f32_16x16x32_bf16 v[116:119], v[160:163], v[184:187], v[116:119]
	v_mfma_f32_16x16x32_bf16 v[108:111], v[152:155], v[192:195], v[108:111]
	v_mfma_f32_16x16x32_bf16 v[100:103], v[160:163], v[192:195], v[100:103]
	v_mfma_f32_16x16x32_bf16 v[92:95], v[152:155], v[200:203], v[92:95]
	v_mfma_f32_16x16x32_bf16 v[84:87], v[160:163], v[200:203], v[84:87]
	v_mfma_f32_16x16x32_bf16 v[76:79], v[152:155], v[212:215], v[76:79]
	v_mfma_f32_16x16x32_bf16 v[68:71], v[160:163], v[212:215], v[68:71]
	s_setprio 0
	s_setprio 1
	v_mfma_f32_16x16x32_bf16 v[120:123], v[164:167], v[180:183], v[120:123]
	v_mfma_f32_16x16x32_bf16 v[112:115], v[172:175], v[180:183], v[112:115]
	v_mfma_f32_16x16x32_bf16 v[104:107], v[164:167], v[188:191], v[104:107]
	v_mfma_f32_16x16x32_bf16 v[96:99], v[172:175], v[188:191], v[96:99]
	v_mfma_f32_16x16x32_bf16 v[88:91], v[164:167], v[196:199], v[88:91]
	v_mfma_f32_16x16x32_bf16 v[80:83], v[172:175], v[196:199], v[80:83]
	v_mfma_f32_16x16x32_bf16 v[72:75], v[164:167], v[208:211], v[72:75]
	v_mfma_f32_16x16x32_bf16 v[64:67], v[172:175], v[208:211], v[64:67]
	v_mfma_f32_16x16x32_bf16 v[120:123], v[168:171], v[184:187], v[120:123]
	v_mfma_f32_16x16x32_bf16 v[112:115], v[176:179], v[184:187], v[112:115]
	v_mfma_f32_16x16x32_bf16 v[104:107], v[168:171], v[192:195], v[104:107]
	v_mfma_f32_16x16x32_bf16 v[96:99], v[176:179], v[192:195], v[96:99]
	v_mfma_f32_16x16x32_bf16 v[88:91], v[168:171], v[200:203], v[88:91]
	v_mfma_f32_16x16x32_bf16 v[80:83], v[176:179], v[200:203], v[80:83]
	v_mfma_f32_16x16x32_bf16 v[72:75], v[168:171], v[212:215], v[72:75]
	v_mfma_f32_16x16x32_bf16 v[64:67], v[176:179], v[212:215], v[64:67]
	s_setprio 0
	s_barrier
; #define PG8_STAGE(bufoff, gbase, voff) do { _Pragma("unroll") for (int _i = 0; _i < 2; ++_i) \
;         __builtin_amdgcn_global_load_lds((const unsigned*)((const char*)(gbase) + (voff)[_i]), (LAS unsigned*)(lds + (bufoff) + ldsw + _i * 8192), 16, 0, 0); } while (0)
; #define PG8_LDA(dst, b, h) do { _Pragma("unroll") for (int m = 0; m < 4; ++m) _Pragma("unroll") for (int k = 0; k < 2; ++k) dst[m][k] = *(const LAS bf16x8*)(lds + PG8_SA(b, h) + aoff + m * 2048 + k * 1024); } while (0)
; #define PG8_WAIT_V(n) asm volatile("s_waitcnt vmcnt(" #n ")" ::: "memory")
; #define PG8_WAIT_L(n) asm volatile("s_waitcnt lgkmcnt(" #n ")" ::: "memory")
; #define PG8_BAR __builtin_amdgcn_s_barrier()
; #define PG8_SCHED __builtin_amdgcn_sched_barrier(0)
; template <class Epi, class Sched, bool SWAPD = false>
; __device__ __forceinline__ void gemm_phase(LAS unsigned char* lds, const Gemm g, const Sched& S, const Epi& E) {
;     ...
;             PG8_LDA(At, 1, 1); PG8_STAGE(PG8_SB(1, 0), b3, voffB); PG8_STAGE(PG8_SB(1, 1), b3 + hstepB, voffB); PG8_STAGE(PG8_SA(1, 0), a3, voffA);
;             PG8_WAIT_V(8); PG8_WAIT_L(0); PG8_BAR; PG8_MMA(1, 0, At, B0); PG8_MMA(1, 1, At, B1); PG8_BAR; PG8_SCHED;
;         }
;         if (wr == 0) PG8_BAR;
	s_add_i32 s50, s69, s11
	v_lshl_add_u64 v[140:141], v[140:141], 0, s[6:7]
	s_mov_b32 m0, s50
	ds_read_b128 v[180:183], v147 offset:49152
	ds_read_b128 v[184:187], v147 offset:50176
	ds_read_b128 v[188:191], v147 offset:51200
	ds_read_b128 v[192:195], v147 offset:52224
	ds_read_b128 v[196:199], v147 offset:53248
	ds_read_b128 v[200:203], v147 offset:54272
	ds_read_b128 v[208:211], v147 offset:55296
	ds_read_b128 v[212:215], v147 offset:56320
	global_load_lds_dwordx4 v[140:141], off
	s_add_i32 m0, s50, 0x2000
	s_add_u32 s46, s46, 0x40080
	v_lshl_add_u64 v[140:141], v[204:205], 0, s[6:7]
	s_addc_u32 s47, s47, 0
	s_add_i32 s50, s72, s11
	global_load_lds_dwordx4 v[140:141], off
	v_lshl_add_u64 v[140:141], s[46:47], 0, v[130:131]
	s_mov_b32 m0, s50
	s_nop 0
	global_load_lds_dwordx4 v[140:141], off
	v_lshl_add_u64 v[140:141], s[46:47], 0, v[128:129]
	s_add_i32 m0, s50, 0x2000
	s_nop 0
	global_load_lds_dwordx4 v[140:141], off
	v_lshl_add_u64 v[140:141], v[216:217], 0, s[6:7]
	s_mov_b32 m0, s52
	s_nop 0
	global_load_lds_dwordx4 v[140:141], off
	v_lshl_add_u64 v[140:141], v[218:219], 0, s[6:7]
	s_mov_b32 m0, s53
	s_nop 0
	global_load_lds_dwordx4 v[140:141], off
	s_waitcnt vmcnt(8) lgkmcnt(0)
	s_barrier
	s_setprio 1
	v_mfma_f32_16x16x32_bf16 v[60:63], v[148:151], v[180:183], v[60:63]
	v_mfma_f32_16x16x32_bf16 v[52:55], v[156:159], v[180:183], v[52:55]
	v_mfma_f32_16x16x32_bf16 v[44:47], v[148:151], v[188:191], v[44:47]
	v_mfma_f32_16x16x32_bf16 v[36:39], v[156:159], v[188:191], v[36:39]
	v_mfma_f32_16x16x32_bf16 v[28:31], v[148:151], v[196:199], v[28:31]
	v_mfma_f32_16x16x32_bf16 v[20:23], v[156:159], v[196:199], v[20:23]
	v_mfma_f32_16x16x32_bf16 v[12:15], v[148:151], v[208:211], v[12:15]
	v_mfma_f32_16x16x32_bf16 v[4:7], v[156:159], v[208:211], v[4:7]
	v_mfma_f32_16x16x32_bf16 v[60:63], v[152:155], v[184:187], v[60:63]
	v_mfma_f32_16x16x32_bf16 v[52:55], v[160:163], v[184:187], v[52:55]
	v_mfma_f32_16x16x32_bf16 v[44:47], v[152:155], v[192:195], v[44:47]
	v_mfma_f32_16x16x32_bf16 v[36:39], v[160:163], v[192:195], v[36:39]
	v_mfma_f32_16x16x32_bf16 v[28:31], v[152:155], v[200:203], v[28:31]
	v_mfma_f32_16x16x32_bf16 v[20:23], v[160:163], v[200:203], v[20:23]
	v_mfma_f32_16x16x32_bf16 v[12:15], v[152:155], v[212:215], v[12:15]
	v_mfma_f32_16x16x32_bf16 v[4:7], v[160:163], v[212:215], v[4:7]
	s_setprio 0
	s_setprio 1
	v_mfma_f32_16x16x32_bf16 v[56:59], v[164:167], v[180:183], v[56:59]
	v_mfma_f32_16x16x32_bf16 v[48:51], v[172:175], v[180:183], v[48:51]
	v_mfma_f32_16x16x32_bf16 v[40:43], v[164:167], v[188:191], v[40:43]
	v_mfma_f32_16x16x32_bf16 v[32:35], v[172:175], v[188:191], v[32:35]
	v_mfma_f32_16x16x32_bf16 v[24:27], v[164:167], v[196:199], v[24:27]
	v_mfma_f32_16x16x32_bf16 v[16:19], v[172:175], v[196:199], v[16:19]
	v_mfma_f32_16x16x32_bf16 v[8:11], v[164:167], v[208:211], v[8:11]
	v_mfma_f32_16x16x32_bf16 v[0:3], v[172:175], v[208:211], v[0:3]
	v_mfma_f32_16x16x32_bf16 v[56:59], v[168:171], v[184:187], v[56:59]
	v_mfma_f32_16x16x32_bf16 v[48:51], v[176:179], v[184:187], v[48:51]
	v_mfma_f32_16x16x32_bf16 v[40:43], v[168:171], v[192:195], v[40:43]
	v_mfma_f32_16x16x32_bf16 v[32:35], v[176:179], v[192:195], v[32:35]
	v_mfma_f32_16x16x32_bf16 v[24:27], v[168:171], v[200:203], v[24:27]
	v_mfma_f32_16x16x32_bf16 v[16:19], v[176:179], v[200:203], v[16:19]
	v_mfma_f32_16x16x32_bf16 v[8:11], v[168:171], v[212:215], v[8:11]
	v_mfma_f32_16x16x32_bf16 v[0:3], v[176:179], v[212:215], v[0:3]
	s_setprio 0
	s_barrier
	s_add_i32 s68, s68, 2
	s_add_u32 s44, s44, 0x100
	s_addc_u32 s45, s45, 0
	s_add_u32 s66, s66, 0x100
	s_addc_u32 s67, s67, 0
	s_cmp_gt_u32 s68, 13
	s_cbranch_scc0 .LBB0_256
	s_and_b64 vcc, exec, s[8:9]
	s_cbranch_vccz .LBB0_259
	s_barrier

; #define PG8_STAGE(bufoff, gbase, voff) do { _Pragma("unroll") for (int _i = 0; _i < 2; ++_i) \
;         __builtin_amdgcn_global_load_lds((const unsigned*)((const char*)(gbase) + (voff)[_i]), (LAS unsigned*)(lds + (bufoff) + ldsw + _i * 8192), 16, 0, 0); } while (0)
; #define PG8_LDA(dst, b, h) do { _Pragma("unroll") for (int m = 0; m < 4; ++m) _Pragma("unroll") for (int k = 0; k < 2; ++k) dst[m][k] = *(const LAS bf16x8*)(lds + PG8_SA(b, h) + aoff + m * 2048 + k * 1024); } while (0)
; #define PG8_LDB(dst, b, h) do { _Pragma("unroll") for (int n = 0; n < 2; ++n) _Pragma("unroll") for (int k = 0; k < 2; ++k) dst[n][k] = *(const LAS bf16x8*)(lds + PG8_SB(b, h) + boff + n * 2048 + k * 1024); } while (0)
; #define PG8_WAIT_V(n) asm volatile("s_waitcnt vmcnt(" #n ")" ::: "memory")
; #define PG8_WAIT_L(n) asm volatile("s_waitcnt lgkmcnt(" #n ")" ::: "memory")
; #define PG8_BAR __builtin_amdgcn_s_barrier()
; #define PG8_SCHED __builtin_amdgcn_sched_barrier(0)
; template <class Epi, class Sched, bool SWAPD = false>
; __device__ __forceinline__ void gemm_phase(LAS unsigned char* lds, const Gemm g, const Sched& S, const Epi& E) {
;     ...
;         for (int t = 0; t < nt; t += 2) {
;             const bool last = (t == nt - 2);
;             const char* a1 = cA + (size_t)(t + 1) * kstepA;
;             const char* a2 = last ? nA : cA + (size_t)(t + 2) * kstepA; const char* b2 = last ? nB : cB + (size_t)(t + 2) * kstep;
;             const char* a3 = a2 + kstepA; const char* b3 = b2 + kstep;
;             PG8_LDB(B0, 0, 0); PG8_LDB(B1, 0, 1); PG8_SCHED; PG8_LDA(At, 0, 0); PG8_STAGE(PG8_SA(1, 1), a1 + hstepA, voffA);
;             PG8_WAIT_V(8); PG8_WAIT_L(0); PG8_BAR; PG8_MMA(0, 0, At, B0); PG8_MMA(0, 1, At, B1); PG8_BAR; PG8_SCHED;
;             PG8_LDA(At, 0, 1); PG8_STAGE(PG8_SB(0, 0), b2, voffB); PG8_STAGE(PG8_SB(0, 1), b2 + hstepB, voffB); PG8_STAGE(PG8_SA(0, 0), a2, voffA);
;             PG8_WAIT_V(8); PG8_WAIT_L(0); PG8_BAR; PG8_MMA(1, 0, At, B0); PG8_MMA(1, 1, At, B1); PG8_BAR; PG8_SCHED;
.LBB0_353:
	v_add_u32_e32 v132, s57, v184
	ds_read_b128 v[174:177], v132
	ds_read_b128 v[178:181], v132 offset:1024
	ds_read_b128 v[188:191], v132 offset:2048
	ds_read_b128 v[192:195], v132 offset:3072
	v_add_u32_e32 v132, s64, v184
	ds_read_b128 v[196:199], v132
	ds_read_b128 v[200:203], v132 offset:1024
	ds_read_b128 v[208:211], v132 offset:2048
	ds_read_b128 v[212:215], v132 offset:3072
	s_add_i32 s77, s44, 2
	s_add_u32 s42, s38, 0x100
	s_addc_u32 s43, s39, 0
	s_cmp_eq_u32 s74, s44
	s_cselect_b32 s44, s35, s75
	s_cselect_b32 s47, s29, s43
	s_cselect_b32 s46, s33, s42
	s_cselect_b32 s45, s34, s76
	v_lshl_add_u64 v[182:183], s[38:39], 0, v[166:167]
	s_add_i32 m0, s30, 0xc000
	ds_read_b128 v[216:219], v186
	ds_read_b128 v[220:223], v186 offset:1024
	ds_read_b128 v[224:227], v186 offset:2048
	ds_read_b128 v[228:231], v186 offset:3072
	ds_read_b128 v[232:235], v186 offset:4096
	ds_read_b128 v[236:239], v186 offset:5120
	ds_read_b128 v[240:243], v186 offset:6144
	ds_read_b128 v[244:247], v186 offset:7168
	global_load_lds_dwordx4 v[182:183], off
	v_lshl_add_u64 v[182:183], s[38:39], 0, v[168:169]
	s_add_i32 m0, s30, 0xe000
	s_nop 0
	global_load_lds_dwordx4 v[182:183], off
	s_waitcnt vmcnt(8) lgkmcnt(0)
	s_barrier
	s_setprio 1
	v_mfma_f32_16x16x32_bf16 v[124:127], v[174:177], v[216:219], v[124:127]
	v_mfma_f32_16x16x32_bf16 v[120:123], v[188:191], v[216:219], v[120:123]
	v_mfma_f32_16x16x32_bf16 v[108:111], v[174:177], v[224:227], v[108:111]
	v_mfma_f32_16x16x32_bf16 v[104:107], v[188:191], v[224:227], v[104:107]
	v_mfma_f32_16x16x32_bf16 v[92:95], v[174:177], v[232:235], v[92:95]
	v_mfma_f32_16x16x32_bf16 v[88:91], v[188:191], v[232:235], v[88:91]
	v_mfma_f32_16x16x32_bf16 v[76:79], v[174:177], v[240:243], v[76:79]
	v_mfma_f32_16x16x32_bf16 v[72:75], v[188:191], v[240:243], v[72:75]
	v_mfma_f32_16x16x32_bf16 v[124:127], v[178:181], v[220:223], v[124:127]
	v_mfma_f32_16x16x32_bf16 v[120:123], v[192:195], v[220:223], v[120:123]
	v_mfma_f32_16x16x32_bf16 v[108:111], v[178:181], v[228:231], v[108:111]
	v_mfma_f32_16x16x32_bf16 v[104:107], v[192:195], v[228:231], v[104:107]
	v_mfma_f32_16x16x32_bf16 v[92:95], v[178:181], v[236:239], v[92:95]
	v_mfma_f32_16x16x32_bf16 v[88:91], v[192:195], v[236:239], v[88:91]
	v_mfma_f32_16x16x32_bf16 v[76:79], v[178:181], v[244:247], v[76:79]
	v_mfma_f32_16x16x32_bf16 v[72:75], v[192:195], v[244:247], v[72:75]
	s_setprio 0
	s_setprio 1
	v_mfma_f32_16x16x32_bf16 v[116:119], v[196:199], v[216:219], v[116:119]
	v_mfma_f32_16x16x32_bf16 v[112:115], v[208:211], v[216:219], v[112:115]
	v_mfma_f32_16x16x32_bf16 v[100:103], v[196:199], v[224:227], v[100:103]
	v_mfma_f32_16x16x32_bf16 v[96:99], v[208:211], v[224:227], v[96:99]
	v_mfma_f32_16x16x32_bf16 v[84:87], v[196:199], v[232:235], v[84:87]
	v_mfma_f32_16x16x32_bf16 v[80:83], v[208:211], v[232:235], v[80:83]
	v_mfma_f32_16x16x32_bf16 v[68:71], v[196:199], v[240:243], v[68:71]
	v_mfma_f32_16x16x32_bf16 v[64:67], v[208:211], v[240:243], v[64:67]
	v_mfma_f32_16x16x32_bf16 v[116:119], v[200:203], v[220:223], v[116:119]
	v_mfma_f32_16x16x32_bf16 v[112:115], v[212:215], v[220:223], v[112:115]
	v_mfma_f32_16x16x32_bf16 v[100:103], v[200:203], v[228:231], v[100:103]
	v_mfma_f32_16x16x32_bf16 v[96:99], v[212:215], v[228:231], v[96:99]
	v_mfma_f32_16x16x32_bf16 v[84:87], v[200:203], v[236:239], v[84:87]
	v_mfma_f32_16x16x32_bf16 v[80:83], v[212:215], v[236:239], v[80:83]
	v_mfma_f32_16x16x32_bf16 v[68:71], v[200:203], v[244:247], v[68:71]
	v_mfma_f32_16x16x32_bf16 v[64:67], v[212:215], v[244:247], v[64:67]
	s_setprio 0
	s_barrier
	s_add_i32 s38, s57, s21
	v_lshl_add_u64 v[182:183], s[44:45], 0, v[128:129]
	s_mov_b32 m0, s38
	ds_read_b128 v[216:219], v186 offset:16384
	ds_read_b128 v[220:223], v186 offset:17408
	ds_read_b128 v[224:227], v186 offset:18432
	ds_read_b128 v[228:231], v186 offset:19456
	ds_read_b128 v[232:235], v186 offset:20480
	ds_read_b128 v[236:239], v186 offset:21504
	ds_read_b128 v[240:243], v186 offset:22528
	ds_read_b128 v[244:247], v186 offset:23552
	global_load_lds_dwordx4 v[182:183], off
	s_add_i32 m0, s38, 0x2000
	s_add_u32 s38, s44, 0xb0000
	v_lshl_add_u64 v[204:205], s[44:45], 0, v[130:131]
	s_addc_u32 s39, s45, 0
	s_add_i32 s78, s64, s21
	global_load_lds_dwordx4 v[204:205], off
	v_lshl_add_u64 v[248:249], s[38:39], 0, v[128:129]
	s_mov_b32 m0, s78
	v_lshl_add_u64 v[250:251], s[46:47], 0, v[130:131]
	global_load_lds_dwordx4 v[248:249], off
	v_lshl_add_u64 v[248:249], s[38:39], 0, v[130:131]
	s_add_i32 m0, s78, 0x2000
	s_nop 0
	global_load_lds_dwordx4 v[248:249], off
	v_lshl_add_u64 v[248:249], s[46:47], 0, v[128:129]
	s_mov_b32 m0, s30
	s_nop 0
	global_load_lds_dwordx4 v[248:249], off
	s_mov_b32 m0, s31
	s_nop 0
	global_load_lds_dwordx4 v[250:251], off
	s_waitcnt vmcnt(8) lgkmcnt(0)
	s_barrier
; #define PG8_STAGE(bufoff, gbase, voff) do { _Pragma("unroll") for (int _i = 0; _i < 2; ++_i) \
;         __builtin_amdgcn_global_load_lds((const unsigned*)((const char*)(gbase) + (voff)[_i]), (LAS unsigned*)(lds + (bufoff) + ldsw + _i * 8192), 16, 0, 0); } while (0)
; #define PG8_LDA(dst, b, h) do { _Pragma("unroll") for (int m = 0; m < 4; ++m) _Pragma("unroll") for (int k = 0; k < 2; ++k) dst[m][k] = *(const LAS bf16x8*)(lds + PG8_SA(b, h) + aoff + m * 2048 + k * 1024); } while (0)
; #define PG8_LDB(dst, b, h) do { _Pragma("unroll") for (int n = 0; n < 2; ++n) _Pragma("unroll") for (int k = 0; k < 2; ++k) dst[n][k] = *(const LAS bf16x8*)(lds + PG8_SB(b, h) + boff + n * 2048 + k * 1024); } while (0)
; #define PG8_WAIT_V(n) asm volatile("s_waitcnt vmcnt(" #n ")" ::: "memory")
; #define PG8_WAIT_L(n) asm volatile("s_waitcnt lgkmcnt(" #n ")" ::: "memory")
; #define PG8_BAR __builtin_amdgcn_s_barrier()
; #define PG8_SCHED __builtin_amdgcn_sched_barrier(0)
; template <class Epi, class Sched, bool SWAPD = false>
; __device__ __forceinline__ void gemm_phase(LAS unsigned char* lds, const Gemm g, const Sched& S, const Epi& E) {
;     ...
;             PG8_WAIT_V(8); PG8_WAIT_L(0); PG8_BAR; PG8_MMA(1, 0, At, B0); PG8_MMA(1, 1, At, B1); PG8_BAR; PG8_SCHED;
;             PG8_LDB(B0, 1, 0); PG8_LDB(B1, 1, 1); PG8_SCHED; PG8_LDA(At, 1, 0); PG8_STAGE(PG8_SA(0, 1), a2 + hstepA, voffA);
;             PG8_WAIT_V(8); PG8_WAIT_L(0); PG8_BAR; PG8_MMA(0, 0, At, B0); PG8_MMA(0, 1, At, B1); PG8_BAR; PG8_SCHED;
	s_setprio 1
	v_mfma_f32_16x16x32_bf16 v[60:63], v[174:177], v[216:219], v[60:63]
	v_mfma_f32_16x16x32_bf16 v[56:59], v[188:191], v[216:219], v[56:59]
	v_mfma_f32_16x16x32_bf16 v[44:47], v[174:177], v[224:227], v[44:47]
	v_mfma_f32_16x16x32_bf16 v[40:43], v[188:191], v[224:227], v[40:43]
	v_mfma_f32_16x16x32_bf16 v[28:31], v[174:177], v[232:235], v[28:31]
	v_mfma_f32_16x16x32_bf16 v[24:27], v[188:191], v[232:235], v[24:27]
	v_mfma_f32_16x16x32_bf16 v[12:15], v[174:177], v[240:243], v[12:15]
	v_mfma_f32_16x16x32_bf16 v[8:11], v[188:191], v[240:243], v[8:11]
	v_mfma_f32_16x16x32_bf16 v[60:63], v[178:181], v[220:223], v[60:63]
	v_mfma_f32_16x16x32_bf16 v[56:59], v[192:195], v[220:223], v[56:59]
	v_mfma_f32_16x16x32_bf16 v[44:47], v[178:181], v[228:231], v[44:47]
	v_mfma_f32_16x16x32_bf16 v[40:43], v[192:195], v[228:231], v[40:43]
	v_mfma_f32_16x16x32_bf16 v[28:31], v[178:181], v[236:239], v[28:31]
	v_mfma_f32_16x16x32_bf16 v[24:27], v[192:195], v[236:239], v[24:27]
	v_mfma_f32_16x16x32_bf16 v[12:15], v[178:181], v[244:247], v[12:15]
	v_mfma_f32_16x16x32_bf16 v[8:11], v[192:195], v[244:247], v[8:11]
	s_setprio 0
	s_setprio 1
	v_mfma_f32_16x16x32_bf16 v[52:55], v[196:199], v[216:219], v[52:55]
	v_mfma_f32_16x16x32_bf16 v[48:51], v[208:211], v[216:219], v[48:51]
	v_mfma_f32_16x16x32_bf16 v[36:39], v[196:199], v[224:227], v[36:39]
	v_mfma_f32_16x16x32_bf16 v[32:35], v[208:211], v[224:227], v[32:35]
	v_mfma_f32_16x16x32_bf16 v[20:23], v[196:199], v[232:235], v[20:23]
	v_mfma_f32_16x16x32_bf16 v[16:19], v[208:211], v[232:235], v[16:19]
	v_mfma_f32_16x16x32_bf16 v[4:7], v[196:199], v[240:243], v[4:7]
	v_mfma_f32_16x16x32_bf16 v[0:3], v[208:211], v[240:243], v[0:3]
	v_mfma_f32_16x16x32_bf16 v[52:55], v[200:203], v[220:223], v[52:55]
	v_mfma_f32_16x16x32_bf16 v[48:51], v[212:215], v[220:223], v[48:51]
	v_mfma_f32_16x16x32_bf16 v[36:39], v[200:203], v[228:231], v[36:39]
	v_mfma_f32_16x16x32_bf16 v[32:35], v[212:215], v[228:231], v[32:35]
	v_mfma_f32_16x16x32_bf16 v[20:23], v[200:203], v[236:239], v[20:23]
	v_mfma_f32_16x16x32_bf16 v[16:19], v[212:215], v[236:239], v[16:19]
	v_mfma_f32_16x16x32_bf16 v[4:7], v[200:203], v[244:247], v[4:7]
	v_mfma_f32_16x16x32_bf16 v[0:3], v[212:215], v[244:247], v[0:3]
	s_setprio 0
	s_barrier
	s_add_i32 s78, 0, 0x18000
	v_add_u32_e32 v132, s78, v184
	s_add_i32 s79, 0, 0x1c000
	ds_read_b128 v[174:177], v132
	ds_read_b128 v[178:181], v132 offset:1024
	ds_read_b128 v[188:191], v132 offset:2048
	ds_read_b128 v[192:195], v132 offset:3072
	v_add_u32_e32 v132, s79, v184
	ds_read_b128 v[196:199], v132
	ds_read_b128 v[200:203], v132 offset:1024
	ds_read_b128 v[208:211], v132 offset:2048
	ds_read_b128 v[212:215], v132 offset:3072
	s_add_u32 s38, s46, 0xb0000
	s_addc_u32 s39, s47, 0
	s_mov_b32 m0, s50
	v_lshl_add_u64 v[252:253], s[38:39], 0, v[128:129]
	ds_read_b128 v[216:219], v186 offset:32768
	ds_read_b128 v[220:223], v186 offset:33792
	ds_read_b128 v[224:227], v186 offset:34816
	ds_read_b128 v[228:231], v186 offset:35840
	ds_read_b128 v[232:235], v186 offset:36864
	ds_read_b128 v[236:239], v186 offset:37888
	ds_read_b128 v[240:243], v186 offset:38912
	ds_read_b128 v[244:247], v186 offset:39936
	global_load_lds_dwordx4 v[252:253], off
	v_lshl_add_u64 v[252:253], s[38:39], 0, v[130:131]
	s_mov_b32 m0, s51
	s_nop 0
	global_load_lds_dwordx4 v[252:253], off
	s_waitcnt vmcnt(8) lgkmcnt(0)
	s_barrier
	s_setprio 1
	v_mfma_f32_16x16x32_bf16 v[124:127], v[174:177], v[216:219], v[124:127]
	v_mfma_f32_16x16x32_bf16 v[120:123], v[188:191], v[216:219], v[120:123]
	v_mfma_f32_16x16x32_bf16 v[108:111], v[174:177], v[224:227], v[108:111]
	v_mfma_f32_16x16x32_bf16 v[104:107], v[188:191], v[224:227], v[104:107]
	v_mfma_f32_16x16x32_bf16 v[92:95], v[174:177], v[232:235], v[92:95]
	v_mfma_f32_16x16x32_bf16 v[88:91], v[188:191], v[232:235], v[88:91]
	v_mfma_f32_16x16x32_bf16 v[76:79], v[174:177], v[240:243], v[76:79]
	v_mfma_f32_16x16x32_bf16 v[72:75], v[188:191], v[240:243], v[72:75]
	v_mfma_f32_16x16x32_bf16 v[124:127], v[178:181], v[220:223], v[124:127]
	v_mfma_f32_16x16x32_bf16 v[120:123], v[192:195], v[220:223], v[120:123]
	v_mfma_f32_16x16x32_bf16 v[108:111], v[178:181], v[228:231], v[108:111]
	v_mfma_f32_16x16x32_bf16 v[104:107], v[192:195], v[228:231], v[104:107]
	v_mfma_f32_16x16x32_bf16 v[92:95], v[178:181], v[236:239], v[92:95]
	v_mfma_f32_16x16x32_bf16 v[88:91], v[192:195], v[236:239], v[88:91]
	v_mfma_f32_16x16x32_bf16 v[76:79], v[178:181], v[244:247], v[76:79]
	v_mfma_f32_16x16x32_bf16 v[72:75], v[192:195], v[244:247], v[72:75]
	s_setprio 0
	s_setprio 1
	v_mfma_f32_16x16x32_bf16 v[116:119], v[196:199], v[216:219], v[116:119]
	v_mfma_f32_16x16x32_bf16 v[112:115], v[208:211], v[216:219], v[112:115]
	v_mfma_f32_16x16x32_bf16 v[100:103], v[196:199], v[224:227], v[100:103]
	v_mfma_f32_16x16x32_bf16 v[96:99], v[208:211], v[224:227], v[96:99]
	v_mfma_f32_16x16x32_bf16 v[84:87], v[196:199], v[232:235], v[84:87]
	v_mfma_f32_16x16x32_bf16 v[80:83], v[208:211], v[232:235], v[80:83]
	v_mfma_f32_16x16x32_bf16 v[68:71], v[196:199], v[240:243], v[68:71]
	v_mfma_f32_16x16x32_bf16 v[64:67], v[208:211], v[240:243], v[64:67]
	v_mfma_f32_16x16x32_bf16 v[116:119], v[200:203], v[220:223], v[116:119]
	v_mfma_f32_16x16x32_bf16 v[112:115], v[212:215], v[220:223], v[112:115]
	v_mfma_f32_16x16x32_bf16 v[100:103], v[200:203], v[228:231], v[100:103]
	v_mfma_f32_16x16x32_bf16 v[96:99], v[212:215], v[228:231], v[96:99]
	v_mfma_f32_16x16x32_bf16 v[84:87], v[200:203], v[236:239], v[84:87]
	v_mfma_f32_16x16x32_bf16 v[80:83], v[212:215], v[236:239], v[80:83]
	v_mfma_f32_16x16x32_bf16 v[68:71], v[200:203], v[244:247], v[68:71]
	v_mfma_f32_16x16x32_bf16 v[64:67], v[212:215], v[244:247], v[64:67]
	s_setprio 0
	s_barrier
; #define PG8_STAGE(bufoff, gbase, voff) do { _Pragma("unroll") for (int _i = 0; _i < 2; ++_i) \
;         __builtin_amdgcn_global_load_lds((const unsigned*)((const char*)(gbase) + (voff)[_i]), (LAS unsigned*)(lds + (bufoff) + ldsw + _i * 8192), 16, 0, 0); } while (0)
; #define PG8_LDA(dst, b, h) do { _Pragma("unroll") for (int m = 0; m < 4; ++m) _Pragma("unroll") for (int k = 0; k < 2; ++k) dst[m][k] = *(const LAS bf16x8*)(lds + PG8_SA(b, h) + aoff + m * 2048 + k * 1024); } while (0)
; #define PG8_WAIT_V(n) asm volatile("s_waitcnt vmcnt(" #n ")" ::: "memory")
; #define PG8_WAIT_L(n) asm volatile("s_waitcnt lgkmcnt(" #n ")" ::: "memory")
; #define PG8_BAR __builtin_amdgcn_s_barrier()
; #define PG8_SCHED __builtin_amdgcn_sched_barrier(0)
; template <class Epi, class Sched, bool SWAPD = false>
; __device__ __forceinline__ void gemm_phase(LAS unsigned char* lds, const Gemm g, const Sched& S, const Epi& E) {
;     ...
;             PG8_LDA(At, 1, 1); PG8_STAGE(PG8_SB(1, 0), b3, voffB); PG8_STAGE(PG8_SB(1, 1), b3 + hstepB, voffB); PG8_STAGE(PG8_SA(1, 0), a3, voffA);
;             PG8_WAIT_V(8); PG8_WAIT_L(0); PG8_BAR; PG8_MMA(1, 0, At, B0); PG8_MMA(1, 1, At, B1); PG8_BAR; PG8_SCHED;
;         }
;         if (wr == 0) PG8_BAR;
	s_add_i32 s38, s78, s21
	v_lshl_add_u64 v[182:183], v[182:183], 0, s[8:9]
	s_mov_b32 m0, s38
	ds_read_b128 v[216:219], v186 offset:49152
	ds_read_b128 v[220:223], v186 offset:50176
	ds_read_b128 v[224:227], v186 offset:51200
	ds_read_b128 v[228:231], v186 offset:52224
	ds_read_b128 v[232:235], v186 offset:53248
	ds_read_b128 v[236:239], v186 offset:54272
	ds_read_b128 v[240:243], v186 offset:55296
	ds_read_b128 v[244:247], v186 offset:56320
	global_load_lds_dwordx4 v[182:183], off
	s_add_i32 m0, s38, 0x2000
	s_add_u32 s38, s44, 0xb0080
	v_lshl_add_u64 v[182:183], v[204:205], 0, s[8:9]
	s_addc_u32 s39, s45, 0
	s_add_i32 s44, s79, s21
	global_load_lds_dwordx4 v[182:183], off
	v_lshl_add_u64 v[182:183], s[38:39], 0, v[128:129]
	s_mov_b32 m0, s44
	s_nop 0
	global_load_lds_dwordx4 v[182:183], off
	v_lshl_add_u64 v[182:183], s[38:39], 0, v[130:131]
	s_add_i32 m0, s44, 0x2000
	s_nop 0
	global_load_lds_dwordx4 v[182:183], off
	v_lshl_add_u64 v[182:183], v[248:249], 0, s[8:9]
	s_mov_b32 m0, s54
	s_nop 0
	global_load_lds_dwordx4 v[182:183], off
	v_lshl_add_u64 v[182:183], v[250:251], 0, s[8:9]
	s_mov_b32 m0, s55
	s_nop 0
	global_load_lds_dwordx4 v[182:183], off
	s_waitcnt vmcnt(8) lgkmcnt(0)
	s_barrier
	s_setprio 1
	v_mfma_f32_16x16x32_bf16 v[60:63], v[174:177], v[216:219], v[60:63]
	v_mfma_f32_16x16x32_bf16 v[56:59], v[188:191], v[216:219], v[56:59]
	v_mfma_f32_16x16x32_bf16 v[44:47], v[174:177], v[224:227], v[44:47]
	v_mfma_f32_16x16x32_bf16 v[40:43], v[188:191], v[224:227], v[40:43]
	v_mfma_f32_16x16x32_bf16 v[28:31], v[174:177], v[232:235], v[28:31]
	v_mfma_f32_16x16x32_bf16 v[24:27], v[188:191], v[232:235], v[24:27]
	v_mfma_f32_16x16x32_bf16 v[12:15], v[174:177], v[240:243], v[12:15]
	v_mfma_f32_16x16x32_bf16 v[8:11], v[188:191], v[240:243], v[8:11]
	v_mfma_f32_16x16x32_bf16 v[60:63], v[178:181], v[220:223], v[60:63]
	v_mfma_f32_16x16x32_bf16 v[56:59], v[192:195], v[220:223], v[56:59]
	v_mfma_f32_16x16x32_bf16 v[44:47], v[178:181], v[228:231], v[44:47]
	v_mfma_f32_16x16x32_bf16 v[40:43], v[192:195], v[228:231], v[40:43]
	v_mfma_f32_16x16x32_bf16 v[28:31], v[178:181], v[236:239], v[28:31]
	v_mfma_f32_16x16x32_bf16 v[24:27], v[192:195], v[236:239], v[24:27]
	v_mfma_f32_16x16x32_bf16 v[12:15], v[178:181], v[244:247], v[12:15]
	v_mfma_f32_16x16x32_bf16 v[8:11], v[192:195], v[244:247], v[8:11]
	s_setprio 0
	s_setprio 1
	v_mfma_f32_16x16x32_bf16 v[52:55], v[196:199], v[216:219], v[52:55]
	v_mfma_f32_16x16x32_bf16 v[48:51], v[208:211], v[216:219], v[48:51]
	v_mfma_f32_16x16x32_bf16 v[36:39], v[196:199], v[224:227], v[36:39]
	v_mfma_f32_16x16x32_bf16 v[32:35], v[208:211], v[224:227], v[32:35]
	v_mfma_f32_16x16x32_bf16 v[20:23], v[196:199], v[232:235], v[20:23]
	v_mfma_f32_16x16x32_bf16 v[16:19], v[208:211], v[232:235], v[16:19]
	v_mfma_f32_16x16x32_bf16 v[4:7], v[196:199], v[240:243], v[4:7]
	v_mfma_f32_16x16x32_bf16 v[0:3], v[208:211], v[240:243], v[0:3]
	v_mfma_f32_16x16x32_bf16 v[52:55], v[200:203], v[220:223], v[52:55]
	v_mfma_f32_16x16x32_bf16 v[48:51], v[212:215], v[220:223], v[48:51]
	v_mfma_f32_16x16x32_bf16 v[36:39], v[200:203], v[228:231], v[36:39]
	v_mfma_f32_16x16x32_bf16 v[32:35], v[212:215], v[228:231], v[32:35]
	v_mfma_f32_16x16x32_bf16 v[20:23], v[200:203], v[236:239], v[20:23]
	v_mfma_f32_16x16x32_bf16 v[16:19], v[212:215], v[236:239], v[16:19]
	v_mfma_f32_16x16x32_bf16 v[4:7], v[200:203], v[244:247], v[4:7]
	v_mfma_f32_16x16x32_bf16 v[0:3], v[212:215], v[244:247], v[0:3]
	s_setprio 0
	s_barrier
	s_add_u32 s75, s75, 0x100
	s_addc_u32 s76, s76, 0
	s_cmp_ge_i32 s77, s0
	s_mov_b64 s[38:39], s[42:43]
	s_mov_b32 s44, s77
	s_cbranch_scc0 .LBB0_353
	s_and_b64 vcc, exec, s[10:11]
	s_cbranch_vccz .LBB0_359

; #define PG8_STAGE(bufoff, gbase, voff) do { _Pragma("unroll") for (int _i = 0; _i < 2; ++_i) \
;         __builtin_amdgcn_global_load_lds((const unsigned*)((const char*)(gbase) + (voff)[_i]), (LAS unsigned*)(lds + (bufoff) + ldsw + _i * 8192), 16, 0, 0); } while (0)
; #define PG8_LDA(dst, b, h) do { _Pragma("unroll") for (int m = 0; m < 4; ++m) _Pragma("unroll") for (int k = 0; k < 2; ++k) dst[m][k] = *(const LAS bf16x8*)(lds + PG8_SA(b, h) + aoff + m * 2048 + k * 1024); } while (0)
; #define PG8_LDB(dst, b, h) do { _Pragma("unroll") for (int n = 0; n < 2; ++n) _Pragma("unroll") for (int k = 0; k < 2; ++k) dst[n][k] = *(const LAS bf16x8*)(lds + PG8_SB(b, h) + boff + n * 2048 + k * 1024); } while (0)
; #define PG8_WAIT_V(n) asm volatile("s_waitcnt vmcnt(" #n ")" ::: "memory")
; #define PG8_WAIT_L(n) asm volatile("s_waitcnt lgkmcnt(" #n ")" ::: "memory")
; #define PG8_BAR __builtin_amdgcn_s_barrier()
; #define PG8_SCHED __builtin_amdgcn_sched_barrier(0)
; template <class Epi, class Sched, bool SWAPD = false>
; __device__ __forceinline__ void gemm_phase(LAS unsigned char* lds, const Gemm g, const Sched& S, const Epi& E) {
;     ...
;         for (int t = 0; t < nt; t += 2) {
;             const bool last = (t == nt - 2);
;             const char* a1 = cA + (size_t)(t + 1) * kstepA;
;             const char* a2 = last ? nA : cA + (size_t)(t + 2) * kstepA; const char* b2 = last ? nB : cB + (size_t)(t + 2) * kstep;
;             const char* a3 = a2 + kstepA; const char* b3 = b2 + kstep;
;             PG8_LDB(B0, 0, 0); PG8_LDB(B1, 0, 1); PG8_SCHED; PG8_LDA(At, 0, 0); PG8_STAGE(PG8_SA(1, 1), a1 + hstepA, voffA);
;             PG8_WAIT_V(8); PG8_WAIT_L(0); PG8_BAR; PG8_MMA(0, 0, At, B0); PG8_MMA(0, 1, At, B1); PG8_BAR; PG8_SCHED;
;             PG8_LDA(At, 0, 1); PG8_STAGE(PG8_SB(0, 0), b2, voffB); PG8_STAGE(PG8_SB(0, 1), b2 + hstepB, voffB); PG8_STAGE(PG8_SA(0, 0), a2, voffA);
;             PG8_WAIT_V(8); PG8_WAIT_L(0); PG8_BAR; PG8_MMA(1, 0, At, B0); PG8_MMA(1, 1, At, B1); PG8_BAR; PG8_SCHED;
.LBB0_486:
	ds_read_b128 v[152:155], v149
	ds_read_b128 v[156:159], v149 offset:1024
	ds_read_b128 v[160:163], v149 offset:2048
	ds_read_b128 v[164:167], v149 offset:3072
	ds_read_b128 v[168:171], v150
	ds_read_b128 v[172:175], v150 offset:1024
	ds_read_b128 v[176:179], v150 offset:2048
	ds_read_b128 v[180:183], v150 offset:3072
	s_add_u32 s42, s40, 0xfffc0080
	s_addc_u32 s43, s41, -1
	s_cmp_eq_u32 s66, 12
	s_cselect_b32 s45, s7, s43
	s_cselect_b32 s44, s13, s42
	s_cselect_b32 s43, s25, s65
	s_cselect_b32 s42, s57, s64
	v_lshl_add_u64 v[204:205], s[40:41], 0, v[138:139]
	s_add_i32 m0, s30, 0xc000
	ds_read_b128 v[184:187], v151
	ds_read_b128 v[188:191], v151 offset:1024
	ds_read_b128 v[192:195], v151 offset:2048
	ds_read_b128 v[196:199], v151 offset:3072
	ds_read_b128 v[200:203], v151 offset:4096
	ds_read_b128 v[208:211], v151 offset:5120
	ds_read_b128 v[212:215], v151 offset:6144
	ds_read_b128 v[216:219], v151 offset:7168
	global_load_lds_dwordx4 v[204:205], off
	v_lshl_add_u64 v[204:205], s[40:41], 0, v[140:141]
	s_add_i32 m0, s30, 0xe000
	s_nop 0
	global_load_lds_dwordx4 v[204:205], off
	s_waitcnt vmcnt(8) lgkmcnt(0)
	s_barrier
	s_setprio 1
	v_mfma_f32_16x16x32_bf16 v[124:127], v[152:155], v[184:187], v[124:127]
	v_mfma_f32_16x16x32_bf16 v[120:123], v[160:163], v[184:187], v[120:123]
	v_mfma_f32_16x16x32_bf16 v[108:111], v[152:155], v[192:195], v[108:111]
	v_mfma_f32_16x16x32_bf16 v[104:107], v[160:163], v[192:195], v[104:107]
	v_mfma_f32_16x16x32_bf16 v[92:95], v[152:155], v[200:203], v[92:95]
	v_mfma_f32_16x16x32_bf16 v[88:91], v[160:163], v[200:203], v[88:91]
	v_mfma_f32_16x16x32_bf16 v[76:79], v[152:155], v[212:215], v[76:79]
	v_mfma_f32_16x16x32_bf16 v[72:75], v[160:163], v[212:215], v[72:75]
	v_mfma_f32_16x16x32_bf16 v[124:127], v[156:159], v[188:191], v[124:127]
	v_mfma_f32_16x16x32_bf16 v[120:123], v[164:167], v[188:191], v[120:123]
	v_mfma_f32_16x16x32_bf16 v[108:111], v[156:159], v[196:199], v[108:111]
	v_mfma_f32_16x16x32_bf16 v[104:107], v[164:167], v[196:199], v[104:107]
	v_mfma_f32_16x16x32_bf16 v[92:95], v[156:159], v[208:211], v[92:95]
	v_mfma_f32_16x16x32_bf16 v[88:91], v[164:167], v[208:211], v[88:91]
	v_mfma_f32_16x16x32_bf16 v[76:79], v[156:159], v[216:219], v[76:79]
	v_mfma_f32_16x16x32_bf16 v[72:75], v[164:167], v[216:219], v[72:75]
	s_setprio 0
	s_setprio 1
	v_mfma_f32_16x16x32_bf16 v[116:119], v[168:171], v[184:187], v[116:119]
	v_mfma_f32_16x16x32_bf16 v[112:115], v[176:179], v[184:187], v[112:115]
	v_mfma_f32_16x16x32_bf16 v[100:103], v[168:171], v[192:195], v[100:103]
	v_mfma_f32_16x16x32_bf16 v[96:99], v[176:179], v[192:195], v[96:99]
	v_mfma_f32_16x16x32_bf16 v[84:87], v[168:171], v[200:203], v[84:87]
	v_mfma_f32_16x16x32_bf16 v[80:83], v[176:179], v[200:203], v[80:83]
	v_mfma_f32_16x16x32_bf16 v[68:71], v[168:171], v[212:215], v[68:71]
	v_mfma_f32_16x16x32_bf16 v[64:67], v[176:179], v[212:215], v[64:67]
	v_mfma_f32_16x16x32_bf16 v[116:119], v[172:175], v[188:191], v[116:119]
	v_mfma_f32_16x16x32_bf16 v[112:115], v[180:183], v[188:191], v[112:115]
	v_mfma_f32_16x16x32_bf16 v[100:103], v[172:175], v[196:199], v[100:103]
	v_mfma_f32_16x16x32_bf16 v[96:99], v[180:183], v[196:199], v[96:99]
	v_mfma_f32_16x16x32_bf16 v[84:87], v[172:175], v[208:211], v[84:87]
	v_mfma_f32_16x16x32_bf16 v[80:83], v[180:183], v[208:211], v[80:83]
	v_mfma_f32_16x16x32_bf16 v[68:71], v[172:175], v[216:219], v[68:71]
	v_mfma_f32_16x16x32_bf16 v[64:67], v[180:183], v[216:219], v[64:67]
	s_setprio 0
	s_barrier
	s_add_i32 s67, s35, s21
	v_lshl_add_u64 v[204:205], s[42:43], 0, v[128:129]
	s_mov_b32 m0, s67
	ds_read_b128 v[184:187], v151 offset:16384
	ds_read_b128 v[188:191], v151 offset:17408
	ds_read_b128 v[192:195], v151 offset:18432
	ds_read_b128 v[196:199], v151 offset:19456
	ds_read_b128 v[200:203], v151 offset:20480
	ds_read_b128 v[208:211], v151 offset:21504
	ds_read_b128 v[212:215], v151 offset:22528
	ds_read_b128 v[216:219], v151 offset:23552
	global_load_lds_dwordx4 v[204:205], off
	s_add_i32 m0, s67, 0x2000
	s_add_u32 s68, s42, 0x40000
	v_lshl_add_u64 v[220:221], s[42:43], 0, v[130:131]
	s_addc_u32 s69, s43, 0
	s_add_i32 s67, s53, s21
	global_load_lds_dwordx4 v[220:221], off
	v_lshl_add_u64 v[222:223], s[68:69], 0, v[128:129]
	s_mov_b32 m0, s67
	v_lshl_add_u64 v[224:225], s[44:45], 0, v[130:131]
	global_load_lds_dwordx4 v[222:223], off
	v_lshl_add_u64 v[222:223], s[68:69], 0, v[130:131]
	s_add_i32 m0, s67, 0x2000
	s_nop 0
	global_load_lds_dwordx4 v[222:223], off
	v_lshl_add_u64 v[222:223], s[44:45], 0, v[128:129]
	s_mov_b32 m0, s30
	s_nop 0
	global_load_lds_dwordx4 v[222:223], off
	s_mov_b32 m0, s31
	s_nop 0
	global_load_lds_dwordx4 v[224:225], off
	s_waitcnt vmcnt(8) lgkmcnt(0)
	s_barrier
; #define PG8_STAGE(bufoff, gbase, voff) do { _Pragma("unroll") for (int _i = 0; _i < 2; ++_i) \
;         __builtin_amdgcn_global_load_lds((const unsigned*)((const char*)(gbase) + (voff)[_i]), (LAS unsigned*)(lds + (bufoff) + ldsw + _i * 8192), 16, 0, 0); } while (0)
; #define PG8_LDA(dst, b, h) do { _Pragma("unroll") for (int m = 0; m < 4; ++m) _Pragma("unroll") for (int k = 0; k < 2; ++k) dst[m][k] = *(const LAS bf16x8*)(lds + PG8_SA(b, h) + aoff + m * 2048 + k * 1024); } while (0)
; #define PG8_LDB(dst, b, h) do { _Pragma("unroll") for (int n = 0; n < 2; ++n) _Pragma("unroll") for (int k = 0; k < 2; ++k) dst[n][k] = *(const LAS bf16x8*)(lds + PG8_SB(b, h) + boff + n * 2048 + k * 1024); } while (0)
; #define PG8_WAIT_V(n) asm volatile("s_waitcnt vmcnt(" #n ")" ::: "memory")
; #define PG8_WAIT_L(n) asm volatile("s_waitcnt lgkmcnt(" #n ")" ::: "memory")
; #define PG8_BAR __builtin_amdgcn_s_barrier()
; #define PG8_SCHED __builtin_amdgcn_sched_barrier(0)
; template <class Epi, class Sched, bool SWAPD = false>
; __device__ __forceinline__ void gemm_phase(LAS unsigned char* lds, const Gemm g, const Sched& S, const Epi& E) {
;     ...
;             PG8_WAIT_V(8); PG8_WAIT_L(0); PG8_BAR; PG8_MMA(1, 0, At, B0); PG8_MMA(1, 1, At, B1); PG8_BAR; PG8_SCHED;
;             PG8_LDB(B0, 1, 0); PG8_LDB(B1, 1, 1); PG8_SCHED; PG8_LDA(At, 1, 0); PG8_STAGE(PG8_SA(0, 1), a2 + hstepA, voffA);
;             PG8_WAIT_V(8); PG8_WAIT_L(0); PG8_BAR; PG8_MMA(0, 0, At, B0); PG8_MMA(0, 1, At, B1); PG8_BAR; PG8_SCHED;
	s_setprio 1
	v_mfma_f32_16x16x32_bf16 v[60:63], v[152:155], v[184:187], v[60:63]
	v_mfma_f32_16x16x32_bf16 v[56:59], v[160:163], v[184:187], v[56:59]
	v_mfma_f32_16x16x32_bf16 v[44:47], v[152:155], v[192:195], v[44:47]
	v_mfma_f32_16x16x32_bf16 v[40:43], v[160:163], v[192:195], v[40:43]
	v_mfma_f32_16x16x32_bf16 v[28:31], v[152:155], v[200:203], v[28:31]
	v_mfma_f32_16x16x32_bf16 v[24:27], v[160:163], v[200:203], v[24:27]
	v_mfma_f32_16x16x32_bf16 v[12:15], v[152:155], v[212:215], v[12:15]
	v_mfma_f32_16x16x32_bf16 v[8:11], v[160:163], v[212:215], v[8:11]
	v_mfma_f32_16x16x32_bf16 v[60:63], v[156:159], v[188:191], v[60:63]
	v_mfma_f32_16x16x32_bf16 v[56:59], v[164:167], v[188:191], v[56:59]
	v_mfma_f32_16x16x32_bf16 v[44:47], v[156:159], v[196:199], v[44:47]
	v_mfma_f32_16x16x32_bf16 v[40:43], v[164:167], v[196:199], v[40:43]
	v_mfma_f32_16x16x32_bf16 v[28:31], v[156:159], v[208:211], v[28:31]
	v_mfma_f32_16x16x32_bf16 v[24:27], v[164:167], v[208:211], v[24:27]
	v_mfma_f32_16x16x32_bf16 v[12:15], v[156:159], v[216:219], v[12:15]
	v_mfma_f32_16x16x32_bf16 v[8:11], v[164:167], v[216:219], v[8:11]
	s_setprio 0
	s_setprio 1
	v_mfma_f32_16x16x32_bf16 v[52:55], v[168:171], v[184:187], v[52:55]
	v_mfma_f32_16x16x32_bf16 v[48:51], v[176:179], v[184:187], v[48:51]
	v_mfma_f32_16x16x32_bf16 v[36:39], v[168:171], v[192:195], v[36:39]
	v_mfma_f32_16x16x32_bf16 v[32:35], v[176:179], v[192:195], v[32:35]
	v_mfma_f32_16x16x32_bf16 v[20:23], v[168:171], v[200:203], v[20:23]
	v_mfma_f32_16x16x32_bf16 v[16:19], v[176:179], v[200:203], v[16:19]
	v_mfma_f32_16x16x32_bf16 v[4:7], v[168:171], v[212:215], v[4:7]
	v_mfma_f32_16x16x32_bf16 v[0:3], v[176:179], v[212:215], v[0:3]
	v_mfma_f32_16x16x32_bf16 v[52:55], v[172:175], v[188:191], v[52:55]
	v_mfma_f32_16x16x32_bf16 v[48:51], v[180:183], v[188:191], v[48:51]
	v_mfma_f32_16x16x32_bf16 v[36:39], v[172:175], v[196:199], v[36:39]
	v_mfma_f32_16x16x32_bf16 v[32:35], v[180:183], v[196:199], v[32:35]
	v_mfma_f32_16x16x32_bf16 v[20:23], v[172:175], v[208:211], v[20:23]
	v_mfma_f32_16x16x32_bf16 v[16:19], v[180:183], v[208:211], v[16:19]
	v_mfma_f32_16x16x32_bf16 v[4:7], v[172:175], v[216:219], v[4:7]
	v_mfma_f32_16x16x32_bf16 v[0:3], v[180:183], v[216:219], v[0:3]
	s_setprio 0
	s_barrier
	s_add_i32 s67, 0, 0x18000
	v_add_u32_e32 v132, s67, v146
	s_add_i32 s68, 0, 0x1c000
	ds_read_b128 v[152:155], v132
	ds_read_b128 v[156:159], v132 offset:1024
	ds_read_b128 v[160:163], v132 offset:2048
	ds_read_b128 v[164:167], v132 offset:3072
	v_add_u32_e32 v132, s68, v146
	ds_read_b128 v[168:171], v132
	ds_read_b128 v[172:175], v132 offset:1024
	ds_read_b128 v[176:179], v132 offset:2048
	ds_read_b128 v[180:183], v132 offset:3072
	s_add_u32 s44, s44, 0x40000
	s_addc_u32 s45, s45, 0
	s_mov_b32 m0, s33
	v_lshl_add_u64 v[226:227], s[44:45], 0, v[128:129]
	ds_read_b128 v[184:187], v151 offset:32768
	ds_read_b128 v[188:191], v151 offset:33792
	ds_read_b128 v[192:195], v151 offset:34816
	ds_read_b128 v[196:199], v151 offset:35840
	ds_read_b128 v[200:203], v151 offset:36864
	ds_read_b128 v[208:211], v151 offset:37888
	ds_read_b128 v[212:215], v151 offset:38912
	ds_read_b128 v[216:219], v151 offset:39936
	global_load_lds_dwordx4 v[226:227], off
	v_lshl_add_u64 v[226:227], s[44:45], 0, v[130:131]
	s_mov_b32 m0, s46
	s_nop 0
	global_load_lds_dwordx4 v[226:227], off
	s_waitcnt vmcnt(8) lgkmcnt(0)
	s_barrier
	s_setprio 1
	v_mfma_f32_16x16x32_bf16 v[124:127], v[152:155], v[184:187], v[124:127]
	v_mfma_f32_16x16x32_bf16 v[120:123], v[160:163], v[184:187], v[120:123]
	v_mfma_f32_16x16x32_bf16 v[108:111], v[152:155], v[192:195], v[108:111]
	v_mfma_f32_16x16x32_bf16 v[104:107], v[160:163], v[192:195], v[104:107]
	v_mfma_f32_16x16x32_bf16 v[92:95], v[152:155], v[200:203], v[92:95]
	v_mfma_f32_16x16x32_bf16 v[88:91], v[160:163], v[200:203], v[88:91]
	v_mfma_f32_16x16x32_bf16 v[76:79], v[152:155], v[212:215], v[76:79]
	v_mfma_f32_16x16x32_bf16 v[72:75], v[160:163], v[212:215], v[72:75]
	v_mfma_f32_16x16x32_bf16 v[124:127], v[156:159], v[188:191], v[124:127]
	v_mfma_f32_16x16x32_bf16 v[120:123], v[164:167], v[188:191], v[120:123]
	v_mfma_f32_16x16x32_bf16 v[108:111], v[156:159], v[196:199], v[108:111]
	v_mfma_f32_16x16x32_bf16 v[104:107], v[164:167], v[196:199], v[104:107]
	v_mfma_f32_16x16x32_bf16 v[92:95], v[156:159], v[208:211], v[92:95]
	v_mfma_f32_16x16x32_bf16 v[88:91], v[164:167], v[208:211], v[88:91]
	v_mfma_f32_16x16x32_bf16 v[76:79], v[156:159], v[216:219], v[76:79]
	v_mfma_f32_16x16x32_bf16 v[72:75], v[164:167], v[216:219], v[72:75]
	s_setprio 0
	s_setprio 1
	v_mfma_f32_16x16x32_bf16 v[116:119], v[168:171], v[184:187], v[116:119]
	v_mfma_f32_16x16x32_bf16 v[112:115], v[176:179], v[184:187], v[112:115]
	v_mfma_f32_16x16x32_bf16 v[100:103], v[168:171], v[192:195], v[100:103]
	v_mfma_f32_16x16x32_bf16 v[96:99], v[176:179], v[192:195], v[96:99]
	v_mfma_f32_16x16x32_bf16 v[84:87], v[168:171], v[200:203], v[84:87]
	v_mfma_f32_16x16x32_bf16 v[80:83], v[176:179], v[200:203], v[80:83]
	v_mfma_f32_16x16x32_bf16 v[68:71], v[168:171], v[212:215], v[68:71]
	v_mfma_f32_16x16x32_bf16 v[64:67], v[176:179], v[212:215], v[64:67]
	v_mfma_f32_16x16x32_bf16 v[116:119], v[172:175], v[188:191], v[116:119]
	v_mfma_f32_16x16x32_bf16 v[112:115], v[180:183], v[188:191], v[112:115]
	v_mfma_f32_16x16x32_bf16 v[100:103], v[172:175], v[196:199], v[100:103]
	v_mfma_f32_16x16x32_bf16 v[96:99], v[180:183], v[196:199], v[96:99]
	v_mfma_f32_16x16x32_bf16 v[84:87], v[172:175], v[208:211], v[84:87]
	v_mfma_f32_16x16x32_bf16 v[80:83], v[180:183], v[208:211], v[80:83]
	v_mfma_f32_16x16x32_bf16 v[68:71], v[172:175], v[216:219], v[68:71]
	v_mfma_f32_16x16x32_bf16 v[64:67], v[180:183], v[216:219], v[64:67]
	s_setprio 0
	s_barrier
; #define PG8_STAGE(bufoff, gbase, voff) do { _Pragma("unroll") for (int _i = 0; _i < 2; ++_i) \
;         __builtin_amdgcn_global_load_lds((const unsigned*)((const char*)(gbase) + (voff)[_i]), (LAS unsigned*)(lds + (bufoff) + ldsw + _i * 8192), 16, 0, 0); } while (0)
; #define PG8_LDA(dst, b, h) do { _Pragma("unroll") for (int m = 0; m < 4; ++m) _Pragma("unroll") for (int k = 0; k < 2; ++k) dst[m][k] = *(const LAS bf16x8*)(lds + PG8_SA(b, h) + aoff + m * 2048 + k * 1024); } while (0)
; #define PG8_WAIT_V(n) asm volatile("s_waitcnt vmcnt(" #n ")" ::: "memory")
; #define PG8_WAIT_L(n) asm volatile("s_waitcnt lgkmcnt(" #n ")" ::: "memory")
; #define PG8_BAR __builtin_amdgcn_s_barrier()
; #define PG8_SCHED __builtin_amdgcn_sched_barrier(0)
; template <class Epi, class Sched, bool SWAPD = false>
; __device__ __forceinline__ void gemm_phase(LAS unsigned char* lds, const Gemm g, const Sched& S, const Epi& E) {
;     ...
;             PG8_LDA(At, 1, 1); PG8_STAGE(PG8_SB(1, 0), b3, voffB); PG8_STAGE(PG8_SB(1, 1), b3 + hstepB, voffB); PG8_STAGE(PG8_SA(1, 0), a3, voffA);
;             PG8_WAIT_V(8); PG8_WAIT_L(0); PG8_BAR; PG8_MMA(1, 0, At, B0); PG8_MMA(1, 1, At, B1); PG8_BAR; PG8_SCHED;
;         }
;         if (wr == 0) PG8_BAR;
	s_add_i32 s44, s67, s21
	v_lshl_add_u64 v[204:205], v[204:205], 0, s[8:9]
	s_mov_b32 m0, s44
	ds_read_b128 v[184:187], v151 offset:49152
	ds_read_b128 v[188:191], v151 offset:50176
	ds_read_b128 v[192:195], v151 offset:51200
	ds_read_b128 v[196:199], v151 offset:52224
	ds_read_b128 v[200:203], v151 offset:53248
	ds_read_b128 v[208:211], v151 offset:54272
	ds_read_b128 v[212:215], v151 offset:55296
	ds_read_b128 v[216:219], v151 offset:56320
	global_load_lds_dwordx4 v[204:205], off
	s_add_i32 m0, s44, 0x2000
	s_add_u32 s42, s42, 0x40080
	v_lshl_add_u64 v[204:205], v[220:221], 0, s[8:9]
	s_addc_u32 s43, s43, 0
	s_add_i32 s44, s68, s21
	global_load_lds_dwordx4 v[204:205], off
	v_lshl_add_u64 v[204:205], s[42:43], 0, v[128:129]
	s_mov_b32 m0, s44
	s_nop 0
	global_load_lds_dwordx4 v[204:205], off
	v_lshl_add_u64 v[204:205], s[42:43], 0, v[130:131]
	s_add_i32 m0, s44, 0x2000
	s_nop 0
	global_load_lds_dwordx4 v[204:205], off
	v_lshl_add_u64 v[204:205], v[222:223], 0, s[8:9]
	s_mov_b32 m0, s51
	s_nop 0
	global_load_lds_dwordx4 v[204:205], off
	v_lshl_add_u64 v[204:205], v[224:225], 0, s[8:9]
	s_mov_b32 m0, s52
	s_nop 0
	global_load_lds_dwordx4 v[204:205], off
	s_waitcnt vmcnt(8) lgkmcnt(0)
	s_barrier
	s_setprio 1
	v_mfma_f32_16x16x32_bf16 v[60:63], v[152:155], v[184:187], v[60:63]
	v_mfma_f32_16x16x32_bf16 v[56:59], v[160:163], v[184:187], v[56:59]
	v_mfma_f32_16x16x32_bf16 v[44:47], v[152:155], v[192:195], v[44:47]
	v_mfma_f32_16x16x32_bf16 v[40:43], v[160:163], v[192:195], v[40:43]
	v_mfma_f32_16x16x32_bf16 v[28:31], v[152:155], v[200:203], v[28:31]
	v_mfma_f32_16x16x32_bf16 v[24:27], v[160:163], v[200:203], v[24:27]
	v_mfma_f32_16x16x32_bf16 v[12:15], v[152:155], v[212:215], v[12:15]
	v_mfma_f32_16x16x32_bf16 v[8:11], v[160:163], v[212:215], v[8:11]
	v_mfma_f32_16x16x32_bf16 v[60:63], v[156:159], v[188:191], v[60:63]
	v_mfma_f32_16x16x32_bf16 v[56:59], v[164:167], v[188:191], v[56:59]
	v_mfma_f32_16x16x32_bf16 v[44:47], v[156:159], v[196:199], v[44:47]
	v_mfma_f32_16x16x32_bf16 v[40:43], v[164:167], v[196:199], v[40:43]
	v_mfma_f32_16x16x32_bf16 v[28:31], v[156:159], v[208:211], v[28:31]
	v_mfma_f32_16x16x32_bf16 v[24:27], v[164:167], v[208:211], v[24:27]
	v_mfma_f32_16x16x32_bf16 v[12:15], v[156:159], v[216:219], v[12:15]
	v_mfma_f32_16x16x32_bf16 v[8:11], v[164:167], v[216:219], v[8:11]
	s_setprio 0
	s_setprio 1
	v_mfma_f32_16x16x32_bf16 v[52:55], v[168:171], v[184:187], v[52:55]
	v_mfma_f32_16x16x32_bf16 v[48:51], v[176:179], v[184:187], v[48:51]
	v_mfma_f32_16x16x32_bf16 v[36:39], v[168:171], v[192:195], v[36:39]
	v_mfma_f32_16x16x32_bf16 v[32:35], v[176:179], v[192:195], v[32:35]
	v_mfma_f32_16x16x32_bf16 v[20:23], v[168:171], v[200:203], v[20:23]
	v_mfma_f32_16x16x32_bf16 v[16:19], v[176:179], v[200:203], v[16:19]
	v_mfma_f32_16x16x32_bf16 v[4:7], v[168:171], v[212:215], v[4:7]
	v_mfma_f32_16x16x32_bf16 v[0:3], v[176:179], v[212:215], v[0:3]
	v_mfma_f32_16x16x32_bf16 v[52:55], v[172:175], v[188:191], v[52:55]
	v_mfma_f32_16x16x32_bf16 v[48:51], v[180:183], v[188:191], v[48:51]
	v_mfma_f32_16x16x32_bf16 v[36:39], v[172:175], v[196:199], v[36:39]
	v_mfma_f32_16x16x32_bf16 v[32:35], v[180:183], v[196:199], v[32:35]
	v_mfma_f32_16x16x32_bf16 v[20:23], v[172:175], v[208:211], v[20:23]
	v_mfma_f32_16x16x32_bf16 v[16:19], v[180:183], v[208:211], v[16:19]
	v_mfma_f32_16x16x32_bf16 v[4:7], v[172:175], v[216:219], v[4:7]
	v_mfma_f32_16x16x32_bf16 v[0:3], v[180:183], v[216:219], v[0:3]
	s_setprio 0
	s_barrier
	s_add_i32 s66, s66, 2
	s_add_u32 s40, s40, 0x100
	s_addc_u32 s41, s41, 0
	s_add_u32 s64, s64, 0x100
	s_addc_u32 s65, s65, 0
	s_cmp_gt_u32 s66, 13
	s_cbranch_scc0 .LBB0_486
	s_and_b64 vcc, exec, s[10:11]
	s_cbranch_vccz .LBB0_489
	s_barrier

; #define PG8_STAGE(bufoff, gbase, voff) do { _Pragma("unroll") for (int _i = 0; _i < 2; ++_i) \
;         __builtin_amdgcn_global_load_lds((const unsigned*)((const char*)(gbase) + (voff)[_i]), (LAS unsigned*)(lds + (bufoff) + ldsw + _i * 8192), 16, 0, 0); } while (0)
; #define PG8_LDA(dst, b, h) do { _Pragma("unroll") for (int m = 0; m < 4; ++m) _Pragma("unroll") for (int k = 0; k < 2; ++k) dst[m][k] = *(const LAS bf16x8*)(lds + PG8_SA(b, h) + aoff + m * 2048 + k * 1024); } while (0)
; #define PG8_LDB(dst, b, h) do { _Pragma("unroll") for (int n = 0; n < 2; ++n) _Pragma("unroll") for (int k = 0; k < 2; ++k) dst[n][k] = *(const LAS bf16x8*)(lds + PG8_SB(b, h) + boff + n * 2048 + k * 1024); } while (0)
; #define PG8_WAIT_V(n) asm volatile("s_waitcnt vmcnt(" #n ")" ::: "memory")
; #define PG8_WAIT_L(n) asm volatile("s_waitcnt lgkmcnt(" #n ")" ::: "memory")
; #define PG8_BAR __builtin_amdgcn_s_barrier()
; #define PG8_SCHED __builtin_amdgcn_sched_barrier(0)
; template <class Epi, class Sched, bool SWAPD = false>
; __device__ __forceinline__ void gemm_phase(LAS unsigned char* lds, const Gemm g, const Sched& S, const Epi& E) {
;     ...
;         for (int t = 0; t < nt; t += 2) {
;             const bool last = (t == nt - 2);
;             const char* a1 = cA + (size_t)(t + 1) * kstepA;
;             const char* a2 = last ? nA : cA + (size_t)(t + 2) * kstepA; const char* b2 = last ? nB : cB + (size_t)(t + 2) * kstep;
;             const char* a3 = a2 + kstepA; const char* b3 = b2 + kstep;
;             PG8_LDB(B0, 0, 0); PG8_LDB(B1, 0, 1); PG8_SCHED; PG8_LDA(At, 0, 0); PG8_STAGE(PG8_SA(1, 1), a1 + hstepA, voffA);
;             PG8_WAIT_V(8); PG8_WAIT_L(0); PG8_BAR; PG8_MMA(0, 0, At, B0); PG8_MMA(0, 1, At, B1); PG8_BAR; PG8_SCHED;
;             PG8_LDA(At, 0, 1); PG8_STAGE(PG8_SB(0, 0), b2, voffB); PG8_STAGE(PG8_SB(0, 1), b2 + hstepB, voffB); PG8_STAGE(PG8_SA(0, 0), a2, voffA);
;             PG8_WAIT_V(8); PG8_WAIT_L(0); PG8_BAR; PG8_MMA(1, 0, At, B0); PG8_MMA(1, 1, At, B1); PG8_BAR; PG8_SCHED;
.LBB0_633:
	ds_read_b128 v[152:155], v148
	ds_read_b128 v[156:159], v148 offset:1024
	ds_read_b128 v[160:163], v148 offset:2048
	ds_read_b128 v[164:167], v148 offset:3072
	ds_read_b128 v[168:171], v149
	ds_read_b128 v[172:175], v149 offset:1024
	ds_read_b128 v[176:179], v149 offset:2048
	ds_read_b128 v[180:183], v149 offset:3072
	s_add_u32 s52, s50, 0x100
	s_addc_u32 s53, s51, 0
	s_cmp_eq_u32 s81, 4
	s_cselect_b32 s57, s75, s53
	s_cselect_b32 s56, s76, s52
	s_cselect_b32 s55, s77, s80
	s_cselect_b32 s54, s78, s79
	v_lshl_add_u64 v[204:205], s[50:51], 0, v[138:139]
	s_add_i32 m0, s33, 0xc000
	ds_read_b128 v[184:187], v150
	ds_read_b128 v[188:191], v150 offset:1024
	ds_read_b128 v[192:195], v150 offset:2048
	ds_read_b128 v[196:199], v150 offset:3072
	ds_read_b128 v[200:203], v150 offset:4096
	ds_read_b128 v[208:211], v150 offset:5120
	ds_read_b128 v[212:215], v150 offset:6144
	ds_read_b128 v[216:219], v150 offset:7168
	global_load_lds_dwordx4 v[204:205], off
	v_lshl_add_u64 v[204:205], s[50:51], 0, v[140:141]
	s_add_i32 m0, s33, 0xe000
	s_nop 0
	global_load_lds_dwordx4 v[204:205], off
	s_waitcnt vmcnt(8) lgkmcnt(0)
	s_barrier
	s_setprio 1
	v_mfma_f32_16x16x32_bf16 v[124:127], v[152:155], v[184:187], v[124:127]
	v_mfma_f32_16x16x32_bf16 v[120:123], v[160:163], v[184:187], v[120:123]
	v_mfma_f32_16x16x32_bf16 v[116:119], v[152:155], v[192:195], v[116:119]
	v_mfma_f32_16x16x32_bf16 v[112:115], v[160:163], v[192:195], v[112:115]
	v_mfma_f32_16x16x32_bf16 v[104:107], v[152:155], v[200:203], v[104:107]
	v_mfma_f32_16x16x32_bf16 v[96:99], v[160:163], v[200:203], v[96:99]
	v_mfma_f32_16x16x32_bf16 v[88:91], v[152:155], v[212:215], v[88:91]
	v_mfma_f32_16x16x32_bf16 v[80:83], v[160:163], v[212:215], v[80:83]
	v_mfma_f32_16x16x32_bf16 v[124:127], v[156:159], v[188:191], v[124:127]
	v_mfma_f32_16x16x32_bf16 v[120:123], v[164:167], v[188:191], v[120:123]
	v_mfma_f32_16x16x32_bf16 v[116:119], v[156:159], v[196:199], v[116:119]
	v_mfma_f32_16x16x32_bf16 v[112:115], v[164:167], v[196:199], v[112:115]
	v_mfma_f32_16x16x32_bf16 v[104:107], v[156:159], v[208:211], v[104:107]
	v_mfma_f32_16x16x32_bf16 v[96:99], v[164:167], v[208:211], v[96:99]
	v_mfma_f32_16x16x32_bf16 v[88:91], v[156:159], v[216:219], v[88:91]
	v_mfma_f32_16x16x32_bf16 v[80:83], v[164:167], v[216:219], v[80:83]
	s_setprio 0
	s_setprio 1
	v_mfma_f32_16x16x32_bf16 v[108:111], v[168:171], v[184:187], v[108:111]
	v_mfma_f32_16x16x32_bf16 v[100:103], v[176:179], v[184:187], v[100:103]
	v_mfma_f32_16x16x32_bf16 v[92:95], v[168:171], v[192:195], v[92:95]
	v_mfma_f32_16x16x32_bf16 v[84:87], v[176:179], v[192:195], v[84:87]
	v_mfma_f32_16x16x32_bf16 v[76:79], v[168:171], v[200:203], v[76:79]
	v_mfma_f32_16x16x32_bf16 v[72:75], v[176:179], v[200:203], v[72:75]
	v_mfma_f32_16x16x32_bf16 v[68:71], v[168:171], v[212:215], v[68:71]
	v_mfma_f32_16x16x32_bf16 v[64:67], v[176:179], v[212:215], v[64:67]
	v_mfma_f32_16x16x32_bf16 v[108:111], v[172:175], v[188:191], v[108:111]
	v_mfma_f32_16x16x32_bf16 v[100:103], v[180:183], v[188:191], v[100:103]
	v_mfma_f32_16x16x32_bf16 v[92:95], v[172:175], v[196:199], v[92:95]
	v_mfma_f32_16x16x32_bf16 v[84:87], v[180:183], v[196:199], v[84:87]
	v_mfma_f32_16x16x32_bf16 v[76:79], v[172:175], v[208:211], v[76:79]
	v_mfma_f32_16x16x32_bf16 v[72:75], v[180:183], v[208:211], v[72:75]
	v_mfma_f32_16x16x32_bf16 v[68:71], v[172:175], v[216:219], v[68:71]
	v_mfma_f32_16x16x32_bf16 v[64:67], v[180:183], v[216:219], v[64:67]
	s_setprio 0
	s_barrier
	s_add_i32 s50, s64, s21
	v_lshl_add_u64 v[204:205], s[54:55], 0, v[132:133]
	s_mov_b32 m0, s50
	ds_read_b128 v[184:187], v150 offset:16384
	ds_read_b128 v[188:191], v150 offset:17408
	ds_read_b128 v[192:195], v150 offset:18432
	ds_read_b128 v[196:199], v150 offset:19456
	ds_read_b128 v[200:203], v150 offset:20480
	ds_read_b128 v[208:211], v150 offset:21504
	ds_read_b128 v[212:215], v150 offset:22528
	ds_read_b128 v[216:219], v150 offset:23552
	global_load_lds_dwordx4 v[204:205], off
	s_add_i32 m0, s50, 0x2000
	s_add_u32 s50, s54, 0x20000
	v_lshl_add_u64 v[220:221], s[54:55], 0, v[128:129]
	s_addc_u32 s51, s55, 0
	s_add_i32 s82, s65, s21
	global_load_lds_dwordx4 v[220:221], off
	v_lshl_add_u64 v[222:223], s[50:51], 0, v[132:133]
	s_mov_b32 m0, s82
	v_lshl_add_u64 v[224:225], s[56:57], 0, v[130:131]
	global_load_lds_dwordx4 v[222:223], off
	v_lshl_add_u64 v[222:223], s[50:51], 0, v[128:129]
	s_add_i32 m0, s82, 0x2000
	s_nop 0
	global_load_lds_dwordx4 v[222:223], off
	v_lshl_add_u64 v[222:223], s[56:57], 0, v[134:135]
	s_mov_b32 m0, s33
	s_nop 0
	global_load_lds_dwordx4 v[222:223], off
	s_mov_b32 m0, s34
	s_nop 0
	global_load_lds_dwordx4 v[224:225], off
	s_waitcnt vmcnt(8) lgkmcnt(0)
	s_barrier
; #define PG8_STAGE(bufoff, gbase, voff) do { _Pragma("unroll") for (int _i = 0; _i < 2; ++_i) \
;         __builtin_amdgcn_global_load_lds((const unsigned*)((const char*)(gbase) + (voff)[_i]), (LAS unsigned*)(lds + (bufoff) + ldsw + _i * 8192), 16, 0, 0); } while (0)
; #define PG8_LDA(dst, b, h) do { _Pragma("unroll") for (int m = 0; m < 4; ++m) _Pragma("unroll") for (int k = 0; k < 2; ++k) dst[m][k] = *(const LAS bf16x8*)(lds + PG8_SA(b, h) + aoff + m * 2048 + k * 1024); } while (0)
; #define PG8_LDB(dst, b, h) do { _Pragma("unroll") for (int n = 0; n < 2; ++n) _Pragma("unroll") for (int k = 0; k < 2; ++k) dst[n][k] = *(const LAS bf16x8*)(lds + PG8_SB(b, h) + boff + n * 2048 + k * 1024); } while (0)
; #define PG8_WAIT_V(n) asm volatile("s_waitcnt vmcnt(" #n ")" ::: "memory")
; #define PG8_WAIT_L(n) asm volatile("s_waitcnt lgkmcnt(" #n ")" ::: "memory")
; #define PG8_BAR __builtin_amdgcn_s_barrier()
; #define PG8_SCHED __builtin_amdgcn_sched_barrier(0)
; template <class Epi, class Sched, bool SWAPD = false>
; __device__ __forceinline__ void gemm_phase(LAS unsigned char* lds, const Gemm g, const Sched& S, const Epi& E) {
;     ...
;             PG8_WAIT_V(8); PG8_WAIT_L(0); PG8_BAR; PG8_MMA(1, 0, At, B0); PG8_MMA(1, 1, At, B1); PG8_BAR; PG8_SCHED;
;             PG8_LDB(B0, 1, 0); PG8_LDB(B1, 1, 1); PG8_SCHED; PG8_LDA(At, 1, 0); PG8_STAGE(PG8_SA(0, 1), a2 + hstepA, voffA);
;             PG8_WAIT_V(8); PG8_WAIT_L(0); PG8_BAR; PG8_MMA(0, 0, At, B0); PG8_MMA(0, 1, At, B1); PG8_BAR; PG8_SCHED;
	s_setprio 1
	v_mfma_f32_16x16x32_bf16 v[60:63], v[152:155], v[184:187], v[60:63]
	v_mfma_f32_16x16x32_bf16 v[56:59], v[160:163], v[184:187], v[56:59]
	v_mfma_f32_16x16x32_bf16 v[52:55], v[152:155], v[192:195], v[52:55]
	v_mfma_f32_16x16x32_bf16 v[48:51], v[160:163], v[192:195], v[48:51]
	v_mfma_f32_16x16x32_bf16 v[40:43], v[152:155], v[200:203], v[40:43]
	v_mfma_f32_16x16x32_bf16 v[32:35], v[160:163], v[200:203], v[32:35]
	v_mfma_f32_16x16x32_bf16 v[24:27], v[152:155], v[212:215], v[24:27]
	v_mfma_f32_16x16x32_bf16 v[16:19], v[160:163], v[212:215], v[16:19]
	v_mfma_f32_16x16x32_bf16 v[60:63], v[156:159], v[188:191], v[60:63]
	v_mfma_f32_16x16x32_bf16 v[56:59], v[164:167], v[188:191], v[56:59]
	v_mfma_f32_16x16x32_bf16 v[52:55], v[156:159], v[196:199], v[52:55]
	v_mfma_f32_16x16x32_bf16 v[48:51], v[164:167], v[196:199], v[48:51]
	v_mfma_f32_16x16x32_bf16 v[40:43], v[156:159], v[208:211], v[40:43]
	v_mfma_f32_16x16x32_bf16 v[32:35], v[164:167], v[208:211], v[32:35]
	v_mfma_f32_16x16x32_bf16 v[24:27], v[156:159], v[216:219], v[24:27]
	v_mfma_f32_16x16x32_bf16 v[16:19], v[164:167], v[216:219], v[16:19]
	s_setprio 0
	s_setprio 1
	v_mfma_f32_16x16x32_bf16 v[44:47], v[168:171], v[184:187], v[44:47]
	v_mfma_f32_16x16x32_bf16 v[36:39], v[176:179], v[184:187], v[36:39]
	v_mfma_f32_16x16x32_bf16 v[28:31], v[168:171], v[192:195], v[28:31]
	v_mfma_f32_16x16x32_bf16 v[20:23], v[176:179], v[192:195], v[20:23]
	v_mfma_f32_16x16x32_bf16 v[12:15], v[168:171], v[200:203], v[12:15]
	v_mfma_f32_16x16x32_bf16 v[8:11], v[176:179], v[200:203], v[8:11]
	v_mfma_f32_16x16x32_bf16 v[4:7], v[168:171], v[212:215], v[4:7]
	v_mfma_f32_16x16x32_bf16 v[0:3], v[176:179], v[212:215], v[0:3]
	v_mfma_f32_16x16x32_bf16 v[44:47], v[172:175], v[188:191], v[44:47]
	v_mfma_f32_16x16x32_bf16 v[36:39], v[180:183], v[188:191], v[36:39]
	v_mfma_f32_16x16x32_bf16 v[28:31], v[172:175], v[196:199], v[28:31]
	v_mfma_f32_16x16x32_bf16 v[20:23], v[180:183], v[196:199], v[20:23]
	v_mfma_f32_16x16x32_bf16 v[12:15], v[172:175], v[208:211], v[12:15]
	v_mfma_f32_16x16x32_bf16 v[8:11], v[180:183], v[208:211], v[8:11]
	v_mfma_f32_16x16x32_bf16 v[4:7], v[172:175], v[216:219], v[4:7]
	v_mfma_f32_16x16x32_bf16 v[0:3], v[180:183], v[216:219], v[0:3]
	s_setprio 0
	s_barrier
	s_add_i32 s82, 0, 0x18000
	v_add_u32_e32 v151, s82, v147
	s_add_i32 s83, 0, 0x1c000
	ds_read_b128 v[152:155], v151
	ds_read_b128 v[156:159], v151 offset:1024
	ds_read_b128 v[160:163], v151 offset:2048
	ds_read_b128 v[164:167], v151 offset:3072
	v_add_u32_e32 v151, s83, v147
	ds_read_b128 v[168:171], v151
	ds_read_b128 v[172:175], v151 offset:1024
	ds_read_b128 v[176:179], v151 offset:2048
	ds_read_b128 v[180:183], v151 offset:3072
	s_add_u32 s50, s56, 0x30000
	s_addc_u32 s51, s57, 0
	s_mov_b32 m0, s35
	v_lshl_add_u64 v[226:227], s[50:51], 0, v[134:135]
	ds_read_b128 v[184:187], v150 offset:32768
	ds_read_b128 v[188:191], v150 offset:33792
	ds_read_b128 v[192:195], v150 offset:34816
	ds_read_b128 v[196:199], v150 offset:35840
	ds_read_b128 v[200:203], v150 offset:36864
	ds_read_b128 v[208:211], v150 offset:37888
	ds_read_b128 v[212:215], v150 offset:38912
	ds_read_b128 v[216:219], v150 offset:39936
	global_load_lds_dwordx4 v[226:227], off
	v_lshl_add_u64 v[226:227], s[50:51], 0, v[130:131]
	s_mov_b32 m0, s58
	s_nop 0
	global_load_lds_dwordx4 v[226:227], off
	s_waitcnt vmcnt(8) lgkmcnt(0)
	s_barrier
	s_setprio 1
	v_mfma_f32_16x16x32_bf16 v[124:127], v[152:155], v[184:187], v[124:127]
	v_mfma_f32_16x16x32_bf16 v[120:123], v[160:163], v[184:187], v[120:123]
	v_mfma_f32_16x16x32_bf16 v[116:119], v[152:155], v[192:195], v[116:119]
	v_mfma_f32_16x16x32_bf16 v[112:115], v[160:163], v[192:195], v[112:115]
	v_mfma_f32_16x16x32_bf16 v[104:107], v[152:155], v[200:203], v[104:107]
	v_mfma_f32_16x16x32_bf16 v[96:99], v[160:163], v[200:203], v[96:99]
	v_mfma_f32_16x16x32_bf16 v[88:91], v[152:155], v[212:215], v[88:91]
	v_mfma_f32_16x16x32_bf16 v[80:83], v[160:163], v[212:215], v[80:83]
	v_mfma_f32_16x16x32_bf16 v[124:127], v[156:159], v[188:191], v[124:127]
	v_mfma_f32_16x16x32_bf16 v[120:123], v[164:167], v[188:191], v[120:123]
	v_mfma_f32_16x16x32_bf16 v[116:119], v[156:159], v[196:199], v[116:119]
	v_mfma_f32_16x16x32_bf16 v[112:115], v[164:167], v[196:199], v[112:115]
	v_mfma_f32_16x16x32_bf16 v[104:107], v[156:159], v[208:211], v[104:107]
	v_mfma_f32_16x16x32_bf16 v[96:99], v[164:167], v[208:211], v[96:99]
	v_mfma_f32_16x16x32_bf16 v[88:91], v[156:159], v[216:219], v[88:91]
	v_mfma_f32_16x16x32_bf16 v[80:83], v[164:167], v[216:219], v[80:83]
	s_setprio 0
	s_setprio 1
	v_mfma_f32_16x16x32_bf16 v[108:111], v[168:171], v[184:187], v[108:111]
	v_mfma_f32_16x16x32_bf16 v[100:103], v[176:179], v[184:187], v[100:103]
	v_mfma_f32_16x16x32_bf16 v[92:95], v[168:171], v[192:195], v[92:95]
	v_mfma_f32_16x16x32_bf16 v[84:87], v[176:179], v[192:195], v[84:87]
	v_mfma_f32_16x16x32_bf16 v[76:79], v[168:171], v[200:203], v[76:79]
	v_mfma_f32_16x16x32_bf16 v[72:75], v[176:179], v[200:203], v[72:75]
	v_mfma_f32_16x16x32_bf16 v[68:71], v[168:171], v[212:215], v[68:71]
	v_mfma_f32_16x16x32_bf16 v[64:67], v[176:179], v[212:215], v[64:67]
	v_mfma_f32_16x16x32_bf16 v[108:111], v[172:175], v[188:191], v[108:111]
	v_mfma_f32_16x16x32_bf16 v[100:103], v[180:183], v[188:191], v[100:103]
	v_mfma_f32_16x16x32_bf16 v[92:95], v[172:175], v[196:199], v[92:95]
	v_mfma_f32_16x16x32_bf16 v[84:87], v[180:183], v[196:199], v[84:87]
	v_mfma_f32_16x16x32_bf16 v[76:79], v[172:175], v[208:211], v[76:79]
	v_mfma_f32_16x16x32_bf16 v[72:75], v[180:183], v[208:211], v[72:75]
	v_mfma_f32_16x16x32_bf16 v[68:71], v[172:175], v[216:219], v[68:71]
	v_mfma_f32_16x16x32_bf16 v[64:67], v[180:183], v[216:219], v[64:67]
	s_setprio 0
	s_barrier
; #define PG8_STAGE(bufoff, gbase, voff) do { _Pragma("unroll") for (int _i = 0; _i < 2; ++_i) \
;         __builtin_amdgcn_global_load_lds((const unsigned*)((const char*)(gbase) + (voff)[_i]), (LAS unsigned*)(lds + (bufoff) + ldsw + _i * 8192), 16, 0, 0); } while (0)
; #define PG8_LDA(dst, b, h) do { _Pragma("unroll") for (int m = 0; m < 4; ++m) _Pragma("unroll") for (int k = 0; k < 2; ++k) dst[m][k] = *(const LAS bf16x8*)(lds + PG8_SA(b, h) + aoff + m * 2048 + k * 1024); } while (0)
; #define PG8_WAIT_V(n) asm volatile("s_waitcnt vmcnt(" #n ")" ::: "memory")
; #define PG8_WAIT_L(n) asm volatile("s_waitcnt lgkmcnt(" #n ")" ::: "memory")
; #define PG8_BAR __builtin_amdgcn_s_barrier()
; #define PG8_SCHED __builtin_amdgcn_sched_barrier(0)
; template <class Epi, class Sched, bool SWAPD = false>
; __device__ __forceinline__ void gemm_phase(LAS unsigned char* lds, const Gemm g, const Sched& S, const Epi& E) {
;     ...
;             PG8_LDA(At, 1, 1); PG8_STAGE(PG8_SB(1, 0), b3, voffB); PG8_STAGE(PG8_SB(1, 1), b3 + hstepB, voffB); PG8_STAGE(PG8_SA(1, 0), a3, voffA);
;             PG8_WAIT_V(8); PG8_WAIT_L(0); PG8_BAR; PG8_MMA(1, 0, At, B0); PG8_MMA(1, 1, At, B1); PG8_BAR; PG8_SCHED;
;         }
;         if (wr == 0) PG8_BAR;
	s_add_i32 s50, s82, s21
	v_lshl_add_u64 v[204:205], v[204:205], 0, s[10:11]
	s_mov_b32 m0, s50
	ds_read_b128 v[184:187], v150 offset:49152
	ds_read_b128 v[188:191], v150 offset:50176
	ds_read_b128 v[192:195], v150 offset:51200
	ds_read_b128 v[196:199], v150 offset:52224
	ds_read_b128 v[200:203], v150 offset:53248
	ds_read_b128 v[208:211], v150 offset:54272
	ds_read_b128 v[212:215], v150 offset:55296
	ds_read_b128 v[216:219], v150 offset:56320
	global_load_lds_dwordx4 v[204:205], off
	s_add_i32 m0, s50, 0x2000
	s_add_u32 s50, s54, 0x20080
	v_lshl_add_u64 v[204:205], v[220:221], 0, s[10:11]
	s_addc_u32 s51, s55, 0
	s_add_i32 s54, s83, s21
	global_load_lds_dwordx4 v[204:205], off
	v_lshl_add_u64 v[204:205], s[50:51], 0, v[132:133]
	s_mov_b32 m0, s54
	s_nop 0
	global_load_lds_dwordx4 v[204:205], off
	v_lshl_add_u64 v[204:205], s[50:51], 0, v[128:129]
	s_add_i32 m0, s54, 0x2000
	s_nop 0
	global_load_lds_dwordx4 v[204:205], off
	v_lshl_add_u64 v[204:205], v[222:223], 0, s[10:11]
	s_mov_b32 m0, s60
	s_nop 0
	global_load_lds_dwordx4 v[204:205], off
	v_lshl_add_u64 v[204:205], v[224:225], 0, s[10:11]
	s_mov_b32 m0, s61
	s_nop 0
	global_load_lds_dwordx4 v[204:205], off
	s_waitcnt vmcnt(8) lgkmcnt(0)
	s_barrier
	s_setprio 1
	v_mfma_f32_16x16x32_bf16 v[60:63], v[152:155], v[184:187], v[60:63]
	v_mfma_f32_16x16x32_bf16 v[56:59], v[160:163], v[184:187], v[56:59]
	v_mfma_f32_16x16x32_bf16 v[52:55], v[152:155], v[192:195], v[52:55]
	v_mfma_f32_16x16x32_bf16 v[48:51], v[160:163], v[192:195], v[48:51]
	v_mfma_f32_16x16x32_bf16 v[40:43], v[152:155], v[200:203], v[40:43]
	v_mfma_f32_16x16x32_bf16 v[32:35], v[160:163], v[200:203], v[32:35]
	v_mfma_f32_16x16x32_bf16 v[24:27], v[152:155], v[212:215], v[24:27]
	v_mfma_f32_16x16x32_bf16 v[16:19], v[160:163], v[212:215], v[16:19]
	v_mfma_f32_16x16x32_bf16 v[60:63], v[156:159], v[188:191], v[60:63]
	v_mfma_f32_16x16x32_bf16 v[56:59], v[164:167], v[188:191], v[56:59]
	v_mfma_f32_16x16x32_bf16 v[52:55], v[156:159], v[196:199], v[52:55]
	v_mfma_f32_16x16x32_bf16 v[48:51], v[164:167], v[196:199], v[48:51]
	v_mfma_f32_16x16x32_bf16 v[40:43], v[156:159], v[208:211], v[40:43]
	v_mfma_f32_16x16x32_bf16 v[32:35], v[164:167], v[208:211], v[32:35]
	v_mfma_f32_16x16x32_bf16 v[24:27], v[156:159], v[216:219], v[24:27]
	v_mfma_f32_16x16x32_bf16 v[16:19], v[164:167], v[216:219], v[16:19]
	s_setprio 0
	s_setprio 1
	v_mfma_f32_16x16x32_bf16 v[44:47], v[168:171], v[184:187], v[44:47]
	v_mfma_f32_16x16x32_bf16 v[36:39], v[176:179], v[184:187], v[36:39]
	v_mfma_f32_16x16x32_bf16 v[28:31], v[168:171], v[192:195], v[28:31]
	v_mfma_f32_16x16x32_bf16 v[20:23], v[176:179], v[192:195], v[20:23]
	v_mfma_f32_16x16x32_bf16 v[12:15], v[168:171], v[200:203], v[12:15]
	v_mfma_f32_16x16x32_bf16 v[8:11], v[176:179], v[200:203], v[8:11]
	v_mfma_f32_16x16x32_bf16 v[4:7], v[168:171], v[212:215], v[4:7]
	v_mfma_f32_16x16x32_bf16 v[0:3], v[176:179], v[212:215], v[0:3]
	v_mfma_f32_16x16x32_bf16 v[44:47], v[172:175], v[188:191], v[44:47]
	v_mfma_f32_16x16x32_bf16 v[36:39], v[180:183], v[188:191], v[36:39]
	v_mfma_f32_16x16x32_bf16 v[28:31], v[172:175], v[196:199], v[28:31]
	v_mfma_f32_16x16x32_bf16 v[20:23], v[180:183], v[196:199], v[20:23]
	v_mfma_f32_16x16x32_bf16 v[12:15], v[172:175], v[208:211], v[12:15]
	v_mfma_f32_16x16x32_bf16 v[8:11], v[180:183], v[208:211], v[8:11]
	v_mfma_f32_16x16x32_bf16 v[4:7], v[172:175], v[216:219], v[4:7]
	v_mfma_f32_16x16x32_bf16 v[0:3], v[180:183], v[216:219], v[0:3]
	s_setprio 0
	s_barrier
	s_add_i32 s81, s81, 2
	s_add_u32 s79, s79, 0x100
	s_addc_u32 s80, s80, 0
	s_cmp_gt_u32 s81, 5
	s_mov_b64 s[50:51], s[52:53]
	s_cbranch_scc0 .LBB0_633
	s_and_b64 vcc, exec, s[12:13]
	s_cbranch_vccz .LBB0_636
	s_barrier

; #define PG8_STAGE(bufoff, gbase, voff) do { _Pragma("unroll") for (int _i = 0; _i < 2; ++_i) \
;         __builtin_amdgcn_global_load_lds((const unsigned*)((const char*)(gbase) + (voff)[_i]), (LAS unsigned*)(lds + (bufoff) + ldsw + _i * 8192), 16, 0, 0); } while (0)
; #define PG8_LDA(dst, b, h) do { _Pragma("unroll") for (int m = 0; m < 4; ++m) _Pragma("unroll") for (int k = 0; k < 2; ++k) dst[m][k] = *(const LAS bf16x8*)(lds + PG8_SA(b, h) + aoff + m * 2048 + k * 1024); } while (0)
; #define PG8_LDB(dst, b, h) do { _Pragma("unroll") for (int n = 0; n < 2; ++n) _Pragma("unroll") for (int k = 0; k < 2; ++k) dst[n][k] = *(const LAS bf16x8*)(lds + PG8_SB(b, h) + boff + n * 2048 + k * 1024); } while (0)
; #define PG8_WAIT_V(n) asm volatile("s_waitcnt vmcnt(" #n ")" ::: "memory")
; #define PG8_WAIT_L(n) asm volatile("s_waitcnt lgkmcnt(" #n ")" ::: "memory")
; #define PG8_BAR __builtin_amdgcn_s_barrier()
; #define PG8_SCHED __builtin_amdgcn_sched_barrier(0)
; template <class Epi, class Sched, bool SWAPD = false>
; __device__ __forceinline__ void gemm_phase(LAS unsigned char* lds, const Gemm g, const Sched& S, const Epi& E) {
;     ...
;         for (int t = 0; t < nt; t += 2) {
;             const bool last = (t == nt - 2);
;             const char* a1 = cA + (size_t)(t + 1) * kstepA;
;             const char* a2 = last ? nA : cA + (size_t)(t + 2) * kstepA; const char* b2 = last ? nB : cB + (size_t)(t + 2) * kstep;
;             const char* a3 = a2 + kstepA; const char* b3 = b2 + kstep;
;             PG8_LDB(B0, 0, 0); PG8_LDB(B1, 0, 1); PG8_SCHED; PG8_LDA(At, 0, 0); PG8_STAGE(PG8_SA(1, 1), a1 + hstepA, voffA);
;             PG8_WAIT_V(8); PG8_WAIT_L(0); PG8_BAR; PG8_MMA(0, 0, At, B0); PG8_MMA(0, 1, At, B1); PG8_BAR; PG8_SCHED;
;             PG8_LDA(At, 0, 1); PG8_STAGE(PG8_SB(0, 0), b2, voffB); PG8_STAGE(PG8_SB(0, 1), b2 + hstepB, voffB); PG8_STAGE(PG8_SA(0, 0), a2, voffA);
;             PG8_WAIT_V(8); PG8_WAIT_L(0); PG8_BAR; PG8_MMA(1, 0, At, B0); PG8_MMA(1, 1, At, B1); PG8_BAR; PG8_SCHED;
.LBB0_766:
	ds_read_b128 v[150:153], v146
	ds_read_b128 v[154:157], v146 offset:1024
	ds_read_b128 v[158:161], v146 offset:2048
	ds_read_b128 v[162:165], v146 offset:3072
	ds_read_b128 v[166:169], v147
	ds_read_b128 v[170:173], v147 offset:1024
	ds_read_b128 v[174:177], v147 offset:2048
	ds_read_b128 v[178:181], v147 offset:3072
	s_add_u32 s42, s40, 0x100
	s_addc_u32 s43, s41, 0
	s_cmp_eq_u32 s67, 8
	s_cselect_b32 s47, s61, s43
	s_cselect_b32 s46, s62, s42
	s_cselect_b32 s45, s63, s66
	s_cselect_b32 s44, s64, s65
	v_lshl_add_u64 v[142:143], s[40:41], 0, v[134:135]
	s_add_i32 m0, s33, 0xc000
	ds_read_b128 v[182:185], v148
	ds_read_b128 v[186:189], v148 offset:1024
	ds_read_b128 v[190:193], v148 offset:2048
	ds_read_b128 v[194:197], v148 offset:3072
	ds_read_b128 v[198:201], v148 offset:4096
	ds_read_b128 v[202:205], v148 offset:5120
	ds_read_b128 v[208:211], v148 offset:6144
	ds_read_b128 v[212:215], v148 offset:7168
	global_load_lds_dwordx4 v[142:143], off
	v_lshl_add_u64 v[142:143], s[40:41], 0, v[136:137]
	s_add_i32 m0, s33, 0xe000
	s_nop 0
	global_load_lds_dwordx4 v[142:143], off
	s_waitcnt vmcnt(8) lgkmcnt(0)
	s_barrier
	s_setprio 1
	v_mfma_f32_16x16x32_bf16 v[124:127], v[150:153], v[182:185], v[124:127]
	v_mfma_f32_16x16x32_bf16 v[120:123], v[158:161], v[182:185], v[120:123]
	v_mfma_f32_16x16x32_bf16 v[108:111], v[150:153], v[190:193], v[108:111]
	v_mfma_f32_16x16x32_bf16 v[104:107], v[158:161], v[190:193], v[104:107]
	v_mfma_f32_16x16x32_bf16 v[92:95], v[150:153], v[198:201], v[92:95]
	v_mfma_f32_16x16x32_bf16 v[88:91], v[158:161], v[198:201], v[88:91]
	v_mfma_f32_16x16x32_bf16 v[76:79], v[150:153], v[208:211], v[76:79]
	v_mfma_f32_16x16x32_bf16 v[72:75], v[158:161], v[208:211], v[72:75]
	v_mfma_f32_16x16x32_bf16 v[124:127], v[154:157], v[186:189], v[124:127]
	v_mfma_f32_16x16x32_bf16 v[120:123], v[162:165], v[186:189], v[120:123]
	v_mfma_f32_16x16x32_bf16 v[108:111], v[154:157], v[194:197], v[108:111]
	v_mfma_f32_16x16x32_bf16 v[104:107], v[162:165], v[194:197], v[104:107]
	v_mfma_f32_16x16x32_bf16 v[92:95], v[154:157], v[202:205], v[92:95]
	v_mfma_f32_16x16x32_bf16 v[88:91], v[162:165], v[202:205], v[88:91]
	v_mfma_f32_16x16x32_bf16 v[76:79], v[154:157], v[212:215], v[76:79]
	v_mfma_f32_16x16x32_bf16 v[72:75], v[162:165], v[212:215], v[72:75]
	s_setprio 0
	s_setprio 1
	v_mfma_f32_16x16x32_bf16 v[116:119], v[166:169], v[182:185], v[116:119]
	v_mfma_f32_16x16x32_bf16 v[112:115], v[174:177], v[182:185], v[112:115]
	v_mfma_f32_16x16x32_bf16 v[100:103], v[166:169], v[190:193], v[100:103]
	v_mfma_f32_16x16x32_bf16 v[96:99], v[174:177], v[190:193], v[96:99]
	v_mfma_f32_16x16x32_bf16 v[84:87], v[166:169], v[198:201], v[84:87]
	v_mfma_f32_16x16x32_bf16 v[80:83], v[174:177], v[198:201], v[80:83]
	v_mfma_f32_16x16x32_bf16 v[68:71], v[166:169], v[208:211], v[68:71]
	v_mfma_f32_16x16x32_bf16 v[64:67], v[174:177], v[208:211], v[64:67]
	v_mfma_f32_16x16x32_bf16 v[116:119], v[170:173], v[186:189], v[116:119]
	v_mfma_f32_16x16x32_bf16 v[112:115], v[178:181], v[186:189], v[112:115]
	v_mfma_f32_16x16x32_bf16 v[100:103], v[170:173], v[194:197], v[100:103]
	v_mfma_f32_16x16x32_bf16 v[96:99], v[178:181], v[194:197], v[96:99]
	v_mfma_f32_16x16x32_bf16 v[84:87], v[170:173], v[202:205], v[84:87]
	v_mfma_f32_16x16x32_bf16 v[80:83], v[178:181], v[202:205], v[80:83]
	v_mfma_f32_16x16x32_bf16 v[68:71], v[170:173], v[212:215], v[68:71]
	v_mfma_f32_16x16x32_bf16 v[64:67], v[178:181], v[212:215], v[64:67]
	s_setprio 0
	s_barrier
	s_add_i32 s40, s57, s21
	v_lshl_add_u64 v[142:143], s[44:45], 0, v[130:131]
	s_mov_b32 m0, s40
	ds_read_b128 v[182:185], v148 offset:16384
	ds_read_b128 v[186:189], v148 offset:17408
	ds_read_b128 v[190:193], v148 offset:18432
	ds_read_b128 v[194:197], v148 offset:19456
	ds_read_b128 v[198:201], v148 offset:20480
	ds_read_b128 v[202:205], v148 offset:21504
	ds_read_b128 v[208:211], v148 offset:22528
	ds_read_b128 v[212:215], v148 offset:23552
	global_load_lds_dwordx4 v[142:143], off
	s_add_i32 m0, s40, 0x2000
	s_add_u32 s40, s44, 0x30000
	v_lshl_add_u64 v[216:217], s[44:45], 0, v[128:129]
	s_addc_u32 s41, s45, 0
	s_add_i32 s68, s58, s21
	global_load_lds_dwordx4 v[216:217], off
	v_lshl_add_u64 v[218:219], s[40:41], 0, v[130:131]
	s_mov_b32 m0, s68
	v_lshl_add_u64 v[220:221], s[46:47], 0, v[128:129]
	global_load_lds_dwordx4 v[218:219], off
	v_lshl_add_u64 v[218:219], s[40:41], 0, v[128:129]
	s_add_i32 m0, s68, 0x2000
	s_nop 0
	global_load_lds_dwordx4 v[218:219], off
	v_lshl_add_u64 v[218:219], s[46:47], 0, v[130:131]
	s_mov_b32 m0, s33
	s_nop 0
	global_load_lds_dwordx4 v[218:219], off
	s_mov_b32 m0, s50
	s_nop 0
	global_load_lds_dwordx4 v[220:221], off
	s_waitcnt vmcnt(8) lgkmcnt(0)
	s_barrier
; #define PG8_STAGE(bufoff, gbase, voff) do { _Pragma("unroll") for (int _i = 0; _i < 2; ++_i) \
;         __builtin_amdgcn_global_load_lds((const unsigned*)((const char*)(gbase) + (voff)[_i]), (LAS unsigned*)(lds + (bufoff) + ldsw + _i * 8192), 16, 0, 0); } while (0)
; #define PG8_LDA(dst, b, h) do { _Pragma("unroll") for (int m = 0; m < 4; ++m) _Pragma("unroll") for (int k = 0; k < 2; ++k) dst[m][k] = *(const LAS bf16x8*)(lds + PG8_SA(b, h) + aoff + m * 2048 + k * 1024); } while (0)
; #define PG8_LDB(dst, b, h) do { _Pragma("unroll") for (int n = 0; n < 2; ++n) _Pragma("unroll") for (int k = 0; k < 2; ++k) dst[n][k] = *(const LAS bf16x8*)(lds + PG8_SB(b, h) + boff + n * 2048 + k * 1024); } while (0)
; #define PG8_WAIT_V(n) asm volatile("s_waitcnt vmcnt(" #n ")" ::: "memory")
; #define PG8_WAIT_L(n) asm volatile("s_waitcnt lgkmcnt(" #n ")" ::: "memory")
; #define PG8_BAR __builtin_amdgcn_s_barrier()
; #define PG8_SCHED __builtin_amdgcn_sched_barrier(0)
; template <class Epi, class Sched, bool SWAPD = false>
; __device__ __forceinline__ void gemm_phase(LAS unsigned char* lds, const Gemm g, const Sched& S, const Epi& E) {
;     ...
;             PG8_WAIT_V(8); PG8_WAIT_L(0); PG8_BAR; PG8_MMA(1, 0, At, B0); PG8_MMA(1, 1, At, B1); PG8_BAR; PG8_SCHED;
;             PG8_LDB(B0, 1, 0); PG8_LDB(B1, 1, 1); PG8_SCHED; PG8_LDA(At, 1, 0); PG8_STAGE(PG8_SA(0, 1), a2 + hstepA, voffA);
;             PG8_WAIT_V(8); PG8_WAIT_L(0); PG8_BAR; PG8_MMA(0, 0, At, B0); PG8_MMA(0, 1, At, B1); PG8_BAR; PG8_SCHED;
	s_setprio 1
	v_mfma_f32_16x16x32_bf16 v[60:63], v[150:153], v[182:185], v[60:63]
	v_mfma_f32_16x16x32_bf16 v[56:59], v[158:161], v[182:185], v[56:59]
	v_mfma_f32_16x16x32_bf16 v[44:47], v[150:153], v[190:193], v[44:47]
	v_mfma_f32_16x16x32_bf16 v[40:43], v[158:161], v[190:193], v[40:43]
	v_mfma_f32_16x16x32_bf16 v[28:31], v[150:153], v[198:201], v[28:31]
	v_mfma_f32_16x16x32_bf16 v[24:27], v[158:161], v[198:201], v[24:27]
	v_mfma_f32_16x16x32_bf16 v[12:15], v[150:153], v[208:211], v[12:15]
	v_mfma_f32_16x16x32_bf16 v[8:11], v[158:161], v[208:211], v[8:11]
	v_mfma_f32_16x16x32_bf16 v[60:63], v[154:157], v[186:189], v[60:63]
	v_mfma_f32_16x16x32_bf16 v[56:59], v[162:165], v[186:189], v[56:59]
	v_mfma_f32_16x16x32_bf16 v[44:47], v[154:157], v[194:197], v[44:47]
	v_mfma_f32_16x16x32_bf16 v[40:43], v[162:165], v[194:197], v[40:43]
	v_mfma_f32_16x16x32_bf16 v[28:31], v[154:157], v[202:205], v[28:31]
	v_mfma_f32_16x16x32_bf16 v[24:27], v[162:165], v[202:205], v[24:27]
	v_mfma_f32_16x16x32_bf16 v[12:15], v[154:157], v[212:215], v[12:15]
	v_mfma_f32_16x16x32_bf16 v[8:11], v[162:165], v[212:215], v[8:11]
	s_setprio 0
	s_setprio 1
	v_mfma_f32_16x16x32_bf16 v[52:55], v[166:169], v[182:185], v[52:55]
	v_mfma_f32_16x16x32_bf16 v[48:51], v[174:177], v[182:185], v[48:51]
	v_mfma_f32_16x16x32_bf16 v[36:39], v[166:169], v[190:193], v[36:39]
	v_mfma_f32_16x16x32_bf16 v[32:35], v[174:177], v[190:193], v[32:35]
	v_mfma_f32_16x16x32_bf16 v[20:23], v[166:169], v[198:201], v[20:23]
	v_mfma_f32_16x16x32_bf16 v[16:19], v[174:177], v[198:201], v[16:19]
	v_mfma_f32_16x16x32_bf16 v[4:7], v[166:169], v[208:211], v[4:7]
	v_mfma_f32_16x16x32_bf16 v[0:3], v[174:177], v[208:211], v[0:3]
	v_mfma_f32_16x16x32_bf16 v[52:55], v[170:173], v[186:189], v[52:55]
	v_mfma_f32_16x16x32_bf16 v[48:51], v[178:181], v[186:189], v[48:51]
	v_mfma_f32_16x16x32_bf16 v[36:39], v[170:173], v[194:197], v[36:39]
	v_mfma_f32_16x16x32_bf16 v[32:35], v[178:181], v[194:197], v[32:35]
	v_mfma_f32_16x16x32_bf16 v[20:23], v[170:173], v[202:205], v[20:23]
	v_mfma_f32_16x16x32_bf16 v[16:19], v[178:181], v[202:205], v[16:19]
	v_mfma_f32_16x16x32_bf16 v[4:7], v[170:173], v[212:215], v[4:7]
	v_mfma_f32_16x16x32_bf16 v[0:3], v[178:181], v[212:215], v[0:3]
	s_setprio 0
	s_barrier
	s_add_i32 s68, 0, 0x18000
	v_add_u32_e32 v149, s68, v144
	s_add_i32 s69, 0, 0x1c000
	ds_read_b128 v[150:153], v149
	ds_read_b128 v[154:157], v149 offset:1024
	ds_read_b128 v[158:161], v149 offset:2048
	ds_read_b128 v[162:165], v149 offset:3072
	v_add_u32_e32 v149, s69, v144
	ds_read_b128 v[166:169], v149
	ds_read_b128 v[170:173], v149 offset:1024
	ds_read_b128 v[174:177], v149 offset:2048
	ds_read_b128 v[178:181], v149 offset:3072
	s_add_u32 s40, s46, 0x30000
	s_addc_u32 s41, s47, 0
	s_mov_b32 m0, s51
	v_lshl_add_u64 v[222:223], s[40:41], 0, v[130:131]
	ds_read_b128 v[182:185], v148 offset:32768
	ds_read_b128 v[186:189], v148 offset:33792
	ds_read_b128 v[190:193], v148 offset:34816
	ds_read_b128 v[194:197], v148 offset:35840
	ds_read_b128 v[198:201], v148 offset:36864
	ds_read_b128 v[202:205], v148 offset:37888
	ds_read_b128 v[208:211], v148 offset:38912
	ds_read_b128 v[212:215], v148 offset:39936
	global_load_lds_dwordx4 v[222:223], off
	v_lshl_add_u64 v[222:223], s[40:41], 0, v[128:129]
	s_mov_b32 m0, s52
	s_nop 0
	global_load_lds_dwordx4 v[222:223], off
	s_waitcnt vmcnt(8) lgkmcnt(0)
	s_barrier
	s_setprio 1
	v_mfma_f32_16x16x32_bf16 v[124:127], v[150:153], v[182:185], v[124:127]
	v_mfma_f32_16x16x32_bf16 v[120:123], v[158:161], v[182:185], v[120:123]
	v_mfma_f32_16x16x32_bf16 v[108:111], v[150:153], v[190:193], v[108:111]
	v_mfma_f32_16x16x32_bf16 v[104:107], v[158:161], v[190:193], v[104:107]
	v_mfma_f32_16x16x32_bf16 v[92:95], v[150:153], v[198:201], v[92:95]
	v_mfma_f32_16x16x32_bf16 v[88:91], v[158:161], v[198:201], v[88:91]
	v_mfma_f32_16x16x32_bf16 v[76:79], v[150:153], v[208:211], v[76:79]
	v_mfma_f32_16x16x32_bf16 v[72:75], v[158:161], v[208:211], v[72:75]
	v_mfma_f32_16x16x32_bf16 v[124:127], v[154:157], v[186:189], v[124:127]
	v_mfma_f32_16x16x32_bf16 v[120:123], v[162:165], v[186:189], v[120:123]
	v_mfma_f32_16x16x32_bf16 v[108:111], v[154:157], v[194:197], v[108:111]
	v_mfma_f32_16x16x32_bf16 v[104:107], v[162:165], v[194:197], v[104:107]
	v_mfma_f32_16x16x32_bf16 v[92:95], v[154:157], v[202:205], v[92:95]
	v_mfma_f32_16x16x32_bf16 v[88:91], v[162:165], v[202:205], v[88:91]
	v_mfma_f32_16x16x32_bf16 v[76:79], v[154:157], v[212:215], v[76:79]
	v_mfma_f32_16x16x32_bf16 v[72:75], v[162:165], v[212:215], v[72:75]
	s_setprio 0
	s_setprio 1
	v_mfma_f32_16x16x32_bf16 v[116:119], v[166:169], v[182:185], v[116:119]
	v_mfma_f32_16x16x32_bf16 v[112:115], v[174:177], v[182:185], v[112:115]
	v_mfma_f32_16x16x32_bf16 v[100:103], v[166:169], v[190:193], v[100:103]
	v_mfma_f32_16x16x32_bf16 v[96:99], v[174:177], v[190:193], v[96:99]
	v_mfma_f32_16x16x32_bf16 v[84:87], v[166:169], v[198:201], v[84:87]
	v_mfma_f32_16x16x32_bf16 v[80:83], v[174:177], v[198:201], v[80:83]
	v_mfma_f32_16x16x32_bf16 v[68:71], v[166:169], v[208:211], v[68:71]
	v_mfma_f32_16x16x32_bf16 v[64:67], v[174:177], v[208:211], v[64:67]
	v_mfma_f32_16x16x32_bf16 v[116:119], v[170:173], v[186:189], v[116:119]
	v_mfma_f32_16x16x32_bf16 v[112:115], v[178:181], v[186:189], v[112:115]
	v_mfma_f32_16x16x32_bf16 v[100:103], v[170:173], v[194:197], v[100:103]
	v_mfma_f32_16x16x32_bf16 v[96:99], v[178:181], v[194:197], v[96:99]
	v_mfma_f32_16x16x32_bf16 v[84:87], v[170:173], v[202:205], v[84:87]
	v_mfma_f32_16x16x32_bf16 v[80:83], v[178:181], v[202:205], v[80:83]
	v_mfma_f32_16x16x32_bf16 v[68:71], v[170:173], v[212:215], v[68:71]
	v_mfma_f32_16x16x32_bf16 v[64:67], v[178:181], v[212:215], v[64:67]
	s_setprio 0
	s_barrier
; #define PG8_STAGE(bufoff, gbase, voff) do { _Pragma("unroll") for (int _i = 0; _i < 2; ++_i) \
;         __builtin_amdgcn_global_load_lds((const unsigned*)((const char*)(gbase) + (voff)[_i]), (LAS unsigned*)(lds + (bufoff) + ldsw + _i * 8192), 16, 0, 0); } while (0)
; #define PG8_LDA(dst, b, h) do { _Pragma("unroll") for (int m = 0; m < 4; ++m) _Pragma("unroll") for (int k = 0; k < 2; ++k) dst[m][k] = *(const LAS bf16x8*)(lds + PG8_SA(b, h) + aoff + m * 2048 + k * 1024); } while (0)
; #define PG8_WAIT_V(n) asm volatile("s_waitcnt vmcnt(" #n ")" ::: "memory")
; #define PG8_WAIT_L(n) asm volatile("s_waitcnt lgkmcnt(" #n ")" ::: "memory")
; #define PG8_BAR __builtin_amdgcn_s_barrier()
; #define PG8_SCHED __builtin_amdgcn_sched_barrier(0)
; template <class Epi, class Sched, bool SWAPD = false>
; __device__ __forceinline__ void gemm_phase(LAS unsigned char* lds, const Gemm g, const Sched& S, const Epi& E) {
;     ...
;             PG8_LDA(At, 1, 1); PG8_STAGE(PG8_SB(1, 0), b3, voffB); PG8_STAGE(PG8_SB(1, 1), b3 + hstepB, voffB); PG8_STAGE(PG8_SA(1, 0), a3, voffA);
;             PG8_WAIT_V(8); PG8_WAIT_L(0); PG8_BAR; PG8_MMA(1, 0, At, B0); PG8_MMA(1, 1, At, B1); PG8_BAR; PG8_SCHED;
;         }
;         if (wr == 0) PG8_BAR;
	s_add_i32 s40, s68, s21
	v_lshl_add_u64 v[142:143], v[142:143], 0, s[12:13]
	s_mov_b32 m0, s40
	ds_read_b128 v[182:185], v148 offset:49152
	ds_read_b128 v[186:189], v148 offset:50176
	ds_read_b128 v[190:193], v148 offset:51200
	ds_read_b128 v[194:197], v148 offset:52224
	ds_read_b128 v[198:201], v148 offset:53248
	ds_read_b128 v[202:205], v148 offset:54272
	ds_read_b128 v[208:211], v148 offset:55296
	ds_read_b128 v[212:215], v148 offset:56320
	global_load_lds_dwordx4 v[142:143], off
	s_add_i32 m0, s40, 0x2000
	s_add_u32 s40, s44, 0x30080
	v_lshl_add_u64 v[142:143], v[216:217], 0, s[12:13]
	s_addc_u32 s41, s45, 0
	s_add_i32 s44, s69, s21
	global_load_lds_dwordx4 v[142:143], off
	v_lshl_add_u64 v[142:143], s[40:41], 0, v[130:131]
	s_mov_b32 m0, s44
	s_nop 0
	global_load_lds_dwordx4 v[142:143], off
	v_lshl_add_u64 v[142:143], s[40:41], 0, v[128:129]
	s_add_i32 m0, s44, 0x2000
	s_nop 0
	global_load_lds_dwordx4 v[142:143], off
	v_lshl_add_u64 v[142:143], v[218:219], 0, s[12:13]
	s_mov_b32 m0, s54
	s_nop 0
	global_load_lds_dwordx4 v[142:143], off
	v_lshl_add_u64 v[142:143], v[220:221], 0, s[12:13]
	s_mov_b32 m0, s55
	s_nop 0
	global_load_lds_dwordx4 v[142:143], off
	s_waitcnt vmcnt(8) lgkmcnt(0)
	s_barrier
	s_setprio 1
	v_mfma_f32_16x16x32_bf16 v[60:63], v[150:153], v[182:185], v[60:63]
	v_mfma_f32_16x16x32_bf16 v[56:59], v[158:161], v[182:185], v[56:59]
	v_mfma_f32_16x16x32_bf16 v[44:47], v[150:153], v[190:193], v[44:47]
	v_mfma_f32_16x16x32_bf16 v[40:43], v[158:161], v[190:193], v[40:43]
	v_mfma_f32_16x16x32_bf16 v[28:31], v[150:153], v[198:201], v[28:31]
	v_mfma_f32_16x16x32_bf16 v[24:27], v[158:161], v[198:201], v[24:27]
	v_mfma_f32_16x16x32_bf16 v[12:15], v[150:153], v[208:211], v[12:15]
	v_mfma_f32_16x16x32_bf16 v[8:11], v[158:161], v[208:211], v[8:11]
	v_mfma_f32_16x16x32_bf16 v[60:63], v[154:157], v[186:189], v[60:63]
	v_mfma_f32_16x16x32_bf16 v[56:59], v[162:165], v[186:189], v[56:59]
	v_mfma_f32_16x16x32_bf16 v[44:47], v[154:157], v[194:197], v[44:47]
	v_mfma_f32_16x16x32_bf16 v[40:43], v[162:165], v[194:197], v[40:43]
	v_mfma_f32_16x16x32_bf16 v[28:31], v[154:157], v[202:205], v[28:31]
	v_mfma_f32_16x16x32_bf16 v[24:27], v[162:165], v[202:205], v[24:27]
	v_mfma_f32_16x16x32_bf16 v[12:15], v[154:157], v[212:215], v[12:15]
	v_mfma_f32_16x16x32_bf16 v[8:11], v[162:165], v[212:215], v[8:11]
	s_setprio 0
	s_setprio 1
	v_mfma_f32_16x16x32_bf16 v[52:55], v[166:169], v[182:185], v[52:55]
	v_mfma_f32_16x16x32_bf16 v[48:51], v[174:177], v[182:185], v[48:51]
	v_mfma_f32_16x16x32_bf16 v[36:39], v[166:169], v[190:193], v[36:39]
	v_mfma_f32_16x16x32_bf16 v[32:35], v[174:177], v[190:193], v[32:35]
	v_mfma_f32_16x16x32_bf16 v[20:23], v[166:169], v[198:201], v[20:23]
	v_mfma_f32_16x16x32_bf16 v[16:19], v[174:177], v[198:201], v[16:19]
	v_mfma_f32_16x16x32_bf16 v[4:7], v[166:169], v[208:211], v[4:7]
	v_mfma_f32_16x16x32_bf16 v[0:3], v[174:177], v[208:211], v[0:3]
	v_mfma_f32_16x16x32_bf16 v[52:55], v[170:173], v[186:189], v[52:55]
	v_mfma_f32_16x16x32_bf16 v[48:51], v[178:181], v[186:189], v[48:51]
	v_mfma_f32_16x16x32_bf16 v[36:39], v[170:173], v[194:197], v[36:39]
	v_mfma_f32_16x16x32_bf16 v[32:35], v[178:181], v[194:197], v[32:35]
	v_mfma_f32_16x16x32_bf16 v[20:23], v[170:173], v[202:205], v[20:23]
	v_mfma_f32_16x16x32_bf16 v[16:19], v[178:181], v[202:205], v[16:19]
	v_mfma_f32_16x16x32_bf16 v[4:7], v[170:173], v[212:215], v[4:7]
	v_mfma_f32_16x16x32_bf16 v[0:3], v[178:181], v[212:215], v[0:3]
	s_setprio 0
	s_barrier
	s_add_i32 s67, s67, 2
	s_add_u32 s65, s65, 0x100
	s_addc_u32 s66, s66, 0
	s_cmp_gt_u32 s67, 9
	s_mov_b64 s[40:41], s[42:43]
	s_cbranch_scc0 .LBB0_766
	s_and_b64 vcc, exec, s[24:25]
	s_cbranch_vccz .LBB0_769
	s_barrier

; #define PG8_STAGE(bufoff, gbase, voff) do { _Pragma("unroll") for (int _i = 0; _i < 2; ++_i) \
;         __builtin_amdgcn_global_load_lds((const unsigned*)((const char*)(gbase) + (voff)[_i]), (LAS unsigned*)(lds + (bufoff) + ldsw + _i * 8192), 16, 0, 0); } while (0)
; #define PG8_LDA(dst, b, h) do { _Pragma("unroll") for (int m = 0; m < 4; ++m) _Pragma("unroll") for (int k = 0; k < 2; ++k) dst[m][k] = *(const LAS bf16x8*)(lds + PG8_SA(b, h) + aoff + m * 2048 + k * 1024); } while (0)
; #define PG8_LDB(dst, b, h) do { _Pragma("unroll") for (int n = 0; n < 2; ++n) _Pragma("unroll") for (int k = 0; k < 2; ++k) dst[n][k] = *(const LAS bf16x8*)(lds + PG8_SB(b, h) + boff + n * 2048 + k * 1024); } while (0)
; #define PG8_WAIT_V(n) asm volatile("s_waitcnt vmcnt(" #n ")" ::: "memory")
; #define PG8_WAIT_L(n) asm volatile("s_waitcnt lgkmcnt(" #n ")" ::: "memory")
; #define PG8_BAR __builtin_amdgcn_s_barrier()
; #define PG8_SCHED __builtin_amdgcn_sched_barrier(0)
; template <class Epi, class Sched, bool SWAPD = false>
; __device__ __forceinline__ void gemm_phase(LAS unsigned char* lds, const Gemm g, const Sched& S, const Epi& E) {
;     ...
;         for (int t = 0; t < nt; t += 2) {
;             const bool last = (t == nt - 2);
;             const char* a1 = cA + (size_t)(t + 1) * kstepA;
;             const char* a2 = last ? nA : cA + (size_t)(t + 2) * kstepA; const char* b2 = last ? nB : cB + (size_t)(t + 2) * kstep;
;             const char* a3 = a2 + kstepA; const char* b3 = b2 + kstep;
;             PG8_LDB(B0, 0, 0); PG8_LDB(B1, 0, 1); PG8_SCHED; PG8_LDA(At, 0, 0); PG8_STAGE(PG8_SA(1, 1), a1 + hstepA, voffA);
;             PG8_WAIT_V(8); PG8_WAIT_L(0); PG8_BAR; PG8_MMA(0, 0, At, B0); PG8_MMA(0, 1, At, B1); PG8_BAR; PG8_SCHED;
;             PG8_LDA(At, 0, 1); PG8_STAGE(PG8_SB(0, 0), b2, voffB); PG8_STAGE(PG8_SB(0, 1), b2 + hstepB, voffB); PG8_STAGE(PG8_SA(0, 0), a2, voffA);
;             PG8_WAIT_V(8); PG8_WAIT_L(0); PG8_BAR; PG8_MMA(1, 0, At, B0); PG8_MMA(1, 1, At, B1); PG8_BAR; PG8_SCHED;
.LBB0_842:
	ds_read_b128 v[146:149], v153
	ds_read_b128 v[156:159], v153 offset:1024
	ds_read_b128 v[160:163], v153 offset:2048
	ds_read_b128 v[164:167], v153 offset:3072
	ds_read_b128 v[168:171], v154
	ds_read_b128 v[172:175], v154 offset:1024
	ds_read_b128 v[176:179], v154 offset:2048
	ds_read_b128 v[180:183], v154 offset:3072
	s_add_u32 s44, s42, 0x800000
	s_addc_u32 s45, s43, 0
	s_cmp_eq_u32 s62, 4
	s_cselect_b32 s52, s25, s44
	s_cselect_b32 s53, s23, s45
	s_cselect_b32 s50, s59, s60
	s_cselect_b32 s51, s35, s61
	s_add_u32 s46, s52, 0x400000
	s_addc_u32 s47, s53, 0
	v_lshl_add_u64 v[204:205], s[42:43], 0, v[138:139]
	s_add_i32 m0, s30, 0xc000
	ds_read_b128 v[184:187], v155
	ds_read_b128 v[188:191], v155 offset:1024
	ds_read_b128 v[192:195], v155 offset:2048
	ds_read_b128 v[196:199], v155 offset:3072
	ds_read_b128 v[200:203], v155 offset:4096
	ds_read_b128 v[208:211], v155 offset:5120
	ds_read_b128 v[212:215], v155 offset:6144
	ds_read_b128 v[216:219], v155 offset:7168
	global_load_lds_dwordx4 v[204:205], off
	v_lshl_add_u64 v[204:205], s[42:43], 0, v[140:141]
	s_add_i32 m0, s30, 0xe000
	s_nop 0
	global_load_lds_dwordx4 v[204:205], off
	s_waitcnt vmcnt(8) lgkmcnt(0)
	s_barrier
	s_setprio 1
	v_mfma_f32_16x16x32_bf16 v[124:127], v[146:149], v[184:187], v[124:127]
	v_mfma_f32_16x16x32_bf16 v[120:123], v[160:163], v[184:187], v[120:123]
	v_mfma_f32_16x16x32_bf16 v[108:111], v[146:149], v[192:195], v[108:111]
	v_mfma_f32_16x16x32_bf16 v[104:107], v[160:163], v[192:195], v[104:107]
	v_mfma_f32_16x16x32_bf16 v[92:95], v[146:149], v[200:203], v[92:95]
	v_mfma_f32_16x16x32_bf16 v[88:91], v[160:163], v[200:203], v[88:91]
	v_mfma_f32_16x16x32_bf16 v[76:79], v[146:149], v[212:215], v[76:79]
	v_mfma_f32_16x16x32_bf16 v[72:75], v[160:163], v[212:215], v[72:75]
	v_mfma_f32_16x16x32_bf16 v[124:127], v[156:159], v[188:191], v[124:127]
	v_mfma_f32_16x16x32_bf16 v[120:123], v[164:167], v[188:191], v[120:123]
	v_mfma_f32_16x16x32_bf16 v[108:111], v[156:159], v[196:199], v[108:111]
	v_mfma_f32_16x16x32_bf16 v[104:107], v[164:167], v[196:199], v[104:107]
	v_mfma_f32_16x16x32_bf16 v[92:95], v[156:159], v[208:211], v[92:95]
	v_mfma_f32_16x16x32_bf16 v[88:91], v[164:167], v[208:211], v[88:91]
	v_mfma_f32_16x16x32_bf16 v[76:79], v[156:159], v[216:219], v[76:79]
	v_mfma_f32_16x16x32_bf16 v[72:75], v[164:167], v[216:219], v[72:75]
	s_setprio 0
	s_setprio 1
	v_mfma_f32_16x16x32_bf16 v[116:119], v[168:171], v[184:187], v[116:119]
	v_mfma_f32_16x16x32_bf16 v[112:115], v[176:179], v[184:187], v[112:115]
	v_mfma_f32_16x16x32_bf16 v[100:103], v[168:171], v[192:195], v[100:103]
	v_mfma_f32_16x16x32_bf16 v[96:99], v[176:179], v[192:195], v[96:99]
	v_mfma_f32_16x16x32_bf16 v[84:87], v[168:171], v[200:203], v[84:87]
	v_mfma_f32_16x16x32_bf16 v[80:83], v[176:179], v[200:203], v[80:83]
	v_mfma_f32_16x16x32_bf16 v[68:71], v[168:171], v[212:215], v[68:71]
	v_mfma_f32_16x16x32_bf16 v[64:67], v[176:179], v[212:215], v[64:67]
	v_mfma_f32_16x16x32_bf16 v[116:119], v[172:175], v[188:191], v[116:119]
	v_mfma_f32_16x16x32_bf16 v[112:115], v[180:183], v[188:191], v[112:115]
	v_mfma_f32_16x16x32_bf16 v[100:103], v[172:175], v[196:199], v[100:103]
	v_mfma_f32_16x16x32_bf16 v[96:99], v[180:183], v[196:199], v[96:99]
	v_mfma_f32_16x16x32_bf16 v[84:87], v[172:175], v[208:211], v[84:87]
	v_mfma_f32_16x16x32_bf16 v[80:83], v[180:183], v[208:211], v[80:83]
	v_mfma_f32_16x16x32_bf16 v[68:71], v[172:175], v[216:219], v[68:71]
	v_mfma_f32_16x16x32_bf16 v[64:67], v[180:183], v[216:219], v[64:67]
	s_setprio 0
	s_barrier
	s_add_i32 s42, s57, s21
	v_lshl_add_u64 v[204:205], s[50:51], 0, v[130:131]
	s_mov_b32 m0, s42
	ds_read_b128 v[184:187], v155 offset:16384
	ds_read_b128 v[188:191], v155 offset:17408
	ds_read_b128 v[192:195], v155 offset:18432
	ds_read_b128 v[196:199], v155 offset:19456
	ds_read_b128 v[200:203], v155 offset:20480
	ds_read_b128 v[208:211], v155 offset:21504
	ds_read_b128 v[212:215], v155 offset:22528
	ds_read_b128 v[216:219], v155 offset:23552
	global_load_lds_dwordx4 v[204:205], off
	s_add_i32 m0, s42, 0x2000
	s_add_u32 s42, s50, 0x20000
	v_lshl_add_u64 v[220:221], s[50:51], 0, v[134:135]
	s_addc_u32 s43, s51, 0
	s_add_i32 s63, s58, s21
	global_load_lds_dwordx4 v[220:221], off
	v_lshl_add_u64 v[222:223], s[42:43], 0, v[130:131]
	s_mov_b32 m0, s63
	s_nop 0
	global_load_lds_dwordx4 v[222:223], off
	v_lshl_add_u64 v[222:223], s[42:43], 0, v[134:135]
	s_add_i32 m0, s63, 0x2000
	s_nop 0
	global_load_lds_dwordx4 v[222:223], off
	v_lshl_add_u64 v[222:223], s[52:53], 0, v[128:129]
	s_mov_b32 m0, s30
	s_nop 0
	global_load_lds_dwordx4 v[222:223], off
	v_lshl_add_u64 v[222:223], s[52:53], 0, v[132:133]
	s_mov_b32 m0, s31
	s_nop 0
	global_load_lds_dwordx4 v[222:223], off
	s_waitcnt vmcnt(8) lgkmcnt(0)
	s_barrier
; #define PG8_STAGE(bufoff, gbase, voff) do { _Pragma("unroll") for (int _i = 0; _i < 2; ++_i) \
;         __builtin_amdgcn_global_load_lds((const unsigned*)((const char*)(gbase) + (voff)[_i]), (LAS unsigned*)(lds + (bufoff) + ldsw + _i * 8192), 16, 0, 0); } while (0)
; #define PG8_LDA(dst, b, h) do { _Pragma("unroll") for (int m = 0; m < 4; ++m) _Pragma("unroll") for (int k = 0; k < 2; ++k) dst[m][k] = *(const LAS bf16x8*)(lds + PG8_SA(b, h) + aoff + m * 2048 + k * 1024); } while (0)
; #define PG8_LDB(dst, b, h) do { _Pragma("unroll") for (int n = 0; n < 2; ++n) _Pragma("unroll") for (int k = 0; k < 2; ++k) dst[n][k] = *(const LAS bf16x8*)(lds + PG8_SB(b, h) + boff + n * 2048 + k * 1024); } while (0)
; #define PG8_WAIT_V(n) asm volatile("s_waitcnt vmcnt(" #n ")" ::: "memory")
; #define PG8_WAIT_L(n) asm volatile("s_waitcnt lgkmcnt(" #n ")" ::: "memory")
; #define PG8_BAR __builtin_amdgcn_s_barrier()
; #define PG8_SCHED __builtin_amdgcn_sched_barrier(0)
; template <class Epi, class Sched, bool SWAPD = false>
; __device__ __forceinline__ void gemm_phase(LAS unsigned char* lds, const Gemm g, const Sched& S, const Epi& E) {
;     ...
;             PG8_WAIT_V(8); PG8_WAIT_L(0); PG8_BAR; PG8_MMA(1, 0, At, B0); PG8_MMA(1, 1, At, B1); PG8_BAR; PG8_SCHED;
;             PG8_LDB(B0, 1, 0); PG8_LDB(B1, 1, 1); PG8_SCHED; PG8_LDA(At, 1, 0); PG8_STAGE(PG8_SA(0, 1), a2 + hstepA, voffA);
;             PG8_WAIT_V(8); PG8_WAIT_L(0); PG8_BAR; PG8_MMA(0, 0, At, B0); PG8_MMA(0, 1, At, B1); PG8_BAR; PG8_SCHED;
	s_setprio 1
	v_mfma_f32_16x16x32_bf16 v[60:63], v[146:149], v[184:187], v[60:63]
	v_mfma_f32_16x16x32_bf16 v[56:59], v[160:163], v[184:187], v[56:59]
	v_mfma_f32_16x16x32_bf16 v[44:47], v[146:149], v[192:195], v[44:47]
	v_mfma_f32_16x16x32_bf16 v[40:43], v[160:163], v[192:195], v[40:43]
	v_mfma_f32_16x16x32_bf16 v[28:31], v[146:149], v[200:203], v[28:31]
	v_mfma_f32_16x16x32_bf16 v[24:27], v[160:163], v[200:203], v[24:27]
	v_mfma_f32_16x16x32_bf16 v[12:15], v[146:149], v[212:215], v[12:15]
	v_mfma_f32_16x16x32_bf16 v[8:11], v[160:163], v[212:215], v[8:11]
	v_mfma_f32_16x16x32_bf16 v[60:63], v[156:159], v[188:191], v[60:63]
	v_mfma_f32_16x16x32_bf16 v[56:59], v[164:167], v[188:191], v[56:59]
	v_mfma_f32_16x16x32_bf16 v[44:47], v[156:159], v[196:199], v[44:47]
	v_mfma_f32_16x16x32_bf16 v[40:43], v[164:167], v[196:199], v[40:43]
	v_mfma_f32_16x16x32_bf16 v[28:31], v[156:159], v[208:211], v[28:31]
	v_mfma_f32_16x16x32_bf16 v[24:27], v[164:167], v[208:211], v[24:27]
	v_mfma_f32_16x16x32_bf16 v[12:15], v[156:159], v[216:219], v[12:15]
	v_mfma_f32_16x16x32_bf16 v[8:11], v[164:167], v[216:219], v[8:11]
	s_setprio 0
	s_setprio 1
	v_mfma_f32_16x16x32_bf16 v[52:55], v[168:171], v[184:187], v[52:55]
	v_mfma_f32_16x16x32_bf16 v[48:51], v[176:179], v[184:187], v[48:51]
	v_mfma_f32_16x16x32_bf16 v[36:39], v[168:171], v[192:195], v[36:39]
	v_mfma_f32_16x16x32_bf16 v[32:35], v[176:179], v[192:195], v[32:35]
	v_mfma_f32_16x16x32_bf16 v[20:23], v[168:171], v[200:203], v[20:23]
	v_mfma_f32_16x16x32_bf16 v[16:19], v[176:179], v[200:203], v[16:19]
	v_mfma_f32_16x16x32_bf16 v[4:7], v[168:171], v[212:215], v[4:7]
	v_mfma_f32_16x16x32_bf16 v[0:3], v[176:179], v[212:215], v[0:3]
	v_mfma_f32_16x16x32_bf16 v[52:55], v[172:175], v[188:191], v[52:55]
	v_mfma_f32_16x16x32_bf16 v[48:51], v[180:183], v[188:191], v[48:51]
	v_mfma_f32_16x16x32_bf16 v[36:39], v[172:175], v[196:199], v[36:39]
	v_mfma_f32_16x16x32_bf16 v[32:35], v[180:183], v[196:199], v[32:35]
	v_mfma_f32_16x16x32_bf16 v[20:23], v[172:175], v[208:211], v[20:23]
	v_mfma_f32_16x16x32_bf16 v[16:19], v[180:183], v[208:211], v[16:19]
	v_mfma_f32_16x16x32_bf16 v[4:7], v[172:175], v[216:219], v[4:7]
	v_mfma_f32_16x16x32_bf16 v[0:3], v[180:183], v[216:219], v[0:3]
	s_setprio 0
	s_barrier
	s_add_i32 s63, 0, 0x18000
	s_add_i32 s64, 0, 0x1c000
	v_add_u32_e32 v164, s63, v151
	v_add_u32_e32 v180, s64, v151
	ds_read_b128 v[146:149], v164
	ds_read_b128 v[156:159], v164 offset:1024
	ds_read_b128 v[160:163], v164 offset:2048
	ds_read_b128 v[164:167], v164 offset:3072
	ds_read_b128 v[168:171], v180
	ds_read_b128 v[172:175], v180 offset:1024
	ds_read_b128 v[176:179], v180 offset:2048
	ds_read_b128 v[180:183], v180 offset:3072
	s_add_u32 s42, s52, 0x1000
	s_addc_u32 s43, s53, 0
	s_mov_b32 m0, s33
	v_lshl_add_u64 v[222:223], s[42:43], 0, v[128:129]
	ds_read_b128 v[184:187], v155 offset:32768
	ds_read_b128 v[188:191], v155 offset:33792
	ds_read_b128 v[192:195], v155 offset:34816
	ds_read_b128 v[196:199], v155 offset:35840
	ds_read_b128 v[200:203], v155 offset:36864
	ds_read_b128 v[208:211], v155 offset:37888
	ds_read_b128 v[212:215], v155 offset:38912
	ds_read_b128 v[216:219], v155 offset:39936
	global_load_lds_dwordx4 v[222:223], off
	v_lshl_add_u64 v[222:223], s[42:43], 0, v[132:133]
	s_mov_b32 m0, s41
	s_nop 0
	global_load_lds_dwordx4 v[222:223], off
	s_waitcnt vmcnt(8) lgkmcnt(0)
	s_barrier
	s_setprio 1
	v_mfma_f32_16x16x32_bf16 v[124:127], v[146:149], v[184:187], v[124:127]
	v_mfma_f32_16x16x32_bf16 v[120:123], v[160:163], v[184:187], v[120:123]
	v_mfma_f32_16x16x32_bf16 v[108:111], v[146:149], v[192:195], v[108:111]
	v_mfma_f32_16x16x32_bf16 v[104:107], v[160:163], v[192:195], v[104:107]
	v_mfma_f32_16x16x32_bf16 v[92:95], v[146:149], v[200:203], v[92:95]
	v_mfma_f32_16x16x32_bf16 v[88:91], v[160:163], v[200:203], v[88:91]
	v_mfma_f32_16x16x32_bf16 v[76:79], v[146:149], v[212:215], v[76:79]
	v_mfma_f32_16x16x32_bf16 v[72:75], v[160:163], v[212:215], v[72:75]
	v_mfma_f32_16x16x32_bf16 v[124:127], v[156:159], v[188:191], v[124:127]
	v_mfma_f32_16x16x32_bf16 v[120:123], v[164:167], v[188:191], v[120:123]
	v_mfma_f32_16x16x32_bf16 v[108:111], v[156:159], v[196:199], v[108:111]
	v_mfma_f32_16x16x32_bf16 v[104:107], v[164:167], v[196:199], v[104:107]
	v_mfma_f32_16x16x32_bf16 v[92:95], v[156:159], v[208:211], v[92:95]
	v_mfma_f32_16x16x32_bf16 v[88:91], v[164:167], v[208:211], v[88:91]
	v_mfma_f32_16x16x32_bf16 v[76:79], v[156:159], v[216:219], v[76:79]
	v_mfma_f32_16x16x32_bf16 v[72:75], v[164:167], v[216:219], v[72:75]
	s_setprio 0
	s_setprio 1
	v_mfma_f32_16x16x32_bf16 v[116:119], v[168:171], v[184:187], v[116:119]
	v_mfma_f32_16x16x32_bf16 v[112:115], v[176:179], v[184:187], v[112:115]
	v_mfma_f32_16x16x32_bf16 v[100:103], v[168:171], v[192:195], v[100:103]
	v_mfma_f32_16x16x32_bf16 v[96:99], v[176:179], v[192:195], v[96:99]
	v_mfma_f32_16x16x32_bf16 v[84:87], v[168:171], v[200:203], v[84:87]
	v_mfma_f32_16x16x32_bf16 v[80:83], v[176:179], v[200:203], v[80:83]
	v_mfma_f32_16x16x32_bf16 v[68:71], v[168:171], v[212:215], v[68:71]
	v_mfma_f32_16x16x32_bf16 v[64:67], v[176:179], v[212:215], v[64:67]
	v_mfma_f32_16x16x32_bf16 v[116:119], v[172:175], v[188:191], v[116:119]
	v_mfma_f32_16x16x32_bf16 v[112:115], v[180:183], v[188:191], v[112:115]
	v_mfma_f32_16x16x32_bf16 v[100:103], v[172:175], v[196:199], v[100:103]
	v_mfma_f32_16x16x32_bf16 v[96:99], v[180:183], v[196:199], v[96:99]
	v_mfma_f32_16x16x32_bf16 v[84:87], v[172:175], v[208:211], v[84:87]
	v_mfma_f32_16x16x32_bf16 v[80:83], v[180:183], v[208:211], v[80:83]
	v_mfma_f32_16x16x32_bf16 v[68:71], v[172:175], v[216:219], v[68:71]
	v_mfma_f32_16x16x32_bf16 v[64:67], v[180:183], v[216:219], v[64:67]
	s_setprio 0
	s_barrier
; #define PG8_STAGE(bufoff, gbase, voff) do { _Pragma("unroll") for (int _i = 0; _i < 2; ++_i) \
;         __builtin_amdgcn_global_load_lds((const unsigned*)((const char*)(gbase) + (voff)[_i]), (LAS unsigned*)(lds + (bufoff) + ldsw + _i * 8192), 16, 0, 0); } while (0)
; #define PG8_LDA(dst, b, h) do { _Pragma("unroll") for (int m = 0; m < 4; ++m) _Pragma("unroll") for (int k = 0; k < 2; ++k) dst[m][k] = *(const LAS bf16x8*)(lds + PG8_SA(b, h) + aoff + m * 2048 + k * 1024); } while (0)
; #define PG8_WAIT_V(n) asm volatile("s_waitcnt vmcnt(" #n ")" ::: "memory")
; #define PG8_WAIT_L(n) asm volatile("s_waitcnt lgkmcnt(" #n ")" ::: "memory")
; #define PG8_BAR __builtin_amdgcn_s_barrier()
; #define PG8_SCHED __builtin_amdgcn_sched_barrier(0)
; template <class Epi, class Sched, bool SWAPD = false>
; __device__ __forceinline__ void gemm_phase(LAS unsigned char* lds, const Gemm g, const Sched& S, const Epi& E) {
;     ...
;             PG8_LDA(At, 1, 1); PG8_STAGE(PG8_SB(1, 0), b3, voffB); PG8_STAGE(PG8_SB(1, 1), b3 + hstepB, voffB); PG8_STAGE(PG8_SA(1, 0), a3, voffA);
;             PG8_WAIT_V(8); PG8_WAIT_L(0); PG8_BAR; PG8_MMA(1, 0, At, B0); PG8_MMA(1, 1, At, B1); PG8_BAR; PG8_SCHED;
;         }
;         if (wr == 0) PG8_BAR;
	s_add_i32 s42, s63, s21
	v_lshl_add_u64 v[204:205], v[204:205], 0, s[10:11]
	s_mov_b32 m0, s42
	ds_read_b128 v[184:187], v155 offset:49152
	ds_read_b128 v[188:191], v155 offset:50176
	ds_read_b128 v[192:195], v155 offset:51200
	ds_read_b128 v[196:199], v155 offset:52224
	ds_read_b128 v[200:203], v155 offset:53248
	ds_read_b128 v[208:211], v155 offset:54272
	ds_read_b128 v[212:215], v155 offset:55296
	ds_read_b128 v[216:219], v155 offset:56320
	global_load_lds_dwordx4 v[204:205], off
	s_add_i32 m0, s42, 0x2000
	s_add_u32 s42, s50, 0x20080
	v_lshl_add_u64 v[204:205], v[220:221], 0, s[10:11]
	s_addc_u32 s43, s51, 0
	s_add_i32 s50, s64, s21
	global_load_lds_dwordx4 v[204:205], off
	v_lshl_add_u64 v[204:205], s[42:43], 0, v[130:131]
	s_mov_b32 m0, s50
	s_nop 0
	global_load_lds_dwordx4 v[204:205], off
	v_lshl_add_u64 v[204:205], s[42:43], 0, v[134:135]
	s_add_i32 m0, s50, 0x2000
	s_nop 0
	global_load_lds_dwordx4 v[204:205], off
	v_lshl_add_u64 v[204:205], s[46:47], 0, v[128:129]
	s_mov_b32 m0, s55
	s_nop 0
	global_load_lds_dwordx4 v[204:205], off
	v_lshl_add_u64 v[204:205], s[46:47], 0, v[132:133]
	s_mov_b32 m0, s56
	s_nop 0
	global_load_lds_dwordx4 v[204:205], off
	s_waitcnt vmcnt(8) lgkmcnt(0)
	s_barrier
	s_setprio 1
	v_mfma_f32_16x16x32_bf16 v[60:63], v[146:149], v[184:187], v[60:63]
	v_mfma_f32_16x16x32_bf16 v[56:59], v[160:163], v[184:187], v[56:59]
	v_mfma_f32_16x16x32_bf16 v[44:47], v[146:149], v[192:195], v[44:47]
	v_mfma_f32_16x16x32_bf16 v[40:43], v[160:163], v[192:195], v[40:43]
	v_mfma_f32_16x16x32_bf16 v[28:31], v[146:149], v[200:203], v[28:31]
	v_mfma_f32_16x16x32_bf16 v[24:27], v[160:163], v[200:203], v[24:27]
	v_mfma_f32_16x16x32_bf16 v[12:15], v[146:149], v[212:215], v[12:15]
	v_mfma_f32_16x16x32_bf16 v[8:11], v[160:163], v[212:215], v[8:11]
	v_mfma_f32_16x16x32_bf16 v[60:63], v[156:159], v[188:191], v[60:63]
	v_mfma_f32_16x16x32_bf16 v[56:59], v[164:167], v[188:191], v[56:59]
	v_mfma_f32_16x16x32_bf16 v[44:47], v[156:159], v[196:199], v[44:47]
	v_mfma_f32_16x16x32_bf16 v[40:43], v[164:167], v[196:199], v[40:43]
	v_mfma_f32_16x16x32_bf16 v[28:31], v[156:159], v[208:211], v[28:31]
	v_mfma_f32_16x16x32_bf16 v[24:27], v[164:167], v[208:211], v[24:27]
	v_mfma_f32_16x16x32_bf16 v[12:15], v[156:159], v[216:219], v[12:15]
	v_mfma_f32_16x16x32_bf16 v[8:11], v[164:167], v[216:219], v[8:11]
	s_setprio 0
	s_setprio 1
	v_mfma_f32_16x16x32_bf16 v[52:55], v[168:171], v[184:187], v[52:55]
	v_mfma_f32_16x16x32_bf16 v[48:51], v[176:179], v[184:187], v[48:51]
	v_mfma_f32_16x16x32_bf16 v[36:39], v[168:171], v[192:195], v[36:39]
	v_mfma_f32_16x16x32_bf16 v[32:35], v[176:179], v[192:195], v[32:35]
	v_mfma_f32_16x16x32_bf16 v[20:23], v[168:171], v[200:203], v[20:23]
	v_mfma_f32_16x16x32_bf16 v[16:19], v[176:179], v[200:203], v[16:19]
	v_mfma_f32_16x16x32_bf16 v[4:7], v[168:171], v[212:215], v[4:7]
	v_mfma_f32_16x16x32_bf16 v[0:3], v[176:179], v[212:215], v[0:3]
	v_mfma_f32_16x16x32_bf16 v[52:55], v[172:175], v[188:191], v[52:55]
	v_mfma_f32_16x16x32_bf16 v[48:51], v[180:183], v[188:191], v[48:51]
	v_mfma_f32_16x16x32_bf16 v[36:39], v[172:175], v[196:199], v[36:39]
	v_mfma_f32_16x16x32_bf16 v[32:35], v[180:183], v[196:199], v[32:35]
	v_mfma_f32_16x16x32_bf16 v[20:23], v[172:175], v[208:211], v[20:23]
	v_mfma_f32_16x16x32_bf16 v[16:19], v[180:183], v[208:211], v[16:19]
	v_mfma_f32_16x16x32_bf16 v[4:7], v[172:175], v[216:219], v[4:7]
	v_mfma_f32_16x16x32_bf16 v[0:3], v[180:183], v[216:219], v[0:3]
	s_setprio 0
	s_barrier
	s_add_i32 s62, s62, 2
	s_add_u32 s60, s60, 0x100
	s_addc_u32 s61, s61, 0
	s_cmp_gt_u32 s62, 5
	s_mov_b64 s[42:43], s[44:45]
	s_cbranch_scc0 .LBB0_842
	s_and_b64 vcc, exec, s[12:13]
	s_cbranch_vccz .LBB0_845
	s_barrier

; #define PG8_STAGE(bufoff, gbase, voff) do { _Pragma("unroll") for (int _i = 0; _i < 2; ++_i) \
;         __builtin_amdgcn_global_load_lds((const unsigned*)((const char*)(gbase) + (voff)[_i]), (LAS unsigned*)(lds + (bufoff) + ldsw + _i * 8192), 16, 0, 0); } while (0)
; #define PG8_LDA(dst, b, h) do { _Pragma("unroll") for (int m = 0; m < 4; ++m) _Pragma("unroll") for (int k = 0; k < 2; ++k) dst[m][k] = *(const LAS bf16x8*)(lds + PG8_SA(b, h) + aoff + m * 2048 + k * 1024); } while (0)
; #define PG8_LDB(dst, b, h) do { _Pragma("unroll") for (int n = 0; n < 2; ++n) _Pragma("unroll") for (int k = 0; k < 2; ++k) dst[n][k] = *(const LAS bf16x8*)(lds + PG8_SB(b, h) + boff + n * 2048 + k * 1024); } while (0)
; #define PG8_WAIT_V(n) asm volatile("s_waitcnt vmcnt(" #n ")" ::: "memory")
; #define PG8_WAIT_L(n) asm volatile("s_waitcnt lgkmcnt(" #n ")" ::: "memory")
; #define PG8_BAR __builtin_amdgcn_s_barrier()
; #define PG8_SCHED __builtin_amdgcn_sched_barrier(0)
; template <class Epi, class Sched, bool SWAPD = false>
; __device__ __forceinline__ void gemm_phase(LAS unsigned char* lds, const Gemm g, const Sched& S, const Epi& E) {
;     ...
;             const bool last = (t == nt - 2);
;             const char* a1 = cA + (size_t)(t + 1) * kstepA;
;             const char* a2 = last ? nA : cA + (size_t)(t + 2) * kstepA; const char* b2 = last ? nB : cB + (size_t)(t + 2) * kstep;
;             const char* a3 = a2 + kstepA; const char* b3 = b2 + kstep;
;             PG8_LDB(B0, 0, 0); PG8_LDB(B1, 0, 1); PG8_SCHED; PG8_LDA(At, 0, 0); PG8_STAGE(PG8_SA(1, 1), a1 + hstepA, voffA);
;             PG8_WAIT_V(8); PG8_WAIT_L(0); PG8_BAR; PG8_MMA(0, 0, At, B0); PG8_MMA(0, 1, At, B1); PG8_BAR; PG8_SCHED;
;             PG8_LDA(At, 0, 1); PG8_STAGE(PG8_SB(0, 0), b2, voffB); PG8_STAGE(PG8_SB(0, 1), b2 + hstepB, voffB); PG8_STAGE(PG8_SA(0, 0), a2, voffA);
;             PG8_WAIT_V(8); PG8_WAIT_L(0); PG8_BAR; PG8_MMA(1, 0, At, B0); PG8_MMA(1, 1, At, B1); PG8_BAR; PG8_SCHED;
.LBB0_918:
	ds_read_b128 v[128:131], v200
	ds_read_b128 v[132:135], v200 offset:1024
	ds_read_b128 v[136:139], v200 offset:2048
	ds_read_b128 v[140:143], v200 offset:3072
	ds_read_b128 v[144:147], v201
	ds_read_b128 v[148:151], v201 offset:1024
	ds_read_b128 v[152:155], v201 offset:2048
	ds_read_b128 v[156:159], v201 offset:3072
	s_add_u32 s44, s42, 0xfffc0080
	s_addc_u32 s45, s43, -1
	s_cmp_eq_u32 s60, 12
	s_cselect_b32 s47, s23, s45
	s_cselect_b32 s46, s25, s44
	s_cselect_b32 s45, s35, s59
	s_cselect_b32 s44, s41, s58
	v_lshl_add_u64 v[196:197], s[42:43], 0, v[180:181]
	s_add_i32 m0, s30, 0xc000
	ds_read_b128 v[188:191], v202
	ds_read_b128 v[192:195], v202 offset:1024
	ds_read_b128 v[208:211], v202 offset:2048
	ds_read_b128 v[212:215], v202 offset:3072
	ds_read_b128 v[216:219], v202 offset:4096
	ds_read_b128 v[220:223], v202 offset:5120
	ds_read_b128 v[224:227], v202 offset:6144
	ds_read_b128 v[228:231], v202 offset:7168
	global_load_lds_dwordx4 v[196:197], off
	v_lshl_add_u64 v[196:197], s[42:43], 0, v[182:183]
	s_add_i32 m0, s30, 0xe000
	s_nop 0
	global_load_lds_dwordx4 v[196:197], off
	s_waitcnt vmcnt(8) lgkmcnt(0)
	s_barrier
	s_setprio 1
	v_mfma_f32_16x16x32_bf16 v[124:127], v[128:131], v[188:191], v[124:127]
	v_mfma_f32_16x16x32_bf16 v[120:123], v[136:139], v[188:191], v[120:123]
	v_mfma_f32_16x16x32_bf16 v[116:119], v[128:131], v[208:211], v[116:119]
	v_mfma_f32_16x16x32_bf16 v[112:115], v[136:139], v[208:211], v[112:115]
	v_mfma_f32_16x16x32_bf16 v[92:95], v[128:131], v[216:219], v[92:95]
	v_mfma_f32_16x16x32_bf16 v[88:91], v[136:139], v[216:219], v[88:91]
	v_mfma_f32_16x16x32_bf16 v[76:79], v[128:131], v[224:227], v[76:79]
	v_mfma_f32_16x16x32_bf16 v[72:75], v[136:139], v[224:227], v[72:75]
	v_mfma_f32_16x16x32_bf16 v[124:127], v[132:135], v[192:195], v[124:127]
	v_mfma_f32_16x16x32_bf16 v[120:123], v[140:143], v[192:195], v[120:123]
	v_mfma_f32_16x16x32_bf16 v[116:119], v[132:135], v[212:215], v[116:119]
	v_mfma_f32_16x16x32_bf16 v[112:115], v[140:143], v[212:215], v[112:115]
	v_mfma_f32_16x16x32_bf16 v[92:95], v[132:135], v[220:223], v[92:95]
	v_mfma_f32_16x16x32_bf16 v[88:91], v[140:143], v[220:223], v[88:91]
	v_mfma_f32_16x16x32_bf16 v[76:79], v[132:135], v[228:231], v[76:79]
	v_mfma_f32_16x16x32_bf16 v[72:75], v[140:143], v[228:231], v[72:75]
	s_setprio 0
	s_setprio 1
	v_mfma_f32_16x16x32_bf16 v[108:111], v[144:147], v[188:191], v[108:111]
	v_mfma_f32_16x16x32_bf16 v[104:107], v[152:155], v[188:191], v[104:107]
	v_mfma_f32_16x16x32_bf16 v[100:103], v[144:147], v[208:211], v[100:103]
	v_mfma_f32_16x16x32_bf16 v[96:99], v[152:155], v[208:211], v[96:99]
	v_mfma_f32_16x16x32_bf16 v[84:87], v[144:147], v[216:219], v[84:87]
	v_mfma_f32_16x16x32_bf16 v[80:83], v[152:155], v[216:219], v[80:83]
	v_mfma_f32_16x16x32_bf16 v[68:71], v[144:147], v[224:227], v[68:71]
	v_mfma_f32_16x16x32_bf16 v[64:67], v[152:155], v[224:227], v[64:67]
	v_mfma_f32_16x16x32_bf16 v[108:111], v[148:151], v[192:195], v[108:111]
	v_mfma_f32_16x16x32_bf16 v[104:107], v[156:159], v[192:195], v[104:107]
	v_mfma_f32_16x16x32_bf16 v[100:103], v[148:151], v[212:215], v[100:103]
	v_mfma_f32_16x16x32_bf16 v[96:99], v[156:159], v[212:215], v[96:99]
	v_mfma_f32_16x16x32_bf16 v[84:87], v[148:151], v[220:223], v[84:87]
	v_mfma_f32_16x16x32_bf16 v[80:83], v[156:159], v[220:223], v[80:83]
	v_mfma_f32_16x16x32_bf16 v[68:71], v[148:151], v[228:231], v[68:71]
	v_mfma_f32_16x16x32_bf16 v[64:67], v[156:159], v[228:231], v[64:67]
	s_setprio 0
	s_barrier
	s_add_i32 s61, s56, s21
	v_lshl_add_u64 v[196:197], s[44:45], 0, v[160:161]
	s_mov_b32 m0, s61
	ds_read_b128 v[188:191], v202 offset:16384
	ds_read_b128 v[192:195], v202 offset:17408
	ds_read_b128 v[208:211], v202 offset:18432
	ds_read_b128 v[212:215], v202 offset:19456
	ds_read_b128 v[216:219], v202 offset:20480
	ds_read_b128 v[220:223], v202 offset:21504
	ds_read_b128 v[224:227], v202 offset:22528
	ds_read_b128 v[228:231], v202 offset:23552
	global_load_lds_dwordx4 v[196:197], off
	s_add_i32 m0, s61, 0x2000
	s_add_u32 s62, s44, 0x40000
	v_lshl_add_u64 v[204:205], s[44:45], 0, v[162:163]
	s_addc_u32 s63, s45, 0
	s_add_i32 s61, s57, s21
	global_load_lds_dwordx4 v[204:205], off
	v_lshl_add_u64 v[232:233], s[62:63], 0, v[160:161]
	s_mov_b32 m0, s61
	v_lshl_add_u64 v[234:235], s[46:47], 0, v[162:163]
	global_load_lds_dwordx4 v[232:233], off
	v_lshl_add_u64 v[232:233], s[62:63], 0, v[162:163]
	s_add_i32 m0, s61, 0x2000
	s_nop 0
	global_load_lds_dwordx4 v[232:233], off
	v_lshl_add_u64 v[232:233], s[46:47], 0, v[160:161]
	s_mov_b32 m0, s30
	s_nop 0
	global_load_lds_dwordx4 v[232:233], off
	s_mov_b32 m0, s31
	s_nop 0
	global_load_lds_dwordx4 v[234:235], off
	s_waitcnt vmcnt(8) lgkmcnt(0)
	s_barrier
; #define PG8_STAGE(bufoff, gbase, voff) do { _Pragma("unroll") for (int _i = 0; _i < 2; ++_i) \
;         __builtin_amdgcn_global_load_lds((const unsigned*)((const char*)(gbase) + (voff)[_i]), (LAS unsigned*)(lds + (bufoff) + ldsw + _i * 8192), 16, 0, 0); } while (0)
; #define PG8_LDA(dst, b, h) do { _Pragma("unroll") for (int m = 0; m < 4; ++m) _Pragma("unroll") for (int k = 0; k < 2; ++k) dst[m][k] = *(const LAS bf16x8*)(lds + PG8_SA(b, h) + aoff + m * 2048 + k * 1024); } while (0)
; #define PG8_LDB(dst, b, h) do { _Pragma("unroll") for (int n = 0; n < 2; ++n) _Pragma("unroll") for (int k = 0; k < 2; ++k) dst[n][k] = *(const LAS bf16x8*)(lds + PG8_SB(b, h) + boff + n * 2048 + k * 1024); } while (0)
; #define PG8_WAIT_V(n) asm volatile("s_waitcnt vmcnt(" #n ")" ::: "memory")
; #define PG8_WAIT_L(n) asm volatile("s_waitcnt lgkmcnt(" #n ")" ::: "memory")
; #define PG8_BAR __builtin_amdgcn_s_barrier()
; #define PG8_SCHED __builtin_amdgcn_sched_barrier(0)
; template <class Epi, class Sched, bool SWAPD = false>
; __device__ __forceinline__ void gemm_phase(LAS unsigned char* lds, const Gemm g, const Sched& S, const Epi& E) {
;     ...
;             PG8_WAIT_V(8); PG8_WAIT_L(0); PG8_BAR; PG8_MMA(1, 0, At, B0); PG8_MMA(1, 1, At, B1); PG8_BAR; PG8_SCHED;
;             PG8_LDB(B0, 1, 0); PG8_LDB(B1, 1, 1); PG8_SCHED; PG8_LDA(At, 1, 0); PG8_STAGE(PG8_SA(0, 1), a2 + hstepA, voffA);
;             PG8_WAIT_V(8); PG8_WAIT_L(0); PG8_BAR; PG8_MMA(0, 0, At, B0); PG8_MMA(0, 1, At, B1); PG8_BAR; PG8_SCHED;
	s_setprio 1
	v_mfma_f32_16x16x32_bf16 v[60:63], v[128:131], v[188:191], v[60:63]
	v_mfma_f32_16x16x32_bf16 v[56:59], v[136:139], v[188:191], v[56:59]
	v_mfma_f32_16x16x32_bf16 v[44:47], v[128:131], v[208:211], v[44:47]
	v_mfma_f32_16x16x32_bf16 v[40:43], v[136:139], v[208:211], v[40:43]
	v_mfma_f32_16x16x32_bf16 v[36:39], v[128:131], v[216:219], v[36:39]
	v_mfma_f32_16x16x32_bf16 v[32:35], v[136:139], v[216:219], v[32:35]
	v_mfma_f32_16x16x32_bf16 v[20:23], v[128:131], v[224:227], v[20:23]
	v_mfma_f32_16x16x32_bf16 v[16:19], v[136:139], v[224:227], v[16:19]
	v_mfma_f32_16x16x32_bf16 v[60:63], v[132:135], v[192:195], v[60:63]
	v_mfma_f32_16x16x32_bf16 v[56:59], v[140:143], v[192:195], v[56:59]
	v_mfma_f32_16x16x32_bf16 v[44:47], v[132:135], v[212:215], v[44:47]
	v_mfma_f32_16x16x32_bf16 v[40:43], v[140:143], v[212:215], v[40:43]
	v_mfma_f32_16x16x32_bf16 v[36:39], v[132:135], v[220:223], v[36:39]
	v_mfma_f32_16x16x32_bf16 v[32:35], v[140:143], v[220:223], v[32:35]
	v_mfma_f32_16x16x32_bf16 v[20:23], v[132:135], v[228:231], v[20:23]
	v_mfma_f32_16x16x32_bf16 v[16:19], v[140:143], v[228:231], v[16:19]
	s_setprio 0
	s_setprio 1
	v_mfma_f32_16x16x32_bf16 v[52:55], v[144:147], v[188:191], v[52:55]
	v_mfma_f32_16x16x32_bf16 v[48:51], v[152:155], v[188:191], v[48:51]
	v_mfma_f32_16x16x32_bf16 v[28:31], v[144:147], v[208:211], v[28:31]
	v_mfma_f32_16x16x32_bf16 v[24:27], v[152:155], v[208:211], v[24:27]
	v_mfma_f32_16x16x32_bf16 v[12:15], v[144:147], v[216:219], v[12:15]
	v_mfma_f32_16x16x32_bf16 v[8:11], v[152:155], v[216:219], v[8:11]
	v_mfma_f32_16x16x32_bf16 v[4:7], v[144:147], v[224:227], v[4:7]
	v_mfma_f32_16x16x32_bf16 v[0:3], v[152:155], v[224:227], v[0:3]
	v_mfma_f32_16x16x32_bf16 v[52:55], v[148:151], v[192:195], v[52:55]
	v_mfma_f32_16x16x32_bf16 v[48:51], v[156:159], v[192:195], v[48:51]
	v_mfma_f32_16x16x32_bf16 v[28:31], v[148:151], v[212:215], v[28:31]
	v_mfma_f32_16x16x32_bf16 v[24:27], v[156:159], v[212:215], v[24:27]
	v_mfma_f32_16x16x32_bf16 v[12:15], v[148:151], v[220:223], v[12:15]
	v_mfma_f32_16x16x32_bf16 v[8:11], v[156:159], v[220:223], v[8:11]
	v_mfma_f32_16x16x32_bf16 v[4:7], v[148:151], v[228:231], v[4:7]
	v_mfma_f32_16x16x32_bf16 v[0:3], v[156:159], v[228:231], v[0:3]
	s_setprio 0
	s_barrier
	s_add_i32 s61, 0, 0x18000
	s_add_i32 s62, 0, 0x1c000
	v_add_u32_e32 v140, s61, v198
	v_add_u32_e32 v156, s62, v198
	ds_read_b128 v[128:131], v140
	ds_read_b128 v[132:135], v140 offset:1024
	ds_read_b128 v[136:139], v140 offset:2048
	ds_read_b128 v[140:143], v140 offset:3072
	ds_read_b128 v[144:147], v156
	ds_read_b128 v[148:151], v156 offset:1024
	ds_read_b128 v[152:155], v156 offset:2048
	ds_read_b128 v[156:159], v156 offset:3072
	s_add_u32 s46, s46, 0x40000
	s_addc_u32 s47, s47, 0
	s_mov_b32 m0, s33
	v_lshl_add_u64 v[236:237], s[46:47], 0, v[160:161]
	ds_read_b128 v[188:191], v202 offset:32768
	ds_read_b128 v[192:195], v202 offset:33792
	ds_read_b128 v[208:211], v202 offset:34816
	ds_read_b128 v[212:215], v202 offset:35840
	ds_read_b128 v[216:219], v202 offset:36864
	ds_read_b128 v[220:223], v202 offset:37888
	ds_read_b128 v[224:227], v202 offset:38912
	ds_read_b128 v[228:231], v202 offset:39936
	global_load_lds_dwordx4 v[236:237], off
	v_lshl_add_u64 v[236:237], s[46:47], 0, v[162:163]
	s_mov_b32 m0, s50
	s_nop 0
	global_load_lds_dwordx4 v[236:237], off
	s_waitcnt vmcnt(8) lgkmcnt(0)
	s_barrier
	s_setprio 1
	v_mfma_f32_16x16x32_bf16 v[124:127], v[128:131], v[188:191], v[124:127]
	v_mfma_f32_16x16x32_bf16 v[120:123], v[136:139], v[188:191], v[120:123]
	v_mfma_f32_16x16x32_bf16 v[116:119], v[128:131], v[208:211], v[116:119]
	v_mfma_f32_16x16x32_bf16 v[112:115], v[136:139], v[208:211], v[112:115]
	v_mfma_f32_16x16x32_bf16 v[92:95], v[128:131], v[216:219], v[92:95]
	v_mfma_f32_16x16x32_bf16 v[88:91], v[136:139], v[216:219], v[88:91]
	v_mfma_f32_16x16x32_bf16 v[76:79], v[128:131], v[224:227], v[76:79]
	v_mfma_f32_16x16x32_bf16 v[72:75], v[136:139], v[224:227], v[72:75]
	v_mfma_f32_16x16x32_bf16 v[124:127], v[132:135], v[192:195], v[124:127]
	v_mfma_f32_16x16x32_bf16 v[120:123], v[140:143], v[192:195], v[120:123]
	v_mfma_f32_16x16x32_bf16 v[116:119], v[132:135], v[212:215], v[116:119]
	v_mfma_f32_16x16x32_bf16 v[112:115], v[140:143], v[212:215], v[112:115]
	v_mfma_f32_16x16x32_bf16 v[92:95], v[132:135], v[220:223], v[92:95]
	v_mfma_f32_16x16x32_bf16 v[88:91], v[140:143], v[220:223], v[88:91]
	v_mfma_f32_16x16x32_bf16 v[76:79], v[132:135], v[228:231], v[76:79]
	v_mfma_f32_16x16x32_bf16 v[72:75], v[140:143], v[228:231], v[72:75]
	s_setprio 0
	s_setprio 1
	v_mfma_f32_16x16x32_bf16 v[108:111], v[144:147], v[188:191], v[108:111]
	v_mfma_f32_16x16x32_bf16 v[104:107], v[152:155], v[188:191], v[104:107]
	v_mfma_f32_16x16x32_bf16 v[100:103], v[144:147], v[208:211], v[100:103]
	v_mfma_f32_16x16x32_bf16 v[96:99], v[152:155], v[208:211], v[96:99]
	v_mfma_f32_16x16x32_bf16 v[84:87], v[144:147], v[216:219], v[84:87]
	v_mfma_f32_16x16x32_bf16 v[80:83], v[152:155], v[216:219], v[80:83]
	v_mfma_f32_16x16x32_bf16 v[68:71], v[144:147], v[224:227], v[68:71]
	v_mfma_f32_16x16x32_bf16 v[64:67], v[152:155], v[224:227], v[64:67]
	v_mfma_f32_16x16x32_bf16 v[108:111], v[148:151], v[192:195], v[108:111]
	v_mfma_f32_16x16x32_bf16 v[104:107], v[156:159], v[192:195], v[104:107]
	v_mfma_f32_16x16x32_bf16 v[100:103], v[148:151], v[212:215], v[100:103]
	v_mfma_f32_16x16x32_bf16 v[96:99], v[156:159], v[212:215], v[96:99]
	v_mfma_f32_16x16x32_bf16 v[84:87], v[148:151], v[220:223], v[84:87]
	v_mfma_f32_16x16x32_bf16 v[80:83], v[156:159], v[220:223], v[80:83]
	v_mfma_f32_16x16x32_bf16 v[68:71], v[148:151], v[228:231], v[68:71]
	v_mfma_f32_16x16x32_bf16 v[64:67], v[156:159], v[228:231], v[64:67]
	s_setprio 0
	s_barrier
; #define PG8_STAGE(bufoff, gbase, voff) do { _Pragma("unroll") for (int _i = 0; _i < 2; ++_i) \
;         __builtin_amdgcn_global_load_lds((const unsigned*)((const char*)(gbase) + (voff)[_i]), (LAS unsigned*)(lds + (bufoff) + ldsw + _i * 8192), 16, 0, 0); } while (0)
; #define PG8_LDA(dst, b, h) do { _Pragma("unroll") for (int m = 0; m < 4; ++m) _Pragma("unroll") for (int k = 0; k < 2; ++k) dst[m][k] = *(const LAS bf16x8*)(lds + PG8_SA(b, h) + aoff + m * 2048 + k * 1024); } while (0)
; #define PG8_WAIT_V(n) asm volatile("s_waitcnt vmcnt(" #n ")" ::: "memory")
; #define PG8_WAIT_L(n) asm volatile("s_waitcnt lgkmcnt(" #n ")" ::: "memory")
; #define PG8_BAR __builtin_amdgcn_s_barrier()
; #define PG8_SCHED __builtin_amdgcn_sched_barrier(0)
; template <class Epi, class Sched, bool SWAPD = false>
; __device__ __forceinline__ void gemm_phase(LAS unsigned char* lds, const Gemm g, const Sched& S, const Epi& E) {
;     ...
;             PG8_LDA(At, 1, 1); PG8_STAGE(PG8_SB(1, 0), b3, voffB); PG8_STAGE(PG8_SB(1, 1), b3 + hstepB, voffB); PG8_STAGE(PG8_SA(1, 0), a3, voffA);
;             PG8_WAIT_V(8); PG8_WAIT_L(0); PG8_BAR; PG8_MMA(1, 0, At, B0); PG8_MMA(1, 1, At, B1); PG8_BAR; PG8_SCHED;
;         }
;         if (wr == 0) PG8_BAR;
	s_add_i32 s46, s61, s21
	v_lshl_add_u64 v[196:197], v[196:197], 0, s[10:11]
	s_mov_b32 m0, s46
	ds_read_b128 v[188:191], v202 offset:49152
	ds_read_b128 v[192:195], v202 offset:50176
	ds_read_b128 v[208:211], v202 offset:51200
	ds_read_b128 v[212:215], v202 offset:52224
	ds_read_b128 v[216:219], v202 offset:53248
	ds_read_b128 v[220:223], v202 offset:54272
	ds_read_b128 v[224:227], v202 offset:55296
	ds_read_b128 v[228:231], v202 offset:56320
	global_load_lds_dwordx4 v[196:197], off
	s_add_i32 m0, s46, 0x2000
	s_add_u32 s44, s44, 0x40080
	v_lshl_add_u64 v[196:197], v[204:205], 0, s[10:11]
	s_addc_u32 s45, s45, 0
	s_add_i32 s46, s62, s21
	global_load_lds_dwordx4 v[196:197], off
	v_lshl_add_u64 v[196:197], s[44:45], 0, v[160:161]
	s_mov_b32 m0, s46
	s_nop 0
	global_load_lds_dwordx4 v[196:197], off
	v_lshl_add_u64 v[196:197], s[44:45], 0, v[162:163]
	s_add_i32 m0, s46, 0x2000
	s_nop 0
	global_load_lds_dwordx4 v[196:197], off
	v_lshl_add_u64 v[196:197], v[232:233], 0, s[10:11]
	s_mov_b32 m0, s54
	s_nop 0
	global_load_lds_dwordx4 v[196:197], off
	v_lshl_add_u64 v[196:197], v[234:235], 0, s[10:11]
	s_mov_b32 m0, s55
	s_nop 0
	global_load_lds_dwordx4 v[196:197], off
	s_waitcnt vmcnt(8) lgkmcnt(0)
	s_barrier
	s_setprio 1
	v_mfma_f32_16x16x32_bf16 v[60:63], v[128:131], v[188:191], v[60:63]
	v_mfma_f32_16x16x32_bf16 v[56:59], v[136:139], v[188:191], v[56:59]
	v_mfma_f32_16x16x32_bf16 v[44:47], v[128:131], v[208:211], v[44:47]
	v_mfma_f32_16x16x32_bf16 v[40:43], v[136:139], v[208:211], v[40:43]
	v_mfma_f32_16x16x32_bf16 v[36:39], v[128:131], v[216:219], v[36:39]
	v_mfma_f32_16x16x32_bf16 v[32:35], v[136:139], v[216:219], v[32:35]
	v_mfma_f32_16x16x32_bf16 v[20:23], v[128:131], v[224:227], v[20:23]
	v_mfma_f32_16x16x32_bf16 v[16:19], v[136:139], v[224:227], v[16:19]
	v_mfma_f32_16x16x32_bf16 v[60:63], v[132:135], v[192:195], v[60:63]
	v_mfma_f32_16x16x32_bf16 v[56:59], v[140:143], v[192:195], v[56:59]
	v_mfma_f32_16x16x32_bf16 v[44:47], v[132:135], v[212:215], v[44:47]
	v_mfma_f32_16x16x32_bf16 v[40:43], v[140:143], v[212:215], v[40:43]
	v_mfma_f32_16x16x32_bf16 v[36:39], v[132:135], v[220:223], v[36:39]
	v_mfma_f32_16x16x32_bf16 v[32:35], v[140:143], v[220:223], v[32:35]
	v_mfma_f32_16x16x32_bf16 v[20:23], v[132:135], v[228:231], v[20:23]
	v_mfma_f32_16x16x32_bf16 v[16:19], v[140:143], v[228:231], v[16:19]
	s_setprio 0
	s_setprio 1
	v_mfma_f32_16x16x32_bf16 v[52:55], v[144:147], v[188:191], v[52:55]
	v_mfma_f32_16x16x32_bf16 v[48:51], v[152:155], v[188:191], v[48:51]
	v_mfma_f32_16x16x32_bf16 v[28:31], v[144:147], v[208:211], v[28:31]
	v_mfma_f32_16x16x32_bf16 v[24:27], v[152:155], v[208:211], v[24:27]
	v_mfma_f32_16x16x32_bf16 v[12:15], v[144:147], v[216:219], v[12:15]
	v_mfma_f32_16x16x32_bf16 v[8:11], v[152:155], v[216:219], v[8:11]
	v_mfma_f32_16x16x32_bf16 v[4:7], v[144:147], v[224:227], v[4:7]
	v_mfma_f32_16x16x32_bf16 v[0:3], v[152:155], v[224:227], v[0:3]
	v_mfma_f32_16x16x32_bf16 v[52:55], v[148:151], v[192:195], v[52:55]
	v_mfma_f32_16x16x32_bf16 v[48:51], v[156:159], v[192:195], v[48:51]
	v_mfma_f32_16x16x32_bf16 v[28:31], v[148:151], v[212:215], v[28:31]
	v_mfma_f32_16x16x32_bf16 v[24:27], v[156:159], v[212:215], v[24:27]
	v_mfma_f32_16x16x32_bf16 v[12:15], v[148:151], v[220:223], v[12:15]
	v_mfma_f32_16x16x32_bf16 v[8:11], v[156:159], v[220:223], v[8:11]
	v_mfma_f32_16x16x32_bf16 v[4:7], v[148:151], v[228:231], v[4:7]
	v_mfma_f32_16x16x32_bf16 v[0:3], v[156:159], v[228:231], v[0:3]
	s_setprio 0
	s_barrier
	s_add_i32 s60, s60, 2
	s_add_u32 s42, s42, 0x100
	s_addc_u32 s43, s43, 0
	s_add_u32 s58, s58, 0x100
	s_addc_u32 s59, s59, 0
	s_cmp_gt_u32 s60, 13
	s_cbranch_scc0 .LBB0_918
	s_and_b64 vcc, exec, s[12:13]
	s_cbranch_vccz .LBB0_921
	s_barrier

; #define PG8_STAGE(bufoff, gbase, voff) do { _Pragma("unroll") for (int _i = 0; _i < 2; ++_i) \
;         __builtin_amdgcn_global_load_lds((const unsigned*)((const char*)(gbase) + (voff)[_i]), (LAS unsigned*)(lds + (bufoff) + ldsw + _i * 8192), 16, 0, 0); } while (0)
; #define PG8_LDA(dst, b, h) do { _Pragma("unroll") for (int m = 0; m < 4; ++m) _Pragma("unroll") for (int k = 0; k < 2; ++k) dst[m][k] = *(const LAS bf16x8*)(lds + PG8_SA(b, h) + aoff + m * 2048 + k * 1024); } while (0)
; #define PG8_LDB(dst, b, h) do { _Pragma("unroll") for (int n = 0; n < 2; ++n) _Pragma("unroll") for (int k = 0; k < 2; ++k) dst[n][k] = *(const LAS bf16x8*)(lds + PG8_SB(b, h) + boff + n * 2048 + k * 1024); } while (0)
; #define PG8_WAIT_V(n) asm volatile("s_waitcnt vmcnt(" #n ")" ::: "memory")
; #define PG8_WAIT_L(n) asm volatile("s_waitcnt lgkmcnt(" #n ")" ::: "memory")
; #define PG8_BAR __builtin_amdgcn_s_barrier()
; #define PG8_SCHED __builtin_amdgcn_sched_barrier(0)
; template <class Epi, class Sched, bool SWAPD = false>
; __device__ __forceinline__ void gemm_phase(LAS unsigned char* lds, const Gemm g, const Sched& S, const Epi& E) {
;     ...
;             const bool last = (t == nt - 2);
;             const char* a1 = cA + (size_t)(t + 1) * kstepA;
;             const char* a2 = last ? nA : cA + (size_t)(t + 2) * kstepA; const char* b2 = last ? nB : cB + (size_t)(t + 2) * kstep;
;             const char* a3 = a2 + kstepA; const char* b3 = b2 + kstep;
;             PG8_LDB(B0, 0, 0); PG8_LDB(B1, 0, 1); PG8_SCHED; PG8_LDA(At, 0, 0); PG8_STAGE(PG8_SA(1, 1), a1 + hstepA, voffA);
;             PG8_WAIT_V(8); PG8_WAIT_L(0); PG8_BAR; PG8_MMA(0, 0, At, B0); PG8_MMA(0, 1, At, B1); PG8_BAR; PG8_SCHED;
;             PG8_LDA(At, 0, 1); PG8_STAGE(PG8_SB(0, 0), b2, voffB); PG8_STAGE(PG8_SB(0, 1), b2 + hstepB, voffB); PG8_STAGE(PG8_SA(0, 0), a2, voffA);
;             PG8_WAIT_V(8); PG8_WAIT_L(0); PG8_BAR; PG8_MMA(1, 0, At, B0); PG8_MMA(1, 1, At, B1); PG8_BAR; PG8_SCHED;
.LBB0_1044:
	ds_read_b128 v[148:151], v145
	ds_read_b128 v[152:155], v145 offset:1024
	ds_read_b128 v[156:159], v145 offset:2048
	ds_read_b128 v[160:163], v145 offset:3072
	ds_read_b128 v[164:167], v146
	ds_read_b128 v[168:171], v146 offset:1024
	ds_read_b128 v[172:175], v146 offset:2048
	ds_read_b128 v[176:179], v146 offset:3072
	s_add_u32 s44, s42, 0xfffc0080
	s_addc_u32 s45, s43, -1
	s_cmp_eq_u32 s63, 12
	s_cselect_b32 s47, s25, s45
	s_cselect_b32 s46, s27, s44
	s_cselect_b32 s45, s59, s62
	s_cselect_b32 s44, s60, s61
	v_lshl_add_u64 v[140:141], s[42:43], 0, v[132:133]
	s_add_i32 m0, s33, 0xc000
	ds_read_b128 v[180:183], v147
	ds_read_b128 v[184:187], v147 offset:1024
	ds_read_b128 v[188:191], v147 offset:2048
	ds_read_b128 v[192:195], v147 offset:3072
	ds_read_b128 v[196:199], v147 offset:4096
	ds_read_b128 v[200:203], v147 offset:5120
	ds_read_b128 v[208:211], v147 offset:6144
	ds_read_b128 v[212:215], v147 offset:7168
	global_load_lds_dwordx4 v[140:141], off
	v_lshl_add_u64 v[140:141], s[42:43], 0, v[134:135]
	s_add_i32 m0, s33, 0xe000
	s_nop 0
	global_load_lds_dwordx4 v[140:141], off
	s_waitcnt vmcnt(8) lgkmcnt(0)
	s_barrier
	s_setprio 1
	v_mfma_f32_16x16x32_bf16 v[124:127], v[148:151], v[180:183], v[124:127]
	v_mfma_f32_16x16x32_bf16 v[116:119], v[156:159], v[180:183], v[116:119]
	v_mfma_f32_16x16x32_bf16 v[108:111], v[148:151], v[188:191], v[108:111]
	v_mfma_f32_16x16x32_bf16 v[100:103], v[156:159], v[188:191], v[100:103]
	v_mfma_f32_16x16x32_bf16 v[92:95], v[148:151], v[196:199], v[92:95]
	v_mfma_f32_16x16x32_bf16 v[84:87], v[156:159], v[196:199], v[84:87]
	v_mfma_f32_16x16x32_bf16 v[76:79], v[148:151], v[208:211], v[76:79]
	v_mfma_f32_16x16x32_bf16 v[68:71], v[156:159], v[208:211], v[68:71]
	v_mfma_f32_16x16x32_bf16 v[124:127], v[152:155], v[184:187], v[124:127]
	v_mfma_f32_16x16x32_bf16 v[116:119], v[160:163], v[184:187], v[116:119]
	v_mfma_f32_16x16x32_bf16 v[108:111], v[152:155], v[192:195], v[108:111]
	v_mfma_f32_16x16x32_bf16 v[100:103], v[160:163], v[192:195], v[100:103]
	v_mfma_f32_16x16x32_bf16 v[92:95], v[152:155], v[200:203], v[92:95]
	v_mfma_f32_16x16x32_bf16 v[84:87], v[160:163], v[200:203], v[84:87]
	v_mfma_f32_16x16x32_bf16 v[76:79], v[152:155], v[212:215], v[76:79]
	v_mfma_f32_16x16x32_bf16 v[68:71], v[160:163], v[212:215], v[68:71]
	s_setprio 0
	s_setprio 1
	v_mfma_f32_16x16x32_bf16 v[120:123], v[164:167], v[180:183], v[120:123]
	v_mfma_f32_16x16x32_bf16 v[112:115], v[172:175], v[180:183], v[112:115]
	v_mfma_f32_16x16x32_bf16 v[104:107], v[164:167], v[188:191], v[104:107]
	v_mfma_f32_16x16x32_bf16 v[96:99], v[172:175], v[188:191], v[96:99]
	v_mfma_f32_16x16x32_bf16 v[88:91], v[164:167], v[196:199], v[88:91]
	v_mfma_f32_16x16x32_bf16 v[80:83], v[172:175], v[196:199], v[80:83]
	v_mfma_f32_16x16x32_bf16 v[72:75], v[164:167], v[208:211], v[72:75]
	v_mfma_f32_16x16x32_bf16 v[64:67], v[172:175], v[208:211], v[64:67]
	v_mfma_f32_16x16x32_bf16 v[120:123], v[168:171], v[184:187], v[120:123]
	v_mfma_f32_16x16x32_bf16 v[112:115], v[176:179], v[184:187], v[112:115]
	v_mfma_f32_16x16x32_bf16 v[104:107], v[168:171], v[192:195], v[104:107]
	v_mfma_f32_16x16x32_bf16 v[96:99], v[176:179], v[192:195], v[96:99]
	v_mfma_f32_16x16x32_bf16 v[88:91], v[168:171], v[200:203], v[88:91]
	v_mfma_f32_16x16x32_bf16 v[80:83], v[176:179], v[200:203], v[80:83]
	v_mfma_f32_16x16x32_bf16 v[72:75], v[168:171], v[212:215], v[72:75]
	v_mfma_f32_16x16x32_bf16 v[64:67], v[176:179], v[212:215], v[64:67]
	s_setprio 0
	s_barrier
	s_add_i32 s64, s55, s30
	v_lshl_add_u64 v[140:141], s[44:45], 0, v[130:131]
	s_mov_b32 m0, s64
	ds_read_b128 v[180:183], v147 offset:16384
	ds_read_b128 v[184:187], v147 offset:17408
	ds_read_b128 v[188:191], v147 offset:18432
	ds_read_b128 v[192:195], v147 offset:19456
	ds_read_b128 v[196:199], v147 offset:20480
	ds_read_b128 v[200:203], v147 offset:21504
	ds_read_b128 v[208:211], v147 offset:22528
	ds_read_b128 v[212:215], v147 offset:23552
	global_load_lds_dwordx4 v[140:141], off
	s_add_i32 m0, s64, 0x2000
	s_add_u32 s64, s44, 0x40000
	v_lshl_add_u64 v[204:205], s[44:45], 0, v[128:129]
	s_addc_u32 s65, s45, 0
	s_add_i32 s66, s56, s30
	global_load_lds_dwordx4 v[204:205], off
	v_lshl_add_u64 v[216:217], s[64:65], 0, v[130:131]
	s_mov_b32 m0, s66
	v_lshl_add_u64 v[218:219], s[46:47], 0, v[128:129]
	global_load_lds_dwordx4 v[216:217], off
	v_lshl_add_u64 v[216:217], s[64:65], 0, v[128:129]
	s_add_i32 m0, s66, 0x2000
	s_nop 0
	global_load_lds_dwordx4 v[216:217], off
	v_lshl_add_u64 v[216:217], s[46:47], 0, v[130:131]
	s_mov_b32 m0, s33
	s_nop 0
	global_load_lds_dwordx4 v[216:217], off
	s_mov_b32 m0, s41
	s_nop 0
	global_load_lds_dwordx4 v[218:219], off
	s_waitcnt vmcnt(8) lgkmcnt(0)
	s_barrier
; #define PG8_STAGE(bufoff, gbase, voff) do { _Pragma("unroll") for (int _i = 0; _i < 2; ++_i) \
;         __builtin_amdgcn_global_load_lds((const unsigned*)((const char*)(gbase) + (voff)[_i]), (LAS unsigned*)(lds + (bufoff) + ldsw + _i * 8192), 16, 0, 0); } while (0)
; #define PG8_LDA(dst, b, h) do { _Pragma("unroll") for (int m = 0; m < 4; ++m) _Pragma("unroll") for (int k = 0; k < 2; ++k) dst[m][k] = *(const LAS bf16x8*)(lds + PG8_SA(b, h) + aoff + m * 2048 + k * 1024); } while (0)
; #define PG8_LDB(dst, b, h) do { _Pragma("unroll") for (int n = 0; n < 2; ++n) _Pragma("unroll") for (int k = 0; k < 2; ++k) dst[n][k] = *(const LAS bf16x8*)(lds + PG8_SB(b, h) + boff + n * 2048 + k * 1024); } while (0)
; #define PG8_WAIT_V(n) asm volatile("s_waitcnt vmcnt(" #n ")" ::: "memory")
; #define PG8_WAIT_L(n) asm volatile("s_waitcnt lgkmcnt(" #n ")" ::: "memory")
; #define PG8_BAR __builtin_amdgcn_s_barrier()
; #define PG8_SCHED __builtin_amdgcn_sched_barrier(0)
; template <class Epi, class Sched, bool SWAPD = false>
; __device__ __forceinline__ void gemm_phase(LAS unsigned char* lds, const Gemm g, const Sched& S, const Epi& E) {
;     ...
;             PG8_WAIT_V(8); PG8_WAIT_L(0); PG8_BAR; PG8_MMA(1, 0, At, B0); PG8_MMA(1, 1, At, B1); PG8_BAR; PG8_SCHED;
;             PG8_LDB(B0, 1, 0); PG8_LDB(B1, 1, 1); PG8_SCHED; PG8_LDA(At, 1, 0); PG8_STAGE(PG8_SA(0, 1), a2 + hstepA, voffA);
;             PG8_WAIT_V(8); PG8_WAIT_L(0); PG8_BAR; PG8_MMA(0, 0, At, B0); PG8_MMA(0, 1, At, B1); PG8_BAR; PG8_SCHED;
	s_setprio 1
	v_mfma_f32_16x16x32_bf16 v[60:63], v[148:151], v[180:183], v[60:63]
	v_mfma_f32_16x16x32_bf16 v[52:55], v[156:159], v[180:183], v[52:55]
	v_mfma_f32_16x16x32_bf16 v[44:47], v[148:151], v[188:191], v[44:47]
	v_mfma_f32_16x16x32_bf16 v[36:39], v[156:159], v[188:191], v[36:39]
	v_mfma_f32_16x16x32_bf16 v[28:31], v[148:151], v[196:199], v[28:31]
	v_mfma_f32_16x16x32_bf16 v[20:23], v[156:159], v[196:199], v[20:23]
	v_mfma_f32_16x16x32_bf16 v[12:15], v[148:151], v[208:211], v[12:15]
	v_mfma_f32_16x16x32_bf16 v[4:7], v[156:159], v[208:211], v[4:7]
	v_mfma_f32_16x16x32_bf16 v[60:63], v[152:155], v[184:187], v[60:63]
	v_mfma_f32_16x16x32_bf16 v[52:55], v[160:163], v[184:187], v[52:55]
	v_mfma_f32_16x16x32_bf16 v[44:47], v[152:155], v[192:195], v[44:47]
	v_mfma_f32_16x16x32_bf16 v[36:39], v[160:163], v[192:195], v[36:39]
	v_mfma_f32_16x16x32_bf16 v[28:31], v[152:155], v[200:203], v[28:31]
	v_mfma_f32_16x16x32_bf16 v[20:23], v[160:163], v[200:203], v[20:23]
	v_mfma_f32_16x16x32_bf16 v[12:15], v[152:155], v[212:215], v[12:15]
	v_mfma_f32_16x16x32_bf16 v[4:7], v[160:163], v[212:215], v[4:7]
	s_setprio 0
	s_setprio 1
	v_mfma_f32_16x16x32_bf16 v[56:59], v[164:167], v[180:183], v[56:59]
	v_mfma_f32_16x16x32_bf16 v[48:51], v[172:175], v[180:183], v[48:51]
	v_mfma_f32_16x16x32_bf16 v[40:43], v[164:167], v[188:191], v[40:43]
	v_mfma_f32_16x16x32_bf16 v[32:35], v[172:175], v[188:191], v[32:35]
	v_mfma_f32_16x16x32_bf16 v[24:27], v[164:167], v[196:199], v[24:27]
	v_mfma_f32_16x16x32_bf16 v[16:19], v[172:175], v[196:199], v[16:19]
	v_mfma_f32_16x16x32_bf16 v[8:11], v[164:167], v[208:211], v[8:11]
	v_mfma_f32_16x16x32_bf16 v[0:3], v[172:175], v[208:211], v[0:3]
	v_mfma_f32_16x16x32_bf16 v[56:59], v[168:171], v[184:187], v[56:59]
	v_mfma_f32_16x16x32_bf16 v[48:51], v[176:179], v[184:187], v[48:51]
	v_mfma_f32_16x16x32_bf16 v[40:43], v[168:171], v[192:195], v[40:43]
	v_mfma_f32_16x16x32_bf16 v[32:35], v[176:179], v[192:195], v[32:35]
	v_mfma_f32_16x16x32_bf16 v[24:27], v[168:171], v[200:203], v[24:27]
	v_mfma_f32_16x16x32_bf16 v[16:19], v[176:179], v[200:203], v[16:19]
	v_mfma_f32_16x16x32_bf16 v[8:11], v[168:171], v[212:215], v[8:11]
	v_mfma_f32_16x16x32_bf16 v[0:3], v[176:179], v[212:215], v[0:3]
	s_setprio 0
	s_barrier
	s_add_i32 s64, 0, 0x18000
	s_add_i32 s65, 0, 0x1c000
	v_add_u32_e32 v160, s64, v143
	v_add_u32_e32 v176, s65, v143
	ds_read_b128 v[148:151], v160
	ds_read_b128 v[152:155], v160 offset:1024
	ds_read_b128 v[156:159], v160 offset:2048
	ds_read_b128 v[160:163], v160 offset:3072
	ds_read_b128 v[164:167], v176
	ds_read_b128 v[168:171], v176 offset:1024
	ds_read_b128 v[172:175], v176 offset:2048
	ds_read_b128 v[176:179], v176 offset:3072
	s_add_u32 s46, s46, 0x40000
	s_addc_u32 s47, s47, 0
	s_mov_b32 m0, s50
	v_lshl_add_u64 v[220:221], s[46:47], 0, v[130:131]
	ds_read_b128 v[180:183], v147 offset:32768
	ds_read_b128 v[184:187], v147 offset:33792
	ds_read_b128 v[188:191], v147 offset:34816
	ds_read_b128 v[192:195], v147 offset:35840
	ds_read_b128 v[196:199], v147 offset:36864
	ds_read_b128 v[200:203], v147 offset:37888
	ds_read_b128 v[208:211], v147 offset:38912
	ds_read_b128 v[212:215], v147 offset:39936
	global_load_lds_dwordx4 v[220:221], off
	v_lshl_add_u64 v[220:221], s[46:47], 0, v[128:129]
	s_mov_b32 m0, s51
	s_nop 0
	global_load_lds_dwordx4 v[220:221], off
	s_waitcnt vmcnt(8) lgkmcnt(0)
	s_barrier
	s_setprio 1
	v_mfma_f32_16x16x32_bf16 v[124:127], v[148:151], v[180:183], v[124:127]
	v_mfma_f32_16x16x32_bf16 v[116:119], v[156:159], v[180:183], v[116:119]
	v_mfma_f32_16x16x32_bf16 v[108:111], v[148:151], v[188:191], v[108:111]
	v_mfma_f32_16x16x32_bf16 v[100:103], v[156:159], v[188:191], v[100:103]
	v_mfma_f32_16x16x32_bf16 v[92:95], v[148:151], v[196:199], v[92:95]
	v_mfma_f32_16x16x32_bf16 v[84:87], v[156:159], v[196:199], v[84:87]
	v_mfma_f32_16x16x32_bf16 v[76:79], v[148:151], v[208:211], v[76:79]
	v_mfma_f32_16x16x32_bf16 v[68:71], v[156:159], v[208:211], v[68:71]
	v_mfma_f32_16x16x32_bf16 v[124:127], v[152:155], v[184:187], v[124:127]
	v_mfma_f32_16x16x32_bf16 v[116:119], v[160:163], v[184:187], v[116:119]
	v_mfma_f32_16x16x32_bf16 v[108:111], v[152:155], v[192:195], v[108:111]
	v_mfma_f32_16x16x32_bf16 v[100:103], v[160:163], v[192:195], v[100:103]
	v_mfma_f32_16x16x32_bf16 v[92:95], v[152:155], v[200:203], v[92:95]
	v_mfma_f32_16x16x32_bf16 v[84:87], v[160:163], v[200:203], v[84:87]
	v_mfma_f32_16x16x32_bf16 v[76:79], v[152:155], v[212:215], v[76:79]
	v_mfma_f32_16x16x32_bf16 v[68:71], v[160:163], v[212:215], v[68:71]
	s_setprio 0
	s_setprio 1
	v_mfma_f32_16x16x32_bf16 v[120:123], v[164:167], v[180:183], v[120:123]
	v_mfma_f32_16x16x32_bf16 v[112:115], v[172:175], v[180:183], v[112:115]
	v_mfma_f32_16x16x32_bf16 v[104:107], v[164:167], v[188:191], v[104:107]
	v_mfma_f32_16x16x32_bf16 v[96:99], v[172:175], v[188:191], v[96:99]
	v_mfma_f32_16x16x32_bf16 v[88:91], v[164:167], v[196:199], v[88:91]
	v_mfma_f32_16x16x32_bf16 v[80:83], v[172:175], v[196:199], v[80:83]
	v_mfma_f32_16x16x32_bf16 v[72:75], v[164:167], v[208:211], v[72:75]
	v_mfma_f32_16x16x32_bf16 v[64:67], v[172:175], v[208:211], v[64:67]
	v_mfma_f32_16x16x32_bf16 v[120:123], v[168:171], v[184:187], v[120:123]
	v_mfma_f32_16x16x32_bf16 v[112:115], v[176:179], v[184:187], v[112:115]
	v_mfma_f32_16x16x32_bf16 v[104:107], v[168:171], v[192:195], v[104:107]
	v_mfma_f32_16x16x32_bf16 v[96:99], v[176:179], v[192:195], v[96:99]
	v_mfma_f32_16x16x32_bf16 v[88:91], v[168:171], v[200:203], v[88:91]
	v_mfma_f32_16x16x32_bf16 v[80:83], v[176:179], v[200:203], v[80:83]
	v_mfma_f32_16x16x32_bf16 v[72:75], v[168:171], v[212:215], v[72:75]
	v_mfma_f32_16x16x32_bf16 v[64:67], v[176:179], v[212:215], v[64:67]
	s_setprio 0
	s_barrier
; #define PG8_STAGE(bufoff, gbase, voff) do { _Pragma("unroll") for (int _i = 0; _i < 2; ++_i) \
;         __builtin_amdgcn_global_load_lds((const unsigned*)((const char*)(gbase) + (voff)[_i]), (LAS unsigned*)(lds + (bufoff) + ldsw + _i * 8192), 16, 0, 0); } while (0)
; #define PG8_LDA(dst, b, h) do { _Pragma("unroll") for (int m = 0; m < 4; ++m) _Pragma("unroll") for (int k = 0; k < 2; ++k) dst[m][k] = *(const LAS bf16x8*)(lds + PG8_SA(b, h) + aoff + m * 2048 + k * 1024); } while (0)
; #define PG8_WAIT_V(n) asm volatile("s_waitcnt vmcnt(" #n ")" ::: "memory")
; #define PG8_WAIT_L(n) asm volatile("s_waitcnt lgkmcnt(" #n ")" ::: "memory")
; #define PG8_BAR __builtin_amdgcn_s_barrier()
; #define PG8_SCHED __builtin_amdgcn_sched_barrier(0)
; template <class Epi, class Sched, bool SWAPD = false>
; __device__ __forceinline__ void gemm_phase(LAS unsigned char* lds, const Gemm g, const Sched& S, const Epi& E) {
;     ...
;             PG8_LDA(At, 1, 1); PG8_STAGE(PG8_SB(1, 0), b3, voffB); PG8_STAGE(PG8_SB(1, 1), b3 + hstepB, voffB); PG8_STAGE(PG8_SA(1, 0), a3, voffA);
;             PG8_WAIT_V(8); PG8_WAIT_L(0); PG8_BAR; PG8_MMA(1, 0, At, B0); PG8_MMA(1, 1, At, B1); PG8_BAR; PG8_SCHED;
;         }
;         if (wr == 0) PG8_BAR;
	s_add_i32 s46, s64, s30
	v_lshl_add_u64 v[140:141], v[140:141], 0, s[8:9]
	s_mov_b32 m0, s46
	ds_read_b128 v[180:183], v147 offset:49152
	ds_read_b128 v[184:187], v147 offset:50176
	ds_read_b128 v[188:191], v147 offset:51200
	ds_read_b128 v[192:195], v147 offset:52224
	ds_read_b128 v[196:199], v147 offset:53248
	ds_read_b128 v[200:203], v147 offset:54272
	ds_read_b128 v[208:211], v147 offset:55296
	ds_read_b128 v[212:215], v147 offset:56320
	global_load_lds_dwordx4 v[140:141], off
	s_add_i32 m0, s46, 0x2000
	s_add_u32 s44, s44, 0x40080
	v_lshl_add_u64 v[140:141], v[204:205], 0, s[8:9]
	s_addc_u32 s45, s45, 0
	s_add_i32 s46, s65, s30
	global_load_lds_dwordx4 v[140:141], off
	v_lshl_add_u64 v[140:141], s[44:45], 0, v[130:131]
	s_mov_b32 m0, s46
	s_nop 0
	global_load_lds_dwordx4 v[140:141], off
	v_lshl_add_u64 v[140:141], s[44:45], 0, v[128:129]
	s_add_i32 m0, s46, 0x2000
	s_nop 0
	global_load_lds_dwordx4 v[140:141], off
	v_lshl_add_u64 v[140:141], v[216:217], 0, s[8:9]
	s_mov_b32 m0, s53
	s_nop 0
	global_load_lds_dwordx4 v[140:141], off
	v_lshl_add_u64 v[140:141], v[218:219], 0, s[8:9]
	s_mov_b32 m0, s54
	s_nop 0
	global_load_lds_dwordx4 v[140:141], off
	s_waitcnt vmcnt(8) lgkmcnt(0)
	s_barrier
	s_setprio 1
	v_mfma_f32_16x16x32_bf16 v[60:63], v[148:151], v[180:183], v[60:63]
	v_mfma_f32_16x16x32_bf16 v[52:55], v[156:159], v[180:183], v[52:55]
	v_mfma_f32_16x16x32_bf16 v[44:47], v[148:151], v[188:191], v[44:47]
	v_mfma_f32_16x16x32_bf16 v[36:39], v[156:159], v[188:191], v[36:39]
	v_mfma_f32_16x16x32_bf16 v[28:31], v[148:151], v[196:199], v[28:31]
	v_mfma_f32_16x16x32_bf16 v[20:23], v[156:159], v[196:199], v[20:23]
	v_mfma_f32_16x16x32_bf16 v[12:15], v[148:151], v[208:211], v[12:15]
	v_mfma_f32_16x16x32_bf16 v[4:7], v[156:159], v[208:211], v[4:7]
	v_mfma_f32_16x16x32_bf16 v[60:63], v[152:155], v[184:187], v[60:63]
	v_mfma_f32_16x16x32_bf16 v[52:55], v[160:163], v[184:187], v[52:55]
	v_mfma_f32_16x16x32_bf16 v[44:47], v[152:155], v[192:195], v[44:47]
	v_mfma_f32_16x16x32_bf16 v[36:39], v[160:163], v[192:195], v[36:39]
	v_mfma_f32_16x16x32_bf16 v[28:31], v[152:155], v[200:203], v[28:31]
	v_mfma_f32_16x16x32_bf16 v[20:23], v[160:163], v[200:203], v[20:23]
	v_mfma_f32_16x16x32_bf16 v[12:15], v[152:155], v[212:215], v[12:15]
	v_mfma_f32_16x16x32_bf16 v[4:7], v[160:163], v[212:215], v[4:7]
	s_setprio 0
	s_setprio 1
	v_mfma_f32_16x16x32_bf16 v[56:59], v[164:167], v[180:183], v[56:59]
	v_mfma_f32_16x16x32_bf16 v[48:51], v[172:175], v[180:183], v[48:51]
	v_mfma_f32_16x16x32_bf16 v[40:43], v[164:167], v[188:191], v[40:43]
	v_mfma_f32_16x16x32_bf16 v[32:35], v[172:175], v[188:191], v[32:35]
	v_mfma_f32_16x16x32_bf16 v[24:27], v[164:167], v[196:199], v[24:27]
	v_mfma_f32_16x16x32_bf16 v[16:19], v[172:175], v[196:199], v[16:19]
	v_mfma_f32_16x16x32_bf16 v[8:11], v[164:167], v[208:211], v[8:11]
	v_mfma_f32_16x16x32_bf16 v[0:3], v[172:175], v[208:211], v[0:3]
	v_mfma_f32_16x16x32_bf16 v[56:59], v[168:171], v[184:187], v[56:59]
	v_mfma_f32_16x16x32_bf16 v[48:51], v[176:179], v[184:187], v[48:51]
	v_mfma_f32_16x16x32_bf16 v[40:43], v[168:171], v[192:195], v[40:43]
	v_mfma_f32_16x16x32_bf16 v[32:35], v[176:179], v[192:195], v[32:35]
	v_mfma_f32_16x16x32_bf16 v[24:27], v[168:171], v[200:203], v[24:27]
	v_mfma_f32_16x16x32_bf16 v[16:19], v[176:179], v[200:203], v[16:19]
	v_mfma_f32_16x16x32_bf16 v[8:11], v[168:171], v[212:215], v[8:11]
	v_mfma_f32_16x16x32_bf16 v[0:3], v[176:179], v[212:215], v[0:3]
	s_setprio 0
	s_barrier
	s_add_i32 s63, s63, 2
	s_add_u32 s42, s42, 0x100
	s_addc_u32 s43, s43, 0
	s_add_u32 s61, s61, 0x100
	s_addc_u32 s62, s62, 0
	s_cmp_gt_u32 s63, 13
	s_cbranch_scc0 .LBB0_1044
	s_and_b64 vcc, exec, s[12:13]
	s_cbranch_vccz .LBB0_1047
	s_barrier

; #define PG8_STAGE(bufoff, gbase, voff) do { _Pragma("unroll") for (int _i = 0; _i < 2; ++_i) \
;         __builtin_amdgcn_global_load_lds((const unsigned*)((const char*)(gbase) + (voff)[_i]), (LAS unsigned*)(lds + (bufoff) + ldsw + _i * 8192), 16, 0, 0); } while (0)
; #define PG8_LDA(dst, b, h) do { _Pragma("unroll") for (int m = 0; m < 4; ++m) _Pragma("unroll") for (int k = 0; k < 2; ++k) dst[m][k] = *(const LAS bf16x8*)(lds + PG8_SA(b, h) + aoff + m * 2048 + k * 1024); } while (0)
; #define PG8_LDB(dst, b, h) do { _Pragma("unroll") for (int n = 0; n < 2; ++n) _Pragma("unroll") for (int k = 0; k < 2; ++k) dst[n][k] = *(const LAS bf16x8*)(lds + PG8_SB(b, h) + boff + n * 2048 + k * 1024); } while (0)
; #define PG8_WAIT_V(n) asm volatile("s_waitcnt vmcnt(" #n ")" ::: "memory")
; #define PG8_WAIT_L(n) asm volatile("s_waitcnt lgkmcnt(" #n ")" ::: "memory")
; #define PG8_BAR __builtin_amdgcn_s_barrier()
; #define PG8_SCHED __builtin_amdgcn_sched_barrier(0)
; template <class Epi, class Sched, bool SWAPD = false>
; __device__ __forceinline__ void gemm_phase(LAS unsigned char* lds, const Gemm g, const Sched& S, const Epi& E) {
;     ...
;             const bool last = (t == nt - 2);
;             const char* a1 = cA + (size_t)(t + 1) * kstepA;
;             const char* a2 = last ? nA : cA + (size_t)(t + 2) * kstepA; const char* b2 = last ? nB : cB + (size_t)(t + 2) * kstep;
;             const char* a3 = a2 + kstepA; const char* b3 = b2 + kstep;
;             PG8_LDB(B0, 0, 0); PG8_LDB(B1, 0, 1); PG8_SCHED; PG8_LDA(At, 0, 0); PG8_STAGE(PG8_SA(1, 1), a1 + hstepA, voffA);
;             PG8_WAIT_V(8); PG8_WAIT_L(0); PG8_BAR; PG8_MMA(0, 0, At, B0); PG8_MMA(0, 1, At, B1); PG8_BAR; PG8_SCHED;
;             PG8_LDA(At, 0, 1); PG8_STAGE(PG8_SB(0, 0), b2, voffB); PG8_STAGE(PG8_SB(0, 1), b2 + hstepB, voffB); PG8_STAGE(PG8_SA(0, 0), a2, voffA);
;             PG8_WAIT_V(8); PG8_WAIT_L(0); PG8_BAR; PG8_MMA(1, 0, At, B0); PG8_MMA(1, 1, At, B1); PG8_BAR; PG8_SCHED;
.LBB0_1121:
	ds_read_b128 v[128:131], v210
	ds_read_b128 v[132:135], v210 offset:1024
	ds_read_b128 v[136:139], v210 offset:2048
	ds_read_b128 v[140:143], v210 offset:3072
	ds_read_b128 v[144:147], v211
	ds_read_b128 v[148:151], v211 offset:1024
	ds_read_b128 v[152:155], v211 offset:2048
	ds_read_b128 v[156:159], v211 offset:3072
	s_add_u32 s36, s34, 0x100
	s_addc_u32 s37, s35, 0
	s_cmp_eq_u32 s64, 40
	s_cselect_b32 s41, s58, s37
	s_cselect_b32 s40, s59, s36
	s_cselect_b32 s39, s60, s63
	s_cselect_b32 s38, s61, s62
	v_lshl_add_u64 v[204:205], s[34:35], 0, v[180:181]
	s_add_i32 m0, s33, 0xc000
	ds_read_b128 v[188:191], v212
	ds_read_b128 v[192:195], v212 offset:1024
	ds_read_b128 v[196:199], v212 offset:2048
	ds_read_b128 v[200:203], v212 offset:3072
	ds_read_b128 v[214:217], v212 offset:4096
	ds_read_b128 v[218:221], v212 offset:5120
	ds_read_b128 v[222:225], v212 offset:6144
	ds_read_b128 v[226:229], v212 offset:7168
	global_load_lds_dwordx4 v[204:205], off
	v_lshl_add_u64 v[204:205], s[34:35], 0, v[182:183]
	s_add_i32 m0, s33, 0xe000
	s_nop 0
	global_load_lds_dwordx4 v[204:205], off
	s_waitcnt vmcnt(8) lgkmcnt(0)
	s_barrier
	s_setprio 1
	v_mfma_f32_16x16x32_bf16 v[124:127], v[128:131], v[188:191], v[124:127]
	v_mfma_f32_16x16x32_bf16 v[120:123], v[136:139], v[188:191], v[120:123]
	v_mfma_f32_16x16x32_bf16 v[116:119], v[128:131], v[196:199], v[116:119]
	v_mfma_f32_16x16x32_bf16 v[112:115], v[136:139], v[196:199], v[112:115]
	v_mfma_f32_16x16x32_bf16 v[92:95], v[128:131], v[214:217], v[92:95]
	v_mfma_f32_16x16x32_bf16 v[88:91], v[136:139], v[214:217], v[88:91]
	v_mfma_f32_16x16x32_bf16 v[76:79], v[128:131], v[222:225], v[76:79]
	v_mfma_f32_16x16x32_bf16 v[72:75], v[136:139], v[222:225], v[72:75]
	v_mfma_f32_16x16x32_bf16 v[124:127], v[132:135], v[192:195], v[124:127]
	v_mfma_f32_16x16x32_bf16 v[120:123], v[140:143], v[192:195], v[120:123]
	v_mfma_f32_16x16x32_bf16 v[116:119], v[132:135], v[200:203], v[116:119]
	v_mfma_f32_16x16x32_bf16 v[112:115], v[140:143], v[200:203], v[112:115]
	v_mfma_f32_16x16x32_bf16 v[92:95], v[132:135], v[218:221], v[92:95]
	v_mfma_f32_16x16x32_bf16 v[88:91], v[140:143], v[218:221], v[88:91]
	v_mfma_f32_16x16x32_bf16 v[76:79], v[132:135], v[226:229], v[76:79]
	v_mfma_f32_16x16x32_bf16 v[72:75], v[140:143], v[226:229], v[72:75]
	s_setprio 0
	s_setprio 1
	v_mfma_f32_16x16x32_bf16 v[108:111], v[144:147], v[188:191], v[108:111]
	v_mfma_f32_16x16x32_bf16 v[104:107], v[152:155], v[188:191], v[104:107]
	v_mfma_f32_16x16x32_bf16 v[100:103], v[144:147], v[196:199], v[100:103]
	v_mfma_f32_16x16x32_bf16 v[96:99], v[152:155], v[196:199], v[96:99]
	v_mfma_f32_16x16x32_bf16 v[84:87], v[144:147], v[214:217], v[84:87]
	v_mfma_f32_16x16x32_bf16 v[80:83], v[152:155], v[214:217], v[80:83]
	v_mfma_f32_16x16x32_bf16 v[68:71], v[144:147], v[222:225], v[68:71]
	v_mfma_f32_16x16x32_bf16 v[64:67], v[152:155], v[222:225], v[64:67]
	v_mfma_f32_16x16x32_bf16 v[108:111], v[148:151], v[192:195], v[108:111]
	v_mfma_f32_16x16x32_bf16 v[104:107], v[156:159], v[192:195], v[104:107]
	v_mfma_f32_16x16x32_bf16 v[100:103], v[148:151], v[200:203], v[100:103]
	v_mfma_f32_16x16x32_bf16 v[96:99], v[156:159], v[200:203], v[96:99]
	v_mfma_f32_16x16x32_bf16 v[84:87], v[148:151], v[218:221], v[84:87]
	v_mfma_f32_16x16x32_bf16 v[80:83], v[156:159], v[218:221], v[80:83]
	v_mfma_f32_16x16x32_bf16 v[68:71], v[148:151], v[226:229], v[68:71]
	v_mfma_f32_16x16x32_bf16 v[64:67], v[156:159], v[226:229], v[64:67]
	s_setprio 0
	s_barrier
	s_add_i32 s34, s52, s31
	v_lshl_add_u64 v[204:205], s[38:39], 0, v[160:161]
	s_mov_b32 m0, s34
	ds_read_b128 v[188:191], v212 offset:16384
	ds_read_b128 v[192:195], v212 offset:17408
	ds_read_b128 v[196:199], v212 offset:18432
	ds_read_b128 v[200:203], v212 offset:19456
	ds_read_b128 v[214:217], v212 offset:20480
	ds_read_b128 v[218:221], v212 offset:21504
	ds_read_b128 v[222:225], v212 offset:22528
	ds_read_b128 v[226:229], v212 offset:23552
	global_load_lds_dwordx4 v[204:205], off
	s_add_i32 m0, s34, 0x2000
	s_add_u32 s34, s38, 0xb0000
	v_lshl_add_u64 v[230:231], s[38:39], 0, v[162:163]
	s_addc_u32 s35, s39, 0
	s_add_i32 s65, s53, s31
	global_load_lds_dwordx4 v[230:231], off
	v_lshl_add_u64 v[232:233], s[34:35], 0, v[160:161]
	s_mov_b32 m0, s65
	v_lshl_add_u64 v[234:235], s[40:41], 0, v[162:163]
	global_load_lds_dwordx4 v[232:233], off
	v_lshl_add_u64 v[232:233], s[34:35], 0, v[162:163]
	s_add_i32 m0, s65, 0x2000
	s_nop 0
	global_load_lds_dwordx4 v[232:233], off
	v_lshl_add_u64 v[232:233], s[40:41], 0, v[160:161]
	s_mov_b32 m0, s33
	s_nop 0
	global_load_lds_dwordx4 v[232:233], off
	s_mov_b32 m0, s42
	s_nop 0
	global_load_lds_dwordx4 v[234:235], off
	s_waitcnt vmcnt(8) lgkmcnt(0)
	s_barrier
; #define PG8_STAGE(bufoff, gbase, voff) do { _Pragma("unroll") for (int _i = 0; _i < 2; ++_i) \
;         __builtin_amdgcn_global_load_lds((const unsigned*)((const char*)(gbase) + (voff)[_i]), (LAS unsigned*)(lds + (bufoff) + ldsw + _i * 8192), 16, 0, 0); } while (0)
; #define PG8_LDA(dst, b, h) do { _Pragma("unroll") for (int m = 0; m < 4; ++m) _Pragma("unroll") for (int k = 0; k < 2; ++k) dst[m][k] = *(const LAS bf16x8*)(lds + PG8_SA(b, h) + aoff + m * 2048 + k * 1024); } while (0)
; #define PG8_LDB(dst, b, h) do { _Pragma("unroll") for (int n = 0; n < 2; ++n) _Pragma("unroll") for (int k = 0; k < 2; ++k) dst[n][k] = *(const LAS bf16x8*)(lds + PG8_SB(b, h) + boff + n * 2048 + k * 1024); } while (0)
; #define PG8_WAIT_V(n) asm volatile("s_waitcnt vmcnt(" #n ")" ::: "memory")
; #define PG8_WAIT_L(n) asm volatile("s_waitcnt lgkmcnt(" #n ")" ::: "memory")
; #define PG8_BAR __builtin_amdgcn_s_barrier()
; #define PG8_SCHED __builtin_amdgcn_sched_barrier(0)
; template <class Epi, class Sched, bool SWAPD = false>
; __device__ __forceinline__ void gemm_phase(LAS unsigned char* lds, const Gemm g, const Sched& S, const Epi& E) {
;     ...
;             PG8_WAIT_V(8); PG8_WAIT_L(0); PG8_BAR; PG8_MMA(1, 0, At, B0); PG8_MMA(1, 1, At, B1); PG8_BAR; PG8_SCHED;
;             PG8_LDB(B0, 1, 0); PG8_LDB(B1, 1, 1); PG8_SCHED; PG8_LDA(At, 1, 0); PG8_STAGE(PG8_SA(0, 1), a2 + hstepA, voffA);
;             PG8_WAIT_V(8); PG8_WAIT_L(0); PG8_BAR; PG8_MMA(0, 0, At, B0); PG8_MMA(0, 1, At, B1); PG8_BAR; PG8_SCHED;
	s_setprio 1
	v_mfma_f32_16x16x32_bf16 v[60:63], v[128:131], v[188:191], v[60:63]
	v_mfma_f32_16x16x32_bf16 v[56:59], v[136:139], v[188:191], v[56:59]
	v_mfma_f32_16x16x32_bf16 v[44:47], v[128:131], v[196:199], v[44:47]
	v_mfma_f32_16x16x32_bf16 v[40:43], v[136:139], v[196:199], v[40:43]
	v_mfma_f32_16x16x32_bf16 v[36:39], v[128:131], v[214:217], v[36:39]
	v_mfma_f32_16x16x32_bf16 v[32:35], v[136:139], v[214:217], v[32:35]
	v_mfma_f32_16x16x32_bf16 v[20:23], v[128:131], v[222:225], v[20:23]
	v_mfma_f32_16x16x32_bf16 v[16:19], v[136:139], v[222:225], v[16:19]
	v_mfma_f32_16x16x32_bf16 v[60:63], v[132:135], v[192:195], v[60:63]
	v_mfma_f32_16x16x32_bf16 v[56:59], v[140:143], v[192:195], v[56:59]
	v_mfma_f32_16x16x32_bf16 v[44:47], v[132:135], v[200:203], v[44:47]
	v_mfma_f32_16x16x32_bf16 v[40:43], v[140:143], v[200:203], v[40:43]
	v_mfma_f32_16x16x32_bf16 v[36:39], v[132:135], v[218:221], v[36:39]
	v_mfma_f32_16x16x32_bf16 v[32:35], v[140:143], v[218:221], v[32:35]
	v_mfma_f32_16x16x32_bf16 v[20:23], v[132:135], v[226:229], v[20:23]
	v_mfma_f32_16x16x32_bf16 v[16:19], v[140:143], v[226:229], v[16:19]
	s_setprio 0
	s_setprio 1
	v_mfma_f32_16x16x32_bf16 v[52:55], v[144:147], v[188:191], v[52:55]
	v_mfma_f32_16x16x32_bf16 v[48:51], v[152:155], v[188:191], v[48:51]
	v_mfma_f32_16x16x32_bf16 v[28:31], v[144:147], v[196:199], v[28:31]
	v_mfma_f32_16x16x32_bf16 v[24:27], v[152:155], v[196:199], v[24:27]
	v_mfma_f32_16x16x32_bf16 v[12:15], v[144:147], v[214:217], v[12:15]
	v_mfma_f32_16x16x32_bf16 v[8:11], v[152:155], v[214:217], v[8:11]
	v_mfma_f32_16x16x32_bf16 v[4:7], v[144:147], v[222:225], v[4:7]
	v_mfma_f32_16x16x32_bf16 v[0:3], v[152:155], v[222:225], v[0:3]
	v_mfma_f32_16x16x32_bf16 v[52:55], v[148:151], v[192:195], v[52:55]
	v_mfma_f32_16x16x32_bf16 v[48:51], v[156:159], v[192:195], v[48:51]
	v_mfma_f32_16x16x32_bf16 v[28:31], v[148:151], v[200:203], v[28:31]
	v_mfma_f32_16x16x32_bf16 v[24:27], v[156:159], v[200:203], v[24:27]
	v_mfma_f32_16x16x32_bf16 v[12:15], v[148:151], v[218:221], v[12:15]
	v_mfma_f32_16x16x32_bf16 v[8:11], v[156:159], v[218:221], v[8:11]
	v_mfma_f32_16x16x32_bf16 v[4:7], v[148:151], v[226:229], v[4:7]
	v_mfma_f32_16x16x32_bf16 v[0:3], v[156:159], v[226:229], v[0:3]
	s_setprio 0
	s_barrier
	s_add_i32 s65, 0, 0x18000
	s_add_i32 s66, 0, 0x1c000
	v_add_u32_e32 v140, s65, v208
	v_add_u32_e32 v156, s66, v208
	ds_read_b128 v[128:131], v140
	ds_read_b128 v[132:135], v140 offset:1024
	ds_read_b128 v[136:139], v140 offset:2048
	ds_read_b128 v[140:143], v140 offset:3072
	ds_read_b128 v[144:147], v156
	ds_read_b128 v[148:151], v156 offset:1024
	ds_read_b128 v[152:155], v156 offset:2048
	ds_read_b128 v[156:159], v156 offset:3072
	s_add_u32 s34, s40, 0xb0000
	s_addc_u32 s35, s41, 0
	s_mov_b32 m0, s43
	v_lshl_add_u64 v[236:237], s[34:35], 0, v[160:161]
	ds_read_b128 v[188:191], v212 offset:32768
	ds_read_b128 v[192:195], v212 offset:33792
	ds_read_b128 v[196:199], v212 offset:34816
	ds_read_b128 v[200:203], v212 offset:35840
	ds_read_b128 v[214:217], v212 offset:36864
	ds_read_b128 v[218:221], v212 offset:37888
	ds_read_b128 v[222:225], v212 offset:38912
	ds_read_b128 v[226:229], v212 offset:39936
	global_load_lds_dwordx4 v[236:237], off
	v_lshl_add_u64 v[236:237], s[34:35], 0, v[162:163]
	s_mov_b32 m0, s44
	s_nop 0
	global_load_lds_dwordx4 v[236:237], off
	s_waitcnt vmcnt(8) lgkmcnt(0)
	s_barrier
	s_setprio 1
	v_mfma_f32_16x16x32_bf16 v[124:127], v[128:131], v[188:191], v[124:127]
	v_mfma_f32_16x16x32_bf16 v[120:123], v[136:139], v[188:191], v[120:123]
	v_mfma_f32_16x16x32_bf16 v[116:119], v[128:131], v[196:199], v[116:119]
	v_mfma_f32_16x16x32_bf16 v[112:115], v[136:139], v[196:199], v[112:115]
	v_mfma_f32_16x16x32_bf16 v[92:95], v[128:131], v[214:217], v[92:95]
	v_mfma_f32_16x16x32_bf16 v[88:91], v[136:139], v[214:217], v[88:91]
	v_mfma_f32_16x16x32_bf16 v[76:79], v[128:131], v[222:225], v[76:79]
	v_mfma_f32_16x16x32_bf16 v[72:75], v[136:139], v[222:225], v[72:75]
	v_mfma_f32_16x16x32_bf16 v[124:127], v[132:135], v[192:195], v[124:127]
	v_mfma_f32_16x16x32_bf16 v[120:123], v[140:143], v[192:195], v[120:123]
	v_mfma_f32_16x16x32_bf16 v[116:119], v[132:135], v[200:203], v[116:119]
	v_mfma_f32_16x16x32_bf16 v[112:115], v[140:143], v[200:203], v[112:115]
	v_mfma_f32_16x16x32_bf16 v[92:95], v[132:135], v[218:221], v[92:95]
	v_mfma_f32_16x16x32_bf16 v[88:91], v[140:143], v[218:221], v[88:91]
	v_mfma_f32_16x16x32_bf16 v[76:79], v[132:135], v[226:229], v[76:79]
	v_mfma_f32_16x16x32_bf16 v[72:75], v[140:143], v[226:229], v[72:75]
	s_setprio 0
	s_setprio 1
	v_mfma_f32_16x16x32_bf16 v[108:111], v[144:147], v[188:191], v[108:111]
	v_mfma_f32_16x16x32_bf16 v[104:107], v[152:155], v[188:191], v[104:107]
	v_mfma_f32_16x16x32_bf16 v[100:103], v[144:147], v[196:199], v[100:103]
	v_mfma_f32_16x16x32_bf16 v[96:99], v[152:155], v[196:199], v[96:99]
	v_mfma_f32_16x16x32_bf16 v[84:87], v[144:147], v[214:217], v[84:87]
	v_mfma_f32_16x16x32_bf16 v[80:83], v[152:155], v[214:217], v[80:83]
	v_mfma_f32_16x16x32_bf16 v[68:71], v[144:147], v[222:225], v[68:71]
	v_mfma_f32_16x16x32_bf16 v[64:67], v[152:155], v[222:225], v[64:67]
	v_mfma_f32_16x16x32_bf16 v[108:111], v[148:151], v[192:195], v[108:111]
	v_mfma_f32_16x16x32_bf16 v[104:107], v[156:159], v[192:195], v[104:107]
	v_mfma_f32_16x16x32_bf16 v[100:103], v[148:151], v[200:203], v[100:103]
	v_mfma_f32_16x16x32_bf16 v[96:99], v[156:159], v[200:203], v[96:99]
	v_mfma_f32_16x16x32_bf16 v[84:87], v[148:151], v[218:221], v[84:87]
	v_mfma_f32_16x16x32_bf16 v[80:83], v[156:159], v[218:221], v[80:83]
	v_mfma_f32_16x16x32_bf16 v[68:71], v[148:151], v[226:229], v[68:71]
	v_mfma_f32_16x16x32_bf16 v[64:67], v[156:159], v[226:229], v[64:67]
	s_setprio 0
	s_barrier
; #define PG8_STAGE(bufoff, gbase, voff) do { _Pragma("unroll") for (int _i = 0; _i < 2; ++_i) \
;         __builtin_amdgcn_global_load_lds((const unsigned*)((const char*)(gbase) + (voff)[_i]), (LAS unsigned*)(lds + (bufoff) + ldsw + _i * 8192), 16, 0, 0); } while (0)
; #define PG8_LDA(dst, b, h) do { _Pragma("unroll") for (int m = 0; m < 4; ++m) _Pragma("unroll") for (int k = 0; k < 2; ++k) dst[m][k] = *(const LAS bf16x8*)(lds + PG8_SA(b, h) + aoff + m * 2048 + k * 1024); } while (0)
; #define PG8_WAIT_V(n) asm volatile("s_waitcnt vmcnt(" #n ")" ::: "memory")
; #define PG8_WAIT_L(n) asm volatile("s_waitcnt lgkmcnt(" #n ")" ::: "memory")
; #define PG8_BAR __builtin_amdgcn_s_barrier()
; #define PG8_SCHED __builtin_amdgcn_sched_barrier(0)
; template <class Epi, class Sched, bool SWAPD = false>
; __device__ __forceinline__ void gemm_phase(LAS unsigned char* lds, const Gemm g, const Sched& S, const Epi& E) {
;     ...
;             PG8_LDA(At, 1, 1); PG8_STAGE(PG8_SB(1, 0), b3, voffB); PG8_STAGE(PG8_SB(1, 1), b3 + hstepB, voffB); PG8_STAGE(PG8_SA(1, 0), a3, voffA);
;             PG8_WAIT_V(8); PG8_WAIT_L(0); PG8_BAR; PG8_MMA(1, 0, At, B0); PG8_MMA(1, 1, At, B1); PG8_BAR; PG8_SCHED;
;         }
;         if (wr == 0) PG8_BAR;
	s_add_i32 s34, s65, s31
	v_lshl_add_u64 v[204:205], v[204:205], 0, s[8:9]
	s_mov_b32 m0, s34
	ds_read_b128 v[188:191], v212 offset:49152
	ds_read_b128 v[192:195], v212 offset:50176
	ds_read_b128 v[196:199], v212 offset:51200
	ds_read_b128 v[200:203], v212 offset:52224
	ds_read_b128 v[214:217], v212 offset:53248
	ds_read_b128 v[218:221], v212 offset:54272
	ds_read_b128 v[222:225], v212 offset:55296
	ds_read_b128 v[226:229], v212 offset:56320
	global_load_lds_dwordx4 v[204:205], off
	s_add_i32 m0, s34, 0x2000
	s_add_u32 s34, s38, 0xb0080
	v_lshl_add_u64 v[204:205], v[230:231], 0, s[8:9]
	s_addc_u32 s35, s39, 0
	s_add_i32 s38, s66, s31
	global_load_lds_dwordx4 v[204:205], off
	v_lshl_add_u64 v[204:205], s[34:35], 0, v[160:161]
	s_mov_b32 m0, s38
	s_nop 0
	global_load_lds_dwordx4 v[204:205], off
	v_lshl_add_u64 v[204:205], s[34:35], 0, v[162:163]
	s_add_i32 m0, s38, 0x2000
	s_nop 0
	global_load_lds_dwordx4 v[204:205], off
	v_lshl_add_u64 v[204:205], v[232:233], 0, s[8:9]
	s_mov_b32 m0, s50
	s_nop 0
	global_load_lds_dwordx4 v[204:205], off
	v_lshl_add_u64 v[204:205], v[234:235], 0, s[8:9]
	s_mov_b32 m0, s51
	s_nop 0
	global_load_lds_dwordx4 v[204:205], off
	s_waitcnt vmcnt(8) lgkmcnt(0)
	s_barrier
	s_setprio 1
	v_mfma_f32_16x16x32_bf16 v[60:63], v[128:131], v[188:191], v[60:63]
	v_mfma_f32_16x16x32_bf16 v[56:59], v[136:139], v[188:191], v[56:59]
	v_mfma_f32_16x16x32_bf16 v[44:47], v[128:131], v[196:199], v[44:47]
	v_mfma_f32_16x16x32_bf16 v[40:43], v[136:139], v[196:199], v[40:43]
	v_mfma_f32_16x16x32_bf16 v[36:39], v[128:131], v[214:217], v[36:39]
	v_mfma_f32_16x16x32_bf16 v[32:35], v[136:139], v[214:217], v[32:35]
	v_mfma_f32_16x16x32_bf16 v[20:23], v[128:131], v[222:225], v[20:23]
	v_mfma_f32_16x16x32_bf16 v[16:19], v[136:139], v[222:225], v[16:19]
	v_mfma_f32_16x16x32_bf16 v[60:63], v[132:135], v[192:195], v[60:63]
	v_mfma_f32_16x16x32_bf16 v[56:59], v[140:143], v[192:195], v[56:59]
	v_mfma_f32_16x16x32_bf16 v[44:47], v[132:135], v[200:203], v[44:47]
	v_mfma_f32_16x16x32_bf16 v[40:43], v[140:143], v[200:203], v[40:43]
	v_mfma_f32_16x16x32_bf16 v[36:39], v[132:135], v[218:221], v[36:39]
	v_mfma_f32_16x16x32_bf16 v[32:35], v[140:143], v[218:221], v[32:35]
	v_mfma_f32_16x16x32_bf16 v[20:23], v[132:135], v[226:229], v[20:23]
	v_mfma_f32_16x16x32_bf16 v[16:19], v[140:143], v[226:229], v[16:19]
	s_setprio 0
	s_setprio 1
	v_mfma_f32_16x16x32_bf16 v[52:55], v[144:147], v[188:191], v[52:55]
	v_mfma_f32_16x16x32_bf16 v[48:51], v[152:155], v[188:191], v[48:51]
	v_mfma_f32_16x16x32_bf16 v[28:31], v[144:147], v[196:199], v[28:31]
	v_mfma_f32_16x16x32_bf16 v[24:27], v[152:155], v[196:199], v[24:27]
	v_mfma_f32_16x16x32_bf16 v[12:15], v[144:147], v[214:217], v[12:15]
	v_mfma_f32_16x16x32_bf16 v[8:11], v[152:155], v[214:217], v[8:11]
	v_mfma_f32_16x16x32_bf16 v[4:7], v[144:147], v[222:225], v[4:7]
	v_mfma_f32_16x16x32_bf16 v[0:3], v[152:155], v[222:225], v[0:3]
	v_mfma_f32_16x16x32_bf16 v[52:55], v[148:151], v[192:195], v[52:55]
	v_mfma_f32_16x16x32_bf16 v[48:51], v[156:159], v[192:195], v[48:51]
	v_mfma_f32_16x16x32_bf16 v[28:31], v[148:151], v[200:203], v[28:31]
	v_mfma_f32_16x16x32_bf16 v[24:27], v[156:159], v[200:203], v[24:27]
	v_mfma_f32_16x16x32_bf16 v[12:15], v[148:151], v[218:221], v[12:15]
	v_mfma_f32_16x16x32_bf16 v[8:11], v[156:159], v[218:221], v[8:11]
	v_mfma_f32_16x16x32_bf16 v[4:7], v[148:151], v[226:229], v[4:7]
	v_mfma_f32_16x16x32_bf16 v[0:3], v[156:159], v[226:229], v[0:3]
	s_setprio 0
	s_barrier
	s_add_i32 s64, s64, 2
	s_add_u32 s62, s62, 0x100
	s_addc_u32 s63, s63, 0
	s_cmp_gt_u32 s64, 41
	s_mov_b64 s[34:35], s[36:37]
	s_cbranch_scc0 .LBB0_1121
	s_and_b64 vcc, exec, s[12:13]
	s_cbranch_vccz .LBB0_1124
	s_barrier

; #define PG8_STAGE(bufoff, gbase, voff) do { _Pragma("unroll") for (int _i = 0; _i < 2; ++_i) \
;         __builtin_amdgcn_global_load_lds((const unsigned*)((const char*)(gbase) + (voff)[_i]), (LAS unsigned*)(lds + (bufoff) + ldsw + _i * 8192), 16, 0, 0); } while (0)
; #define PG8_LDA(dst, b, h) do { _Pragma("unroll") for (int m = 0; m < 4; ++m) _Pragma("unroll") for (int k = 0; k < 2; ++k) dst[m][k] = *(const LAS bf16x8*)(lds + PG8_SA(b, h) + aoff + m * 2048 + k * 1024); } while (0)
; #define PG8_LDB(dst, b, h) do { _Pragma("unroll") for (int n = 0; n < 2; ++n) _Pragma("unroll") for (int k = 0; k < 2; ++k) dst[n][k] = *(const LAS bf16x8*)(lds + PG8_SB(b, h) + boff + n * 2048 + k * 1024); } while (0)
; #define PG8_WAIT_V(n) asm volatile("s_waitcnt vmcnt(" #n ")" ::: "memory")
; #define PG8_WAIT_L(n) asm volatile("s_waitcnt lgkmcnt(" #n ")" ::: "memory")
; #define PG8_BAR __builtin_amdgcn_s_barrier()
; #define PG8_SCHED __builtin_amdgcn_sched_barrier(0)
; template <class Epi, class Sched, bool SWAPD = false>
; __device__ __forceinline__ void gemm_phase(LAS unsigned char* lds, const Gemm g, const Sched& S, const Epi& E) {
;     ...
;             const bool last = (t == nt - 2);
;             const char* a1 = cA + (size_t)(t + 1) * kstepA;
;             const char* a2 = last ? nA : cA + (size_t)(t + 2) * kstepA; const char* b2 = last ? nB : cB + (size_t)(t + 2) * kstep;
;             const char* a3 = a2 + kstepA; const char* b3 = b2 + kstep;
;             PG8_LDB(B0, 0, 0); PG8_LDB(B1, 0, 1); PG8_SCHED; PG8_LDA(At, 0, 0); PG8_STAGE(PG8_SA(1, 1), a1 + hstepA, voffA);
;             PG8_WAIT_V(8); PG8_WAIT_L(0); PG8_BAR; PG8_MMA(0, 0, At, B0); PG8_MMA(0, 1, At, B1); PG8_BAR; PG8_SCHED;
;             PG8_LDA(At, 0, 1); PG8_STAGE(PG8_SB(0, 0), b2, voffB); PG8_STAGE(PG8_SB(0, 1), b2 + hstepB, voffB); PG8_STAGE(PG8_SA(0, 0), a2, voffA);
;             PG8_WAIT_V(8); PG8_WAIT_L(0); PG8_BAR; PG8_MMA(1, 0, At, B0); PG8_MMA(1, 1, At, B1); PG8_BAR; PG8_SCHED;
.LBB0_1531:
	ds_read_b128 v[142:145], v151
	ds_read_b128 v[154:157], v151 offset:1024
	ds_read_b128 v[158:161], v151 offset:2048
	ds_read_b128 v[162:165], v151 offset:3072
	ds_read_b128 v[166:169], v152
	ds_read_b128 v[170:173], v152 offset:1024
	ds_read_b128 v[174:177], v152 offset:2048
	ds_read_b128 v[178:181], v152 offset:3072
	s_add_u32 s42, s40, 0xfffe0080
	s_addc_u32 s43, s41, -1
	s_cmp_eq_u32 s61, 4
	s_cselect_b32 s45, s9, s43
	s_cselect_b32 s44, s25, s42
	s_cselect_b32 s43, s27, s60
	s_cselect_b32 s42, s58, s59
	v_lshl_add_u64 v[216:217], s[40:41], 0, v[134:135]
	s_add_i32 m0, s33, 0xc000
	ds_read_b128 v[182:185], v153
	ds_read_b128 v[186:189], v153 offset:1024
	ds_read_b128 v[190:193], v153 offset:2048
	ds_read_b128 v[194:197], v153 offset:3072
	ds_read_b128 v[198:201], v153 offset:4096
	ds_read_b128 v[202:205], v153 offset:5120
	ds_read_b128 v[208:211], v153 offset:6144
	ds_read_b128 v[212:215], v153 offset:7168
	global_load_lds_dwordx4 v[216:217], off
	v_lshl_add_u64 v[216:217], s[40:41], 0, v[136:137]
	s_add_i32 m0, s33, 0xe000
	s_nop 0
	global_load_lds_dwordx4 v[216:217], off
	s_waitcnt vmcnt(8) lgkmcnt(0)
	s_barrier
	s_setprio 1
	v_mfma_f32_16x16x32_bf16 v[124:127], v[182:185], v[142:145], v[124:127]
	v_mfma_f32_16x16x32_bf16 v[120:123], v[182:185], v[158:161], v[120:123]
	v_mfma_f32_16x16x32_bf16 v[108:111], v[190:193], v[142:145], v[108:111]
	v_mfma_f32_16x16x32_bf16 v[104:107], v[190:193], v[158:161], v[104:107]
	v_mfma_f32_16x16x32_bf16 v[96:99], v[198:201], v[142:145], v[96:99]
	v_mfma_f32_16x16x32_bf16 v[88:91], v[198:201], v[158:161], v[88:91]
	v_mfma_f32_16x16x32_bf16 v[80:83], v[208:211], v[142:145], v[80:83]
	v_mfma_f32_16x16x32_bf16 v[72:75], v[208:211], v[158:161], v[72:75]
	v_mfma_f32_16x16x32_bf16 v[124:127], v[186:189], v[154:157], v[124:127]
	v_mfma_f32_16x16x32_bf16 v[120:123], v[186:189], v[162:165], v[120:123]
	v_mfma_f32_16x16x32_bf16 v[108:111], v[194:197], v[154:157], v[108:111]
	v_mfma_f32_16x16x32_bf16 v[104:107], v[194:197], v[162:165], v[104:107]
	v_mfma_f32_16x16x32_bf16 v[96:99], v[202:205], v[154:157], v[96:99]
	v_mfma_f32_16x16x32_bf16 v[88:91], v[202:205], v[162:165], v[88:91]
	v_mfma_f32_16x16x32_bf16 v[80:83], v[212:215], v[154:157], v[80:83]
	v_mfma_f32_16x16x32_bf16 v[72:75], v[212:215], v[162:165], v[72:75]
	s_setprio 0
	s_setprio 1
	v_mfma_f32_16x16x32_bf16 v[116:119], v[182:185], v[166:169], v[116:119]
	v_mfma_f32_16x16x32_bf16 v[112:115], v[182:185], v[174:177], v[112:115]
	v_mfma_f32_16x16x32_bf16 v[100:103], v[190:193], v[166:169], v[100:103]
	v_mfma_f32_16x16x32_bf16 v[92:95], v[190:193], v[174:177], v[92:95]
	v_mfma_f32_16x16x32_bf16 v[84:87], v[198:201], v[166:169], v[84:87]
	v_mfma_f32_16x16x32_bf16 v[76:79], v[198:201], v[174:177], v[76:79]
	v_mfma_f32_16x16x32_bf16 v[68:71], v[208:211], v[166:169], v[68:71]
	v_mfma_f32_16x16x32_bf16 v[64:67], v[208:211], v[174:177], v[64:67]
	v_mfma_f32_16x16x32_bf16 v[116:119], v[186:189], v[170:173], v[116:119]
	v_mfma_f32_16x16x32_bf16 v[112:115], v[186:189], v[178:181], v[112:115]
	v_mfma_f32_16x16x32_bf16 v[100:103], v[194:197], v[170:173], v[100:103]
	v_mfma_f32_16x16x32_bf16 v[92:95], v[194:197], v[178:181], v[92:95]
	v_mfma_f32_16x16x32_bf16 v[84:87], v[202:205], v[170:173], v[84:87]
	v_mfma_f32_16x16x32_bf16 v[76:79], v[202:205], v[178:181], v[76:79]
	v_mfma_f32_16x16x32_bf16 v[68:71], v[212:215], v[170:173], v[68:71]
	v_mfma_f32_16x16x32_bf16 v[64:67], v[212:215], v[178:181], v[64:67]
	s_setprio 0
	s_barrier
	s_add_i32 s62, s55, s21
	v_lshl_add_u64 v[216:217], s[42:43], 0, v[128:129]
	s_mov_b32 m0, s62
	ds_read_b128 v[182:185], v153 offset:16384
	ds_read_b128 v[186:189], v153 offset:17408
	ds_read_b128 v[190:193], v153 offset:18432
	ds_read_b128 v[194:197], v153 offset:19456
	ds_read_b128 v[198:201], v153 offset:20480
	ds_read_b128 v[202:205], v153 offset:21504
	ds_read_b128 v[208:211], v153 offset:22528
	ds_read_b128 v[212:215], v153 offset:23552
	global_load_lds_dwordx4 v[216:217], off
	s_add_i32 m0, s62, 0x2000
	s_add_u32 s62, s42, 0x20000
	v_lshl_add_u64 v[218:219], s[42:43], 0, v[130:131]
	s_addc_u32 s63, s43, 0
	s_add_i32 s64, s56, s21
	global_load_lds_dwordx4 v[218:219], off
	v_lshl_add_u64 v[220:221], s[62:63], 0, v[128:129]
	s_mov_b32 m0, s64
	v_lshl_add_u64 v[222:223], s[44:45], 0, v[130:131]
	global_load_lds_dwordx4 v[220:221], off
	v_lshl_add_u64 v[220:221], s[62:63], 0, v[130:131]
	s_add_i32 m0, s64, 0x2000
	s_nop 0
	global_load_lds_dwordx4 v[220:221], off
	v_lshl_add_u64 v[220:221], s[44:45], 0, v[128:129]
	s_mov_b32 m0, s33
	s_nop 0
	global_load_lds_dwordx4 v[220:221], off
	s_mov_b32 m0, s46
	s_nop 0
	global_load_lds_dwordx4 v[222:223], off
	s_waitcnt vmcnt(8) lgkmcnt(0)
	s_barrier
; #define PG8_STAGE(bufoff, gbase, voff) do { _Pragma("unroll") for (int _i = 0; _i < 2; ++_i) \
;         __builtin_amdgcn_global_load_lds((const unsigned*)((const char*)(gbase) + (voff)[_i]), (LAS unsigned*)(lds + (bufoff) + ldsw + _i * 8192), 16, 0, 0); } while (0)
; #define PG8_LDA(dst, b, h) do { _Pragma("unroll") for (int m = 0; m < 4; ++m) _Pragma("unroll") for (int k = 0; k < 2; ++k) dst[m][k] = *(const LAS bf16x8*)(lds + PG8_SA(b, h) + aoff + m * 2048 + k * 1024); } while (0)
; #define PG8_LDB(dst, b, h) do { _Pragma("unroll") for (int n = 0; n < 2; ++n) _Pragma("unroll") for (int k = 0; k < 2; ++k) dst[n][k] = *(const LAS bf16x8*)(lds + PG8_SB(b, h) + boff + n * 2048 + k * 1024); } while (0)
; #define PG8_WAIT_V(n) asm volatile("s_waitcnt vmcnt(" #n ")" ::: "memory")
; #define PG8_WAIT_L(n) asm volatile("s_waitcnt lgkmcnt(" #n ")" ::: "memory")
; #define PG8_BAR __builtin_amdgcn_s_barrier()
; #define PG8_SCHED __builtin_amdgcn_sched_barrier(0)
; template <class Epi, class Sched, bool SWAPD = false>
; __device__ __forceinline__ void gemm_phase(LAS unsigned char* lds, const Gemm g, const Sched& S, const Epi& E) {
;     ...
;             PG8_WAIT_V(8); PG8_WAIT_L(0); PG8_BAR; PG8_MMA(1, 0, At, B0); PG8_MMA(1, 1, At, B1); PG8_BAR; PG8_SCHED;
;             PG8_LDB(B0, 1, 0); PG8_LDB(B1, 1, 1); PG8_SCHED; PG8_LDA(At, 1, 0); PG8_STAGE(PG8_SA(0, 1), a2 + hstepA, voffA);
;             PG8_WAIT_V(8); PG8_WAIT_L(0); PG8_BAR; PG8_MMA(0, 0, At, B0); PG8_MMA(0, 1, At, B1); PG8_BAR; PG8_SCHED;
	s_setprio 1
	v_mfma_f32_16x16x32_bf16 v[60:63], v[182:185], v[142:145], v[60:63]
	v_mfma_f32_16x16x32_bf16 v[56:59], v[182:185], v[158:161], v[56:59]
	v_mfma_f32_16x16x32_bf16 v[48:51], v[190:193], v[142:145], v[48:51]
	v_mfma_f32_16x16x32_bf16 v[40:43], v[190:193], v[158:161], v[40:43]
	v_mfma_f32_16x16x32_bf16 v[32:35], v[198:201], v[142:145], v[32:35]
	v_mfma_f32_16x16x32_bf16 v[24:27], v[198:201], v[158:161], v[24:27]
	v_mfma_f32_16x16x32_bf16 v[16:19], v[208:211], v[142:145], v[16:19]
	v_mfma_f32_16x16x32_bf16 v[8:11], v[208:211], v[158:161], v[8:11]
	v_mfma_f32_16x16x32_bf16 v[60:63], v[186:189], v[154:157], v[60:63]
	v_mfma_f32_16x16x32_bf16 v[56:59], v[186:189], v[162:165], v[56:59]
	v_mfma_f32_16x16x32_bf16 v[48:51], v[194:197], v[154:157], v[48:51]
	v_mfma_f32_16x16x32_bf16 v[40:43], v[194:197], v[162:165], v[40:43]
	v_mfma_f32_16x16x32_bf16 v[32:35], v[202:205], v[154:157], v[32:35]
	v_mfma_f32_16x16x32_bf16 v[24:27], v[202:205], v[162:165], v[24:27]
	v_mfma_f32_16x16x32_bf16 v[16:19], v[212:215], v[154:157], v[16:19]
	v_mfma_f32_16x16x32_bf16 v[8:11], v[212:215], v[162:165], v[8:11]
	s_setprio 0
	s_setprio 1
	v_mfma_f32_16x16x32_bf16 v[52:55], v[182:185], v[166:169], v[52:55]
	v_mfma_f32_16x16x32_bf16 v[44:47], v[182:185], v[174:177], v[44:47]
	v_mfma_f32_16x16x32_bf16 v[36:39], v[190:193], v[166:169], v[36:39]
	v_mfma_f32_16x16x32_bf16 v[28:31], v[190:193], v[174:177], v[28:31]
	v_mfma_f32_16x16x32_bf16 v[20:23], v[198:201], v[166:169], v[20:23]
	v_mfma_f32_16x16x32_bf16 v[12:15], v[198:201], v[174:177], v[12:15]
	v_mfma_f32_16x16x32_bf16 v[4:7], v[208:211], v[166:169], v[4:7]
	v_mfma_f32_16x16x32_bf16 v[0:3], v[208:211], v[174:177], v[0:3]
	v_mfma_f32_16x16x32_bf16 v[52:55], v[186:189], v[170:173], v[52:55]
	v_mfma_f32_16x16x32_bf16 v[44:47], v[186:189], v[178:181], v[44:47]
	v_mfma_f32_16x16x32_bf16 v[36:39], v[194:197], v[170:173], v[36:39]
	v_mfma_f32_16x16x32_bf16 v[28:31], v[194:197], v[178:181], v[28:31]
	v_mfma_f32_16x16x32_bf16 v[20:23], v[202:205], v[170:173], v[20:23]
	v_mfma_f32_16x16x32_bf16 v[12:15], v[202:205], v[178:181], v[12:15]
	v_mfma_f32_16x16x32_bf16 v[4:7], v[212:215], v[170:173], v[4:7]
	v_mfma_f32_16x16x32_bf16 v[0:3], v[212:215], v[178:181], v[0:3]
	s_setprio 0
	s_barrier
	s_add_i32 s62, 0, 0x18000
	s_add_i32 s63, 0, 0x1c000
	v_add_u32_e32 v162, s62, v146
	v_add_u32_e32 v178, s63, v146
	ds_read_b128 v[142:145], v162
	ds_read_b128 v[154:157], v162 offset:1024
	ds_read_b128 v[158:161], v162 offset:2048
	ds_read_b128 v[162:165], v162 offset:3072
	ds_read_b128 v[166:169], v178
	ds_read_b128 v[170:173], v178 offset:1024
	ds_read_b128 v[174:177], v178 offset:2048
	ds_read_b128 v[178:181], v178 offset:3072
	s_add_u32 s44, s44, 0x20000
	s_addc_u32 s45, s45, 0
	s_mov_b32 m0, s47
	v_lshl_add_u64 v[224:225], s[44:45], 0, v[128:129]
	ds_read_b128 v[182:185], v153 offset:32768
	ds_read_b128 v[186:189], v153 offset:33792
	ds_read_b128 v[190:193], v153 offset:34816
	ds_read_b128 v[194:197], v153 offset:35840
	ds_read_b128 v[198:201], v153 offset:36864
	ds_read_b128 v[202:205], v153 offset:37888
	ds_read_b128 v[208:211], v153 offset:38912
	ds_read_b128 v[212:215], v153 offset:39936
	global_load_lds_dwordx4 v[224:225], off
	v_lshl_add_u64 v[224:225], s[44:45], 0, v[130:131]
	s_mov_b32 m0, s50
	s_nop 0
	global_load_lds_dwordx4 v[224:225], off
	s_waitcnt vmcnt(8) lgkmcnt(0)
	s_barrier
	s_setprio 1
	v_mfma_f32_16x16x32_bf16 v[124:127], v[182:185], v[142:145], v[124:127]
	v_mfma_f32_16x16x32_bf16 v[120:123], v[182:185], v[158:161], v[120:123]
	v_mfma_f32_16x16x32_bf16 v[108:111], v[190:193], v[142:145], v[108:111]
	v_mfma_f32_16x16x32_bf16 v[104:107], v[190:193], v[158:161], v[104:107]
	v_mfma_f32_16x16x32_bf16 v[96:99], v[198:201], v[142:145], v[96:99]
	v_mfma_f32_16x16x32_bf16 v[88:91], v[198:201], v[158:161], v[88:91]
	v_mfma_f32_16x16x32_bf16 v[80:83], v[208:211], v[142:145], v[80:83]
	v_mfma_f32_16x16x32_bf16 v[72:75], v[208:211], v[158:161], v[72:75]
	v_mfma_f32_16x16x32_bf16 v[124:127], v[186:189], v[154:157], v[124:127]
	v_mfma_f32_16x16x32_bf16 v[120:123], v[186:189], v[162:165], v[120:123]
	v_mfma_f32_16x16x32_bf16 v[108:111], v[194:197], v[154:157], v[108:111]
	v_mfma_f32_16x16x32_bf16 v[104:107], v[194:197], v[162:165], v[104:107]
	v_mfma_f32_16x16x32_bf16 v[96:99], v[202:205], v[154:157], v[96:99]
	v_mfma_f32_16x16x32_bf16 v[88:91], v[202:205], v[162:165], v[88:91]
	v_mfma_f32_16x16x32_bf16 v[80:83], v[212:215], v[154:157], v[80:83]
	v_mfma_f32_16x16x32_bf16 v[72:75], v[212:215], v[162:165], v[72:75]
	s_setprio 0
	s_setprio 1
	v_mfma_f32_16x16x32_bf16 v[116:119], v[182:185], v[166:169], v[116:119]
	v_mfma_f32_16x16x32_bf16 v[112:115], v[182:185], v[174:177], v[112:115]
	v_mfma_f32_16x16x32_bf16 v[100:103], v[190:193], v[166:169], v[100:103]
	v_mfma_f32_16x16x32_bf16 v[92:95], v[190:193], v[174:177], v[92:95]
	v_mfma_f32_16x16x32_bf16 v[84:87], v[198:201], v[166:169], v[84:87]
	v_mfma_f32_16x16x32_bf16 v[76:79], v[198:201], v[174:177], v[76:79]
	v_mfma_f32_16x16x32_bf16 v[68:71], v[208:211], v[166:169], v[68:71]
	v_mfma_f32_16x16x32_bf16 v[64:67], v[208:211], v[174:177], v[64:67]
	v_mfma_f32_16x16x32_bf16 v[116:119], v[186:189], v[170:173], v[116:119]
	v_mfma_f32_16x16x32_bf16 v[112:115], v[186:189], v[178:181], v[112:115]
	v_mfma_f32_16x16x32_bf16 v[100:103], v[194:197], v[170:173], v[100:103]
	v_mfma_f32_16x16x32_bf16 v[92:95], v[194:197], v[178:181], v[92:95]
	v_mfma_f32_16x16x32_bf16 v[84:87], v[202:205], v[170:173], v[84:87]
	v_mfma_f32_16x16x32_bf16 v[76:79], v[202:205], v[178:181], v[76:79]
	v_mfma_f32_16x16x32_bf16 v[68:71], v[212:215], v[170:173], v[68:71]
	v_mfma_f32_16x16x32_bf16 v[64:67], v[212:215], v[178:181], v[64:67]
	s_setprio 0
	s_barrier
; #define PG8_STAGE(bufoff, gbase, voff) do { _Pragma("unroll") for (int _i = 0; _i < 2; ++_i) \
;         __builtin_amdgcn_global_load_lds((const unsigned*)((const char*)(gbase) + (voff)[_i]), (LAS unsigned*)(lds + (bufoff) + ldsw + _i * 8192), 16, 0, 0); } while (0)
; #define PG8_LDA(dst, b, h) do { _Pragma("unroll") for (int m = 0; m < 4; ++m) _Pragma("unroll") for (int k = 0; k < 2; ++k) dst[m][k] = *(const LAS bf16x8*)(lds + PG8_SA(b, h) + aoff + m * 2048 + k * 1024); } while (0)
; #define PG8_WAIT_V(n) asm volatile("s_waitcnt vmcnt(" #n ")" ::: "memory")
; #define PG8_WAIT_L(n) asm volatile("s_waitcnt lgkmcnt(" #n ")" ::: "memory")
; #define PG8_BAR __builtin_amdgcn_s_barrier()
; #define PG8_SCHED __builtin_amdgcn_sched_barrier(0)
; template <class Epi, class Sched, bool SWAPD = false>
; __device__ __forceinline__ void gemm_phase(LAS unsigned char* lds, const Gemm g, const Sched& S, const Epi& E) {
;     ...
;             PG8_LDA(At, 1, 1); PG8_STAGE(PG8_SB(1, 0), b3, voffB); PG8_STAGE(PG8_SB(1, 1), b3 + hstepB, voffB); PG8_STAGE(PG8_SA(1, 0), a3, voffA);
;             PG8_WAIT_V(8); PG8_WAIT_L(0); PG8_BAR; PG8_MMA(1, 0, At, B0); PG8_MMA(1, 1, At, B1); PG8_BAR; PG8_SCHED;
;         }
;         if (wr == 0) PG8_BAR;
	s_add_i32 s44, s62, s21
	v_lshl_add_u64 v[216:217], v[216:217], 0, s[12:13]
	s_mov_b32 m0, s44
	ds_read_b128 v[182:185], v153 offset:49152
	ds_read_b128 v[186:189], v153 offset:50176
	ds_read_b128 v[190:193], v153 offset:51200
	ds_read_b128 v[194:197], v153 offset:52224
	ds_read_b128 v[198:201], v153 offset:53248
	ds_read_b128 v[202:205], v153 offset:54272
	ds_read_b128 v[208:211], v153 offset:55296
	ds_read_b128 v[212:215], v153 offset:56320
	global_load_lds_dwordx4 v[216:217], off
	s_add_i32 m0, s44, 0x2000
	s_add_u32 s42, s42, 0x20080
	v_lshl_add_u64 v[216:217], v[218:219], 0, s[12:13]
	s_addc_u32 s43, s43, 0
	s_add_i32 s44, s63, s21
	global_load_lds_dwordx4 v[216:217], off
	v_lshl_add_u64 v[216:217], s[42:43], 0, v[128:129]
	s_mov_b32 m0, s44
	s_nop 0
	global_load_lds_dwordx4 v[216:217], off
	v_lshl_add_u64 v[216:217], s[42:43], 0, v[130:131]
	s_add_i32 m0, s44, 0x2000
	s_nop 0
	global_load_lds_dwordx4 v[216:217], off
	v_lshl_add_u64 v[216:217], v[220:221], 0, s[12:13]
	s_mov_b32 m0, s52
	s_nop 0
	global_load_lds_dwordx4 v[216:217], off
	v_lshl_add_u64 v[216:217], v[222:223], 0, s[12:13]
	s_mov_b32 m0, s53
	s_nop 0
	global_load_lds_dwordx4 v[216:217], off
	s_waitcnt vmcnt(8) lgkmcnt(0)
	s_barrier
	s_setprio 1
	v_mfma_f32_16x16x32_bf16 v[60:63], v[182:185], v[142:145], v[60:63]
	v_mfma_f32_16x16x32_bf16 v[56:59], v[182:185], v[158:161], v[56:59]
	v_mfma_f32_16x16x32_bf16 v[48:51], v[190:193], v[142:145], v[48:51]
	v_mfma_f32_16x16x32_bf16 v[40:43], v[190:193], v[158:161], v[40:43]
	v_mfma_f32_16x16x32_bf16 v[32:35], v[198:201], v[142:145], v[32:35]
	v_mfma_f32_16x16x32_bf16 v[24:27], v[198:201], v[158:161], v[24:27]
	v_mfma_f32_16x16x32_bf16 v[16:19], v[208:211], v[142:145], v[16:19]
	v_mfma_f32_16x16x32_bf16 v[8:11], v[208:211], v[158:161], v[8:11]
	v_mfma_f32_16x16x32_bf16 v[60:63], v[186:189], v[154:157], v[60:63]
	v_mfma_f32_16x16x32_bf16 v[56:59], v[186:189], v[162:165], v[56:59]
	v_mfma_f32_16x16x32_bf16 v[48:51], v[194:197], v[154:157], v[48:51]
	v_mfma_f32_16x16x32_bf16 v[40:43], v[194:197], v[162:165], v[40:43]
	v_mfma_f32_16x16x32_bf16 v[32:35], v[202:205], v[154:157], v[32:35]
	v_mfma_f32_16x16x32_bf16 v[24:27], v[202:205], v[162:165], v[24:27]
	v_mfma_f32_16x16x32_bf16 v[16:19], v[212:215], v[154:157], v[16:19]
	v_mfma_f32_16x16x32_bf16 v[8:11], v[212:215], v[162:165], v[8:11]
	s_setprio 0
	s_setprio 1
	v_mfma_f32_16x16x32_bf16 v[52:55], v[182:185], v[166:169], v[52:55]
	v_mfma_f32_16x16x32_bf16 v[44:47], v[182:185], v[174:177], v[44:47]
	v_mfma_f32_16x16x32_bf16 v[36:39], v[190:193], v[166:169], v[36:39]
	v_mfma_f32_16x16x32_bf16 v[28:31], v[190:193], v[174:177], v[28:31]
	v_mfma_f32_16x16x32_bf16 v[20:23], v[198:201], v[166:169], v[20:23]
	v_mfma_f32_16x16x32_bf16 v[12:15], v[198:201], v[174:177], v[12:15]
	v_mfma_f32_16x16x32_bf16 v[4:7], v[208:211], v[166:169], v[4:7]
	v_mfma_f32_16x16x32_bf16 v[0:3], v[208:211], v[174:177], v[0:3]
	v_mfma_f32_16x16x32_bf16 v[52:55], v[186:189], v[170:173], v[52:55]
	v_mfma_f32_16x16x32_bf16 v[44:47], v[186:189], v[178:181], v[44:47]
	v_mfma_f32_16x16x32_bf16 v[36:39], v[194:197], v[170:173], v[36:39]
	v_mfma_f32_16x16x32_bf16 v[28:31], v[194:197], v[178:181], v[28:31]
	v_mfma_f32_16x16x32_bf16 v[20:23], v[202:205], v[170:173], v[20:23]
	v_mfma_f32_16x16x32_bf16 v[12:15], v[202:205], v[178:181], v[12:15]
	v_mfma_f32_16x16x32_bf16 v[4:7], v[212:215], v[170:173], v[4:7]
	v_mfma_f32_16x16x32_bf16 v[0:3], v[212:215], v[178:181], v[0:3]
	s_setprio 0
	s_barrier
	s_add_i32 s61, s61, 2
	s_add_u32 s40, s40, 0x100
	s_addc_u32 s41, s41, 0
	s_add_u32 s59, s59, 0x100
	s_addc_u32 s60, s60, 0
	s_cmp_gt_u32 s61, 5
	s_cbranch_scc0 .LBB0_1531
	s_and_b64 vcc, exec, s[22:23]
	s_cbranch_vccz .LBB0_1534
	s_barrier

; #define PG8_STAGE(bufoff, gbase, voff) do { _Pragma("unroll") for (int _i = 0; _i < 2; ++_i) \
;         __builtin_amdgcn_global_load_lds((const unsigned*)((const char*)(gbase) + (voff)[_i]), (LAS unsigned*)(lds + (bufoff) + ldsw + _i * 8192), 16, 0, 0); } while (0)
; #define PG8_LDA(dst, b, h) do { _Pragma("unroll") for (int m = 0; m < 4; ++m) _Pragma("unroll") for (int k = 0; k < 2; ++k) dst[m][k] = *(const LAS bf16x8*)(lds + PG8_SA(b, h) + aoff + m * 2048 + k * 1024); } while (0)
; #define PG8_LDB(dst, b, h) do { _Pragma("unroll") for (int n = 0; n < 2; ++n) _Pragma("unroll") for (int k = 0; k < 2; ++k) dst[n][k] = *(const LAS bf16x8*)(lds + PG8_SB(b, h) + boff + n * 2048 + k * 1024); } while (0)
; #define PG8_WAIT_V(n) asm volatile("s_waitcnt vmcnt(" #n ")" ::: "memory")
; #define PG8_WAIT_L(n) asm volatile("s_waitcnt lgkmcnt(" #n ")" ::: "memory")
; #define PG8_BAR __builtin_amdgcn_s_barrier()
; #define PG8_SCHED __builtin_amdgcn_sched_barrier(0)
; template <class Epi, class Sched, bool SWAPD = false>
; __device__ __forceinline__ void gemm_phase(LAS unsigned char* lds, const Gemm g, const Sched& S, const Epi& E) {
;     ...
;             const bool last = (t == nt - 2);
;             const char* a1 = cA + (size_t)(t + 1) * kstepA;
;             const char* a2 = last ? nA : cA + (size_t)(t + 2) * kstepA; const char* b2 = last ? nB : cB + (size_t)(t + 2) * kstep;
;             const char* a3 = a2 + kstepA; const char* b3 = b2 + kstep;
;             PG8_LDB(B0, 0, 0); PG8_LDB(B1, 0, 1); PG8_SCHED; PG8_LDA(At, 0, 0); PG8_STAGE(PG8_SA(1, 1), a1 + hstepA, voffA);
;             PG8_WAIT_V(8); PG8_WAIT_L(0); PG8_BAR; PG8_MMA(0, 0, At, B0); PG8_MMA(0, 1, At, B1); PG8_BAR; PG8_SCHED;
;             PG8_LDA(At, 0, 1); PG8_STAGE(PG8_SB(0, 0), b2, voffB); PG8_STAGE(PG8_SB(0, 1), b2 + hstepB, voffB); PG8_STAGE(PG8_SA(0, 0), a2, voffA);
;             PG8_WAIT_V(8); PG8_WAIT_L(0); PG8_BAR; PG8_MMA(1, 0, At, B0); PG8_MMA(1, 1, At, B1); PG8_BAR; PG8_SCHED;
.LBB0_1661:
	ds_read_b128 v[154:157], v150
	ds_read_b128 v[158:161], v150 offset:1024
	ds_read_b128 v[162:165], v150 offset:2048
	ds_read_b128 v[166:169], v150 offset:3072
	ds_read_b128 v[170:173], v151
	ds_read_b128 v[174:177], v151 offset:1024
	ds_read_b128 v[178:181], v151 offset:2048
	ds_read_b128 v[182:185], v151 offset:3072
	s_add_u32 s46, s44, 0x100
	s_addc_u32 s47, s45, 0
	s_add_u32 s50, s75, s44
	s_addc_u32 s51, s76, s45
	s_cmp_eq_u32 s77, 4
	s_cselect_b32 s52, s74, s50
	s_cselect_b32 s50, 0, s46
	s_cselect_b32 s53, s9, s51
	s_cselect_b32 s51, 0, s47
	s_add_u32 s50, s0, s50
	s_addc_u32 s51, s1, s51
	s_mov_b32 m0, s62
	v_lshl_add_u64 v[220:221], v[144:145], 0, s[44:45]
	ds_read_b128 v[186:189], v152
	ds_read_b128 v[190:193], v152 offset:1024
	ds_read_b128 v[194:197], v152 offset:2048
	ds_read_b128 v[198:201], v152 offset:3072
	ds_read_b128 v[202:205], v152 offset:4096
	ds_read_b128 v[208:211], v152 offset:5120
	ds_read_b128 v[212:215], v152 offset:6144
	ds_read_b128 v[216:219], v152 offset:7168
	global_load_lds_dwordx4 v[220:221], off
	v_lshl_add_u64 v[220:221], v[146:147], 0, s[44:45]
	s_mov_b32 m0, s63
	s_nop 0
	global_load_lds_dwordx4 v[220:221], off
	s_waitcnt vmcnt(8) lgkmcnt(0)
	s_barrier
	s_setprio 1
	v_mfma_f32_16x16x32_bf16 v[124:127], v[154:157], v[186:189], v[124:127]
	v_mfma_f32_16x16x32_bf16 v[120:123], v[162:165], v[186:189], v[120:123]
	v_mfma_f32_16x16x32_bf16 v[112:115], v[154:157], v[194:197], v[112:115]
	v_mfma_f32_16x16x32_bf16 v[104:107], v[162:165], v[194:197], v[104:107]
	v_mfma_f32_16x16x32_bf16 v[96:99], v[154:157], v[202:205], v[96:99]
	v_mfma_f32_16x16x32_bf16 v[88:91], v[162:165], v[202:205], v[88:91]
	v_mfma_f32_16x16x32_bf16 v[80:83], v[154:157], v[212:215], v[80:83]
	v_mfma_f32_16x16x32_bf16 v[72:75], v[162:165], v[212:215], v[72:75]
	v_mfma_f32_16x16x32_bf16 v[124:127], v[158:161], v[190:193], v[124:127]
	v_mfma_f32_16x16x32_bf16 v[120:123], v[166:169], v[190:193], v[120:123]
	v_mfma_f32_16x16x32_bf16 v[112:115], v[158:161], v[198:201], v[112:115]
	v_mfma_f32_16x16x32_bf16 v[104:107], v[166:169], v[198:201], v[104:107]
	v_mfma_f32_16x16x32_bf16 v[96:99], v[158:161], v[208:211], v[96:99]
	v_mfma_f32_16x16x32_bf16 v[88:91], v[166:169], v[208:211], v[88:91]
	v_mfma_f32_16x16x32_bf16 v[80:83], v[158:161], v[216:219], v[80:83]
	v_mfma_f32_16x16x32_bf16 v[72:75], v[166:169], v[216:219], v[72:75]
	s_setprio 0
	s_setprio 1
	v_mfma_f32_16x16x32_bf16 v[116:119], v[170:173], v[186:189], v[116:119]
	v_mfma_f32_16x16x32_bf16 v[108:111], v[178:181], v[186:189], v[108:111]
	v_mfma_f32_16x16x32_bf16 v[100:103], v[170:173], v[194:197], v[100:103]
	v_mfma_f32_16x16x32_bf16 v[92:95], v[178:181], v[194:197], v[92:95]
	v_mfma_f32_16x16x32_bf16 v[84:87], v[170:173], v[202:205], v[84:87]
	v_mfma_f32_16x16x32_bf16 v[76:79], v[178:181], v[202:205], v[76:79]
	v_mfma_f32_16x16x32_bf16 v[68:71], v[170:173], v[212:215], v[68:71]
	v_mfma_f32_16x16x32_bf16 v[64:67], v[178:181], v[212:215], v[64:67]
	v_mfma_f32_16x16x32_bf16 v[116:119], v[174:177], v[190:193], v[116:119]
	v_mfma_f32_16x16x32_bf16 v[108:111], v[182:185], v[190:193], v[108:111]
	v_mfma_f32_16x16x32_bf16 v[100:103], v[174:177], v[198:201], v[100:103]
	v_mfma_f32_16x16x32_bf16 v[92:95], v[182:185], v[198:201], v[92:95]
	v_mfma_f32_16x16x32_bf16 v[84:87], v[174:177], v[208:211], v[84:87]
	v_mfma_f32_16x16x32_bf16 v[76:79], v[182:185], v[208:211], v[76:79]
	v_mfma_f32_16x16x32_bf16 v[68:71], v[174:177], v[216:219], v[68:71]
	v_mfma_f32_16x16x32_bf16 v[64:67], v[182:185], v[216:219], v[64:67]
	s_setprio 0
	s_barrier
	s_mov_b32 m0, s64
	v_lshl_add_u64 v[220:221], s[50:51], 0, v[132:133]
	s_add_u32 s44, s50, 0x20000
	ds_read_b128 v[186:189], v152 offset:16384
	ds_read_b128 v[190:193], v152 offset:17408
	ds_read_b128 v[194:197], v152 offset:18432
	ds_read_b128 v[198:201], v152 offset:19456
	ds_read_b128 v[202:205], v152 offset:20480
	ds_read_b128 v[208:211], v152 offset:21504
	ds_read_b128 v[212:215], v152 offset:22528
	ds_read_b128 v[216:219], v152 offset:23552
	global_load_lds_dwordx4 v[220:221], off
	v_lshl_add_u64 v[222:223], s[50:51], 0, v[128:129]
	s_mov_b32 m0, s65
	s_addc_u32 s45, s51, 0
	global_load_lds_dwordx4 v[222:223], off
	v_lshl_add_u64 v[224:225], s[44:45], 0, v[132:133]
	s_mov_b32 m0, s66
	v_lshl_add_u64 v[226:227], s[52:53], 0, v[130:131]
	global_load_lds_dwordx4 v[224:225], off
	v_lshl_add_u64 v[224:225], s[44:45], 0, v[128:129]
	s_mov_b32 m0, s67
	s_nop 0
	global_load_lds_dwordx4 v[224:225], off
	v_lshl_add_u64 v[224:225], s[52:53], 0, v[134:135]
	s_mov_b32 m0, s30
	s_nop 0
	global_load_lds_dwordx4 v[224:225], off
	s_mov_b32 m0, s31
	s_nop 0
	global_load_lds_dwordx4 v[226:227], off
	s_waitcnt vmcnt(8) lgkmcnt(0)
	s_barrier
; #define PG8_STAGE(bufoff, gbase, voff) do { _Pragma("unroll") for (int _i = 0; _i < 2; ++_i) \
;         __builtin_amdgcn_global_load_lds((const unsigned*)((const char*)(gbase) + (voff)[_i]), (LAS unsigned*)(lds + (bufoff) + ldsw + _i * 8192), 16, 0, 0); } while (0)
; #define PG8_LDA(dst, b, h) do { _Pragma("unroll") for (int m = 0; m < 4; ++m) _Pragma("unroll") for (int k = 0; k < 2; ++k) dst[m][k] = *(const LAS bf16x8*)(lds + PG8_SA(b, h) + aoff + m * 2048 + k * 1024); } while (0)
; #define PG8_LDB(dst, b, h) do { _Pragma("unroll") for (int n = 0; n < 2; ++n) _Pragma("unroll") for (int k = 0; k < 2; ++k) dst[n][k] = *(const LAS bf16x8*)(lds + PG8_SB(b, h) + boff + n * 2048 + k * 1024); } while (0)
; #define PG8_WAIT_V(n) asm volatile("s_waitcnt vmcnt(" #n ")" ::: "memory")
; #define PG8_WAIT_L(n) asm volatile("s_waitcnt lgkmcnt(" #n ")" ::: "memory")
; #define PG8_BAR __builtin_amdgcn_s_barrier()
; #define PG8_SCHED __builtin_amdgcn_sched_barrier(0)
; template <class Epi, class Sched, bool SWAPD = false>
; __device__ __forceinline__ void gemm_phase(LAS unsigned char* lds, const Gemm g, const Sched& S, const Epi& E) {
;     ...
;             PG8_WAIT_V(8); PG8_WAIT_L(0); PG8_BAR; PG8_MMA(1, 0, At, B0); PG8_MMA(1, 1, At, B1); PG8_BAR; PG8_SCHED;
;             PG8_LDB(B0, 1, 0); PG8_LDB(B1, 1, 1); PG8_SCHED; PG8_LDA(At, 1, 0); PG8_STAGE(PG8_SA(0, 1), a2 + hstepA, voffA);
;             PG8_WAIT_V(8); PG8_WAIT_L(0); PG8_BAR; PG8_MMA(0, 0, At, B0); PG8_MMA(0, 1, At, B1); PG8_BAR; PG8_SCHED;
	s_setprio 1
	v_mfma_f32_16x16x32_bf16 v[60:63], v[154:157], v[186:189], v[60:63]
	v_mfma_f32_16x16x32_bf16 v[56:59], v[162:165], v[186:189], v[56:59]
	v_mfma_f32_16x16x32_bf16 v[48:51], v[154:157], v[194:197], v[48:51]
	v_mfma_f32_16x16x32_bf16 v[40:43], v[162:165], v[194:197], v[40:43]
	v_mfma_f32_16x16x32_bf16 v[32:35], v[154:157], v[202:205], v[32:35]
	v_mfma_f32_16x16x32_bf16 v[24:27], v[162:165], v[202:205], v[24:27]
	v_mfma_f32_16x16x32_bf16 v[16:19], v[154:157], v[212:215], v[16:19]
	v_mfma_f32_16x16x32_bf16 v[8:11], v[162:165], v[212:215], v[8:11]
	v_mfma_f32_16x16x32_bf16 v[60:63], v[158:161], v[190:193], v[60:63]
	v_mfma_f32_16x16x32_bf16 v[56:59], v[166:169], v[190:193], v[56:59]
	v_mfma_f32_16x16x32_bf16 v[48:51], v[158:161], v[198:201], v[48:51]
	v_mfma_f32_16x16x32_bf16 v[40:43], v[166:169], v[198:201], v[40:43]
	v_mfma_f32_16x16x32_bf16 v[32:35], v[158:161], v[208:211], v[32:35]
	v_mfma_f32_16x16x32_bf16 v[24:27], v[166:169], v[208:211], v[24:27]
	v_mfma_f32_16x16x32_bf16 v[16:19], v[158:161], v[216:219], v[16:19]
	v_mfma_f32_16x16x32_bf16 v[8:11], v[166:169], v[216:219], v[8:11]
	s_setprio 0
	s_setprio 1
	v_mfma_f32_16x16x32_bf16 v[52:55], v[170:173], v[186:189], v[52:55]
	v_mfma_f32_16x16x32_bf16 v[44:47], v[178:181], v[186:189], v[44:47]
	v_mfma_f32_16x16x32_bf16 v[36:39], v[170:173], v[194:197], v[36:39]
	v_mfma_f32_16x16x32_bf16 v[28:31], v[178:181], v[194:197], v[28:31]
	v_mfma_f32_16x16x32_bf16 v[20:23], v[170:173], v[202:205], v[20:23]
	v_mfma_f32_16x16x32_bf16 v[12:15], v[178:181], v[202:205], v[12:15]
	v_mfma_f32_16x16x32_bf16 v[4:7], v[170:173], v[212:215], v[4:7]
	v_mfma_f32_16x16x32_bf16 v[0:3], v[178:181], v[212:215], v[0:3]
	v_mfma_f32_16x16x32_bf16 v[52:55], v[174:177], v[190:193], v[52:55]
	v_mfma_f32_16x16x32_bf16 v[44:47], v[182:185], v[190:193], v[44:47]
	v_mfma_f32_16x16x32_bf16 v[36:39], v[174:177], v[198:201], v[36:39]
	v_mfma_f32_16x16x32_bf16 v[28:31], v[182:185], v[198:201], v[28:31]
	v_mfma_f32_16x16x32_bf16 v[20:23], v[174:177], v[208:211], v[20:23]
	v_mfma_f32_16x16x32_bf16 v[12:15], v[182:185], v[208:211], v[12:15]
	v_mfma_f32_16x16x32_bf16 v[4:7], v[174:177], v[216:219], v[4:7]
	v_mfma_f32_16x16x32_bf16 v[0:3], v[182:185], v[216:219], v[0:3]
	s_setprio 0
	s_barrier
	s_add_i32 s78, 0, 0x18000
	v_add_u32_e32 v136, s78, v149
	s_add_i32 s79, 0, 0x1c000
	ds_read_b128 v[154:157], v136
	ds_read_b128 v[158:161], v136 offset:1024
	ds_read_b128 v[162:165], v136 offset:2048
	ds_read_b128 v[166:169], v136 offset:3072
	v_add_u32_e32 v136, s79, v149
	ds_read_b128 v[170:173], v136
	ds_read_b128 v[174:177], v136 offset:1024
	ds_read_b128 v[178:181], v136 offset:2048
	ds_read_b128 v[182:185], v136 offset:3072
	s_add_u32 s44, s52, 0x80000
	s_addc_u32 s45, s53, 0
	s_mov_b32 m0, s33
	v_lshl_add_u64 v[228:229], s[44:45], 0, v[134:135]
	ds_read_b128 v[186:189], v152 offset:32768
	ds_read_b128 v[190:193], v152 offset:33792
	ds_read_b128 v[194:197], v152 offset:34816
	ds_read_b128 v[198:201], v152 offset:35840
	ds_read_b128 v[202:205], v152 offset:36864
	ds_read_b128 v[208:211], v152 offset:37888
	ds_read_b128 v[212:215], v152 offset:38912
	ds_read_b128 v[216:219], v152 offset:39936
	global_load_lds_dwordx4 v[228:229], off
	v_lshl_add_u64 v[228:229], s[44:45], 0, v[130:131]
	s_mov_b32 m0, s54
	s_nop 0
	global_load_lds_dwordx4 v[228:229], off
	s_waitcnt vmcnt(8) lgkmcnt(0)
	s_barrier
	s_setprio 1
	v_mfma_f32_16x16x32_bf16 v[124:127], v[154:157], v[186:189], v[124:127]
	v_mfma_f32_16x16x32_bf16 v[120:123], v[162:165], v[186:189], v[120:123]
	v_mfma_f32_16x16x32_bf16 v[112:115], v[154:157], v[194:197], v[112:115]
	v_mfma_f32_16x16x32_bf16 v[104:107], v[162:165], v[194:197], v[104:107]
	v_mfma_f32_16x16x32_bf16 v[96:99], v[154:157], v[202:205], v[96:99]
	v_mfma_f32_16x16x32_bf16 v[88:91], v[162:165], v[202:205], v[88:91]
	v_mfma_f32_16x16x32_bf16 v[80:83], v[154:157], v[212:215], v[80:83]
	v_mfma_f32_16x16x32_bf16 v[72:75], v[162:165], v[212:215], v[72:75]
	v_mfma_f32_16x16x32_bf16 v[124:127], v[158:161], v[190:193], v[124:127]
	v_mfma_f32_16x16x32_bf16 v[120:123], v[166:169], v[190:193], v[120:123]
	v_mfma_f32_16x16x32_bf16 v[112:115], v[158:161], v[198:201], v[112:115]
	v_mfma_f32_16x16x32_bf16 v[104:107], v[166:169], v[198:201], v[104:107]
	v_mfma_f32_16x16x32_bf16 v[96:99], v[158:161], v[208:211], v[96:99]
	v_mfma_f32_16x16x32_bf16 v[88:91], v[166:169], v[208:211], v[88:91]
	v_mfma_f32_16x16x32_bf16 v[80:83], v[158:161], v[216:219], v[80:83]
	v_mfma_f32_16x16x32_bf16 v[72:75], v[166:169], v[216:219], v[72:75]
	s_setprio 0
	s_setprio 1
	v_mfma_f32_16x16x32_bf16 v[116:119], v[170:173], v[186:189], v[116:119]
	v_mfma_f32_16x16x32_bf16 v[108:111], v[178:181], v[186:189], v[108:111]
	v_mfma_f32_16x16x32_bf16 v[100:103], v[170:173], v[194:197], v[100:103]
	v_mfma_f32_16x16x32_bf16 v[92:95], v[178:181], v[194:197], v[92:95]
	v_mfma_f32_16x16x32_bf16 v[84:87], v[170:173], v[202:205], v[84:87]
	v_mfma_f32_16x16x32_bf16 v[76:79], v[178:181], v[202:205], v[76:79]
	v_mfma_f32_16x16x32_bf16 v[68:71], v[170:173], v[212:215], v[68:71]
	v_mfma_f32_16x16x32_bf16 v[64:67], v[178:181], v[212:215], v[64:67]
	v_mfma_f32_16x16x32_bf16 v[116:119], v[174:177], v[190:193], v[116:119]
	v_mfma_f32_16x16x32_bf16 v[108:111], v[182:185], v[190:193], v[108:111]
	v_mfma_f32_16x16x32_bf16 v[100:103], v[174:177], v[198:201], v[100:103]
	v_mfma_f32_16x16x32_bf16 v[92:95], v[182:185], v[198:201], v[92:95]
	v_mfma_f32_16x16x32_bf16 v[84:87], v[174:177], v[208:211], v[84:87]
	v_mfma_f32_16x16x32_bf16 v[76:79], v[182:185], v[208:211], v[76:79]
	v_mfma_f32_16x16x32_bf16 v[68:71], v[174:177], v[216:219], v[68:71]
	v_mfma_f32_16x16x32_bf16 v[64:67], v[182:185], v[216:219], v[64:67]
	s_setprio 0
	s_barrier
; #define PG8_STAGE(bufoff, gbase, voff) do { _Pragma("unroll") for (int _i = 0; _i < 2; ++_i) \
;         __builtin_amdgcn_global_load_lds((const unsigned*)((const char*)(gbase) + (voff)[_i]), (LAS unsigned*)(lds + (bufoff) + ldsw + _i * 8192), 16, 0, 0); } while (0)
; #define PG8_LDA(dst, b, h) do { _Pragma("unroll") for (int m = 0; m < 4; ++m) _Pragma("unroll") for (int k = 0; k < 2; ++k) dst[m][k] = *(const LAS bf16x8*)(lds + PG8_SA(b, h) + aoff + m * 2048 + k * 1024); } while (0)
; #define PG8_WAIT_V(n) asm volatile("s_waitcnt vmcnt(" #n ")" ::: "memory")
; #define PG8_WAIT_L(n) asm volatile("s_waitcnt lgkmcnt(" #n ")" ::: "memory")
; #define PG8_BAR __builtin_amdgcn_s_barrier()
; #define PG8_SCHED __builtin_amdgcn_sched_barrier(0)
; template <class Epi, class Sched, bool SWAPD = false>
; __device__ __forceinline__ void gemm_phase(LAS unsigned char* lds, const Gemm g, const Sched& S, const Epi& E) {
;     ...
;             PG8_LDA(At, 1, 1); PG8_STAGE(PG8_SB(1, 0), b3, voffB); PG8_STAGE(PG8_SB(1, 1), b3 + hstepB, voffB); PG8_STAGE(PG8_SA(1, 0), a3, voffA);
;             PG8_WAIT_V(8); PG8_WAIT_L(0); PG8_BAR; PG8_MMA(1, 0, At, B0); PG8_MMA(1, 1, At, B1); PG8_BAR; PG8_SCHED;
;         }
;         if (wr == 0) PG8_BAR;
	s_add_i32 s44, s78, s21
	v_lshl_add_u64 v[220:221], v[220:221], 0, s[24:25]
	s_mov_b32 m0, s44
	ds_read_b128 v[186:189], v152 offset:49152
	ds_read_b128 v[190:193], v152 offset:50176
	ds_read_b128 v[194:197], v152 offset:51200
	ds_read_b128 v[198:201], v152 offset:52224
	ds_read_b128 v[202:205], v152 offset:53248
	ds_read_b128 v[208:211], v152 offset:54272
	ds_read_b128 v[212:215], v152 offset:55296
	ds_read_b128 v[216:219], v152 offset:56320
	global_load_lds_dwordx4 v[220:221], off
	s_add_i32 m0, s44, 0x2000
	s_add_u32 s44, s50, 0x20080
	v_lshl_add_u64 v[220:221], v[222:223], 0, s[24:25]
	s_addc_u32 s45, s51, 0
	s_add_i32 s50, s79, s21
	global_load_lds_dwordx4 v[220:221], off
	v_lshl_add_u64 v[220:221], s[44:45], 0, v[132:133]
	s_mov_b32 m0, s50
	s_nop 0
	global_load_lds_dwordx4 v[220:221], off
	v_lshl_add_u64 v[220:221], s[44:45], 0, v[128:129]
	s_add_i32 m0, s50, 0x2000
	s_nop 0
	global_load_lds_dwordx4 v[220:221], off
	v_lshl_add_u64 v[220:221], v[224:225], 0, s[24:25]
	s_mov_b32 m0, s56
	s_nop 0
	global_load_lds_dwordx4 v[220:221], off
	v_lshl_add_u64 v[220:221], v[226:227], 0, s[24:25]
	s_mov_b32 m0, s57
	s_nop 0
	global_load_lds_dwordx4 v[220:221], off
	s_waitcnt vmcnt(8) lgkmcnt(0)
	s_barrier
	s_setprio 1
	v_mfma_f32_16x16x32_bf16 v[60:63], v[154:157], v[186:189], v[60:63]
	v_mfma_f32_16x16x32_bf16 v[56:59], v[162:165], v[186:189], v[56:59]
	v_mfma_f32_16x16x32_bf16 v[48:51], v[154:157], v[194:197], v[48:51]
	v_mfma_f32_16x16x32_bf16 v[40:43], v[162:165], v[194:197], v[40:43]
	v_mfma_f32_16x16x32_bf16 v[32:35], v[154:157], v[202:205], v[32:35]
	v_mfma_f32_16x16x32_bf16 v[24:27], v[162:165], v[202:205], v[24:27]
	v_mfma_f32_16x16x32_bf16 v[16:19], v[154:157], v[212:215], v[16:19]
	v_mfma_f32_16x16x32_bf16 v[8:11], v[162:165], v[212:215], v[8:11]
	v_mfma_f32_16x16x32_bf16 v[60:63], v[158:161], v[190:193], v[60:63]
	v_mfma_f32_16x16x32_bf16 v[56:59], v[166:169], v[190:193], v[56:59]
	v_mfma_f32_16x16x32_bf16 v[48:51], v[158:161], v[198:201], v[48:51]
	v_mfma_f32_16x16x32_bf16 v[40:43], v[166:169], v[198:201], v[40:43]
	v_mfma_f32_16x16x32_bf16 v[32:35], v[158:161], v[208:211], v[32:35]
	v_mfma_f32_16x16x32_bf16 v[24:27], v[166:169], v[208:211], v[24:27]
	v_mfma_f32_16x16x32_bf16 v[16:19], v[158:161], v[216:219], v[16:19]
	v_mfma_f32_16x16x32_bf16 v[8:11], v[166:169], v[216:219], v[8:11]
	s_setprio 0
	s_setprio 1
	v_mfma_f32_16x16x32_bf16 v[52:55], v[170:173], v[186:189], v[52:55]
	v_mfma_f32_16x16x32_bf16 v[44:47], v[178:181], v[186:189], v[44:47]
	v_mfma_f32_16x16x32_bf16 v[36:39], v[170:173], v[194:197], v[36:39]
	v_mfma_f32_16x16x32_bf16 v[28:31], v[178:181], v[194:197], v[28:31]
	v_mfma_f32_16x16x32_bf16 v[20:23], v[170:173], v[202:205], v[20:23]
	v_mfma_f32_16x16x32_bf16 v[12:15], v[178:181], v[202:205], v[12:15]
	v_mfma_f32_16x16x32_bf16 v[4:7], v[170:173], v[212:215], v[4:7]
	v_mfma_f32_16x16x32_bf16 v[0:3], v[178:181], v[212:215], v[0:3]
	v_mfma_f32_16x16x32_bf16 v[52:55], v[174:177], v[190:193], v[52:55]
	v_mfma_f32_16x16x32_bf16 v[44:47], v[182:185], v[190:193], v[44:47]
	v_mfma_f32_16x16x32_bf16 v[36:39], v[174:177], v[198:201], v[36:39]
	v_mfma_f32_16x16x32_bf16 v[28:31], v[182:185], v[198:201], v[28:31]
	v_mfma_f32_16x16x32_bf16 v[20:23], v[174:177], v[208:211], v[20:23]
	v_mfma_f32_16x16x32_bf16 v[12:15], v[182:185], v[208:211], v[12:15]
	v_mfma_f32_16x16x32_bf16 v[4:7], v[174:177], v[216:219], v[4:7]
	v_mfma_f32_16x16x32_bf16 v[0:3], v[182:185], v[216:219], v[0:3]
	s_setprio 0
	s_barrier
	s_add_i32 s77, s77, 2
	s_cmp_gt_u32 s77, 5
	s_mov_b64 s[44:45], s[46:47]
	s_cbranch_scc0 .LBB0_1661
	s_and_b64 vcc, exec, s[26:27]
	s_cbranch_vccz .LBB0_1664
	s_barrier

; #define PG8_STAGE(bufoff, gbase, voff) do { _Pragma("unroll") for (int _i = 0; _i < 2; ++_i) \
;         __builtin_amdgcn_global_load_lds((const unsigned*)((const char*)(gbase) + (voff)[_i]), (LAS unsigned*)(lds + (bufoff) + ldsw + _i * 8192), 16, 0, 0); } while (0)
; #define PG8_LDA(dst, b, h) do { _Pragma("unroll") for (int m = 0; m < 4; ++m) _Pragma("unroll") for (int k = 0; k < 2; ++k) dst[m][k] = *(const LAS bf16x8*)(lds + PG8_SA(b, h) + aoff + m * 2048 + k * 1024); } while (0)
; #define PG8_LDB(dst, b, h) do { _Pragma("unroll") for (int n = 0; n < 2; ++n) _Pragma("unroll") for (int k = 0; k < 2; ++k) dst[n][k] = *(const LAS bf16x8*)(lds + PG8_SB(b, h) + boff + n * 2048 + k * 1024); } while (0)
; #define PG8_WAIT_V(n) asm volatile("s_waitcnt vmcnt(" #n ")" ::: "memory")
; #define PG8_WAIT_L(n) asm volatile("s_waitcnt lgkmcnt(" #n ")" ::: "memory")
; #define PG8_BAR __builtin_amdgcn_s_barrier()
; #define PG8_SCHED __builtin_amdgcn_sched_barrier(0)
; template <class Epi, class Sched, bool SWAPD = false>
; __device__ __forceinline__ void gemm_phase(LAS unsigned char* lds, const Gemm g, const Sched& S, const Epi& E) {
;     ...
;             const bool last = (t == nt - 2);
;             const char* a1 = cA + (size_t)(t + 1) * kstepA;
;             const char* a2 = last ? nA : cA + (size_t)(t + 2) * kstepA; const char* b2 = last ? nB : cB + (size_t)(t + 2) * kstep;
;             const char* a3 = a2 + kstepA; const char* b3 = b2 + kstep;
;             PG8_LDB(B0, 0, 0); PG8_LDB(B1, 0, 1); PG8_SCHED; PG8_LDA(At, 0, 0); PG8_STAGE(PG8_SA(1, 1), a1 + hstepA, voffA);
;             PG8_WAIT_V(8); PG8_WAIT_L(0); PG8_BAR; PG8_MMA(0, 0, At, B0); PG8_MMA(0, 1, At, B1); PG8_BAR; PG8_SCHED;
;             PG8_LDA(At, 0, 1); PG8_STAGE(PG8_SB(0, 0), b2, voffB); PG8_STAGE(PG8_SB(0, 1), b2 + hstepB, voffB); PG8_STAGE(PG8_SA(0, 0), a2, voffA);
;             PG8_WAIT_V(8); PG8_WAIT_L(0); PG8_BAR; PG8_MMA(1, 0, At, B0); PG8_MMA(1, 1, At, B1); PG8_BAR; PG8_SCHED;
.LBB0_1737:
	ds_read_b128 v[104:107], v176
	ds_read_b128 v[108:111], v176 offset:1024
	ds_read_b128 v[124:127], v176 offset:2048
	ds_read_b128 v[128:131], v176 offset:3072
	ds_read_b128 v[180:183], v177
	ds_read_b128 v[184:187], v177 offset:1024
	ds_read_b128 v[188:191], v177 offset:2048
	ds_read_b128 v[192:195], v177 offset:3072
	s_add_u32 s42, s40, 0xfffc0080
	s_addc_u32 s43, s41, -1
	s_cmp_eq_u32 s60, 12
	s_cselect_b32 s45, s23, s43
	s_cselect_b32 s44, s25, s42
	s_cselect_b32 s43, s56, s59
	s_cselect_b32 s42, s57, s58
	v_lshl_add_u64 v[172:173], s[40:41], 0, v[164:165]
	s_add_i32 m0, s30, 0xc000
	ds_read_b128 v[196:199], v178
	ds_read_b128 v[200:203], v178 offset:1024
	ds_read_b128 v[208:211], v178 offset:2048
	ds_read_b128 v[212:215], v178 offset:3072
	ds_read_b128 v[216:219], v178 offset:4096
	ds_read_b128 v[220:223], v178 offset:5120
	ds_read_b128 v[224:227], v178 offset:6144
	ds_read_b128 v[228:231], v178 offset:7168
	global_load_lds_dwordx4 v[172:173], off
	v_lshl_add_u64 v[172:173], s[40:41], 0, v[166:167]
	s_add_i32 m0, s30, 0xe000
	s_nop 0
	global_load_lds_dwordx4 v[172:173], off
	s_waitcnt vmcnt(8) lgkmcnt(0)
	s_barrier
	s_setprio 1
	v_mfma_f32_16x16x32_bf16 v[140:143], v[104:107], v[196:199], v[140:143]
	v_mfma_f32_16x16x32_bf16 v[136:139], v[124:127], v[196:199], v[136:139]
	v_mfma_f32_16x16x32_bf16 v[116:119], v[104:107], v[208:211], v[116:119]
	v_mfma_f32_16x16x32_bf16 v[112:115], v[124:127], v[208:211], v[112:115]
	v_mfma_f32_16x16x32_bf16 v[92:95], v[104:107], v[216:219], v[92:95]
	v_mfma_f32_16x16x32_bf16 v[88:91], v[124:127], v[216:219], v[88:91]
	v_mfma_f32_16x16x32_bf16 v[76:79], v[104:107], v[224:227], v[76:79]
	v_mfma_f32_16x16x32_bf16 v[72:75], v[124:127], v[224:227], v[72:75]
	v_mfma_f32_16x16x32_bf16 v[140:143], v[108:111], v[200:203], v[140:143]
	v_mfma_f32_16x16x32_bf16 v[136:139], v[128:131], v[200:203], v[136:139]
	v_mfma_f32_16x16x32_bf16 v[116:119], v[108:111], v[212:215], v[116:119]
	v_mfma_f32_16x16x32_bf16 v[112:115], v[128:131], v[212:215], v[112:115]
	v_mfma_f32_16x16x32_bf16 v[92:95], v[108:111], v[220:223], v[92:95]
	v_mfma_f32_16x16x32_bf16 v[88:91], v[128:131], v[220:223], v[88:91]
	v_mfma_f32_16x16x32_bf16 v[76:79], v[108:111], v[228:231], v[76:79]
	v_mfma_f32_16x16x32_bf16 v[72:75], v[128:131], v[228:231], v[72:75]
	s_setprio 0
	s_setprio 1
	v_mfma_f32_16x16x32_bf16 v[132:135], v[180:183], v[196:199], v[132:135]
	v_mfma_f32_16x16x32_bf16 v[120:123], v[188:191], v[196:199], v[120:123]
	v_mfma_f32_16x16x32_bf16 v[100:103], v[180:183], v[208:211], v[100:103]
	v_mfma_f32_16x16x32_bf16 v[96:99], v[188:191], v[208:211], v[96:99]
	v_mfma_f32_16x16x32_bf16 v[84:87], v[180:183], v[216:219], v[84:87]
	v_mfma_f32_16x16x32_bf16 v[80:83], v[188:191], v[216:219], v[80:83]
	v_mfma_f32_16x16x32_bf16 v[68:71], v[180:183], v[224:227], v[68:71]
	v_mfma_f32_16x16x32_bf16 v[64:67], v[188:191], v[224:227], v[64:67]
	v_mfma_f32_16x16x32_bf16 v[132:135], v[184:187], v[200:203], v[132:135]
	v_mfma_f32_16x16x32_bf16 v[120:123], v[192:195], v[200:203], v[120:123]
	v_mfma_f32_16x16x32_bf16 v[100:103], v[184:187], v[212:215], v[100:103]
	v_mfma_f32_16x16x32_bf16 v[96:99], v[192:195], v[212:215], v[96:99]
	v_mfma_f32_16x16x32_bf16 v[84:87], v[184:187], v[220:223], v[84:87]
	v_mfma_f32_16x16x32_bf16 v[80:83], v[192:195], v[220:223], v[80:83]
	v_mfma_f32_16x16x32_bf16 v[68:71], v[184:187], v[228:231], v[68:71]
	v_mfma_f32_16x16x32_bf16 v[64:67], v[192:195], v[228:231], v[64:67]
	s_setprio 0
	s_barrier
	s_add_i32 s61, s54, s21
	v_lshl_add_u64 v[172:173], s[42:43], 0, v[144:145]
	s_mov_b32 m0, s61
	ds_read_b128 v[196:199], v178 offset:16384
	ds_read_b128 v[200:203], v178 offset:17408
	ds_read_b128 v[208:211], v178 offset:18432
	ds_read_b128 v[212:215], v178 offset:19456
	ds_read_b128 v[216:219], v178 offset:20480
	ds_read_b128 v[220:223], v178 offset:21504
	ds_read_b128 v[224:227], v178 offset:22528
	ds_read_b128 v[228:231], v178 offset:23552
	global_load_lds_dwordx4 v[172:173], off
	s_add_i32 m0, s61, 0x2000
	s_add_u32 s62, s42, 0x40000
	v_lshl_add_u64 v[204:205], s[42:43], 0, v[146:147]
	s_addc_u32 s63, s43, 0
	s_add_i32 s61, s55, s21
	global_load_lds_dwordx4 v[204:205], off
	v_lshl_add_u64 v[232:233], s[62:63], 0, v[144:145]
	s_mov_b32 m0, s61
	v_lshl_add_u64 v[234:235], s[44:45], 0, v[146:147]
	global_load_lds_dwordx4 v[232:233], off
	v_lshl_add_u64 v[232:233], s[62:63], 0, v[146:147]
	s_add_i32 m0, s61, 0x2000
	s_nop 0
	global_load_lds_dwordx4 v[232:233], off
	v_lshl_add_u64 v[232:233], s[44:45], 0, v[144:145]
	s_mov_b32 m0, s30
	s_nop 0
	global_load_lds_dwordx4 v[232:233], off
	s_mov_b32 m0, s31
	s_nop 0
	global_load_lds_dwordx4 v[234:235], off
	s_waitcnt vmcnt(8) lgkmcnt(0)
	s_barrier
; #define PG8_STAGE(bufoff, gbase, voff) do { _Pragma("unroll") for (int _i = 0; _i < 2; ++_i) \
;         __builtin_amdgcn_global_load_lds((const unsigned*)((const char*)(gbase) + (voff)[_i]), (LAS unsigned*)(lds + (bufoff) + ldsw + _i * 8192), 16, 0, 0); } while (0)
; #define PG8_LDA(dst, b, h) do { _Pragma("unroll") for (int m = 0; m < 4; ++m) _Pragma("unroll") for (int k = 0; k < 2; ++k) dst[m][k] = *(const LAS bf16x8*)(lds + PG8_SA(b, h) + aoff + m * 2048 + k * 1024); } while (0)
; #define PG8_LDB(dst, b, h) do { _Pragma("unroll") for (int n = 0; n < 2; ++n) _Pragma("unroll") for (int k = 0; k < 2; ++k) dst[n][k] = *(const LAS bf16x8*)(lds + PG8_SB(b, h) + boff + n * 2048 + k * 1024); } while (0)
; #define PG8_WAIT_V(n) asm volatile("s_waitcnt vmcnt(" #n ")" ::: "memory")
; #define PG8_WAIT_L(n) asm volatile("s_waitcnt lgkmcnt(" #n ")" ::: "memory")
; #define PG8_BAR __builtin_amdgcn_s_barrier()
; #define PG8_SCHED __builtin_amdgcn_sched_barrier(0)
; template <class Epi, class Sched, bool SWAPD = false>
; __device__ __forceinline__ void gemm_phase(LAS unsigned char* lds, const Gemm g, const Sched& S, const Epi& E) {
;     ...
;             PG8_WAIT_V(8); PG8_WAIT_L(0); PG8_BAR; PG8_MMA(1, 0, At, B0); PG8_MMA(1, 1, At, B1); PG8_BAR; PG8_SCHED;
;             PG8_LDB(B0, 1, 0); PG8_LDB(B1, 1, 1); PG8_SCHED; PG8_LDA(At, 1, 0); PG8_STAGE(PG8_SA(0, 1), a2 + hstepA, voffA);
;             PG8_WAIT_V(8); PG8_WAIT_L(0); PG8_BAR; PG8_MMA(0, 0, At, B0); PG8_MMA(0, 1, At, B1); PG8_BAR; PG8_SCHED;
	s_setprio 1
	v_mfma_f32_16x16x32_bf16 v[60:63], v[104:107], v[196:199], v[60:63]
	v_mfma_f32_16x16x32_bf16 v[56:59], v[124:127], v[196:199], v[56:59]
	v_mfma_f32_16x16x32_bf16 v[44:47], v[104:107], v[208:211], v[44:47]
	v_mfma_f32_16x16x32_bf16 v[40:43], v[124:127], v[208:211], v[40:43]
	v_mfma_f32_16x16x32_bf16 v[28:31], v[104:107], v[216:219], v[28:31]
	v_mfma_f32_16x16x32_bf16 v[24:27], v[124:127], v[216:219], v[24:27]
	v_mfma_f32_16x16x32_bf16 v[12:15], v[104:107], v[224:227], v[12:15]
	v_mfma_f32_16x16x32_bf16 v[8:11], v[124:127], v[224:227], v[8:11]
	v_mfma_f32_16x16x32_bf16 v[60:63], v[108:111], v[200:203], v[60:63]
	v_mfma_f32_16x16x32_bf16 v[56:59], v[128:131], v[200:203], v[56:59]
	v_mfma_f32_16x16x32_bf16 v[44:47], v[108:111], v[212:215], v[44:47]
	v_mfma_f32_16x16x32_bf16 v[40:43], v[128:131], v[212:215], v[40:43]
	v_mfma_f32_16x16x32_bf16 v[28:31], v[108:111], v[220:223], v[28:31]
	v_mfma_f32_16x16x32_bf16 v[24:27], v[128:131], v[220:223], v[24:27]
	v_mfma_f32_16x16x32_bf16 v[12:15], v[108:111], v[228:231], v[12:15]
	v_mfma_f32_16x16x32_bf16 v[8:11], v[128:131], v[228:231], v[8:11]
	s_setprio 0
	s_setprio 1
	v_mfma_f32_16x16x32_bf16 v[52:55], v[180:183], v[196:199], v[52:55]
	v_mfma_f32_16x16x32_bf16 v[48:51], v[188:191], v[196:199], v[48:51]
	v_mfma_f32_16x16x32_bf16 v[36:39], v[180:183], v[208:211], v[36:39]
	v_mfma_f32_16x16x32_bf16 v[32:35], v[188:191], v[208:211], v[32:35]
	v_mfma_f32_16x16x32_bf16 v[20:23], v[180:183], v[216:219], v[20:23]
	v_mfma_f32_16x16x32_bf16 v[16:19], v[188:191], v[216:219], v[16:19]
	v_mfma_f32_16x16x32_bf16 v[4:7], v[180:183], v[224:227], v[4:7]
	v_mfma_f32_16x16x32_bf16 v[0:3], v[188:191], v[224:227], v[0:3]
	v_mfma_f32_16x16x32_bf16 v[52:55], v[184:187], v[200:203], v[52:55]
	v_mfma_f32_16x16x32_bf16 v[48:51], v[192:195], v[200:203], v[48:51]
	v_mfma_f32_16x16x32_bf16 v[36:39], v[184:187], v[212:215], v[36:39]
	v_mfma_f32_16x16x32_bf16 v[32:35], v[192:195], v[212:215], v[32:35]
	v_mfma_f32_16x16x32_bf16 v[20:23], v[184:187], v[220:223], v[20:23]
	v_mfma_f32_16x16x32_bf16 v[16:19], v[192:195], v[220:223], v[16:19]
	v_mfma_f32_16x16x32_bf16 v[4:7], v[184:187], v[228:231], v[4:7]
	v_mfma_f32_16x16x32_bf16 v[0:3], v[192:195], v[228:231], v[0:3]
	s_setprio 0
	s_barrier
	s_add_i32 s61, 0, 0x18000
	s_add_i32 s62, 0, 0x1c000
	v_add_u32_e32 v128, s61, v174
	v_add_u32_e32 v179, s62, v174
	ds_read_b128 v[104:107], v128
	ds_read_b128 v[108:111], v128 offset:1024
	ds_read_b128 v[124:127], v128 offset:2048
	ds_read_b128 v[128:131], v128 offset:3072
	ds_read_b128 v[180:183], v179
	ds_read_b128 v[184:187], v179 offset:1024
	ds_read_b128 v[188:191], v179 offset:2048
	ds_read_b128 v[192:195], v179 offset:3072
	s_add_u32 s44, s44, 0x40000
	s_addc_u32 s45, s45, 0
	s_mov_b32 m0, s33
	v_lshl_add_u64 v[236:237], s[44:45], 0, v[144:145]
	ds_read_b128 v[196:199], v178 offset:32768
	ds_read_b128 v[200:203], v178 offset:33792
	ds_read_b128 v[208:211], v178 offset:34816
	ds_read_b128 v[212:215], v178 offset:35840
	ds_read_b128 v[216:219], v178 offset:36864
	ds_read_b128 v[220:223], v178 offset:37888
	ds_read_b128 v[224:227], v178 offset:38912
	ds_read_b128 v[228:231], v178 offset:39936
	global_load_lds_dwordx4 v[236:237], off
	v_lshl_add_u64 v[236:237], s[44:45], 0, v[146:147]
	s_mov_b32 m0, s46
	s_nop 0
	global_load_lds_dwordx4 v[236:237], off
	s_waitcnt vmcnt(8) lgkmcnt(0)
	s_barrier
	s_setprio 1
	v_mfma_f32_16x16x32_bf16 v[140:143], v[104:107], v[196:199], v[140:143]
	v_mfma_f32_16x16x32_bf16 v[136:139], v[124:127], v[196:199], v[136:139]
	v_mfma_f32_16x16x32_bf16 v[116:119], v[104:107], v[208:211], v[116:119]
	v_mfma_f32_16x16x32_bf16 v[112:115], v[124:127], v[208:211], v[112:115]
	v_mfma_f32_16x16x32_bf16 v[92:95], v[104:107], v[216:219], v[92:95]
	v_mfma_f32_16x16x32_bf16 v[88:91], v[124:127], v[216:219], v[88:91]
	v_mfma_f32_16x16x32_bf16 v[76:79], v[104:107], v[224:227], v[76:79]
	v_mfma_f32_16x16x32_bf16 v[72:75], v[124:127], v[224:227], v[72:75]
	v_mfma_f32_16x16x32_bf16 v[140:143], v[108:111], v[200:203], v[140:143]
	v_mfma_f32_16x16x32_bf16 v[136:139], v[128:131], v[200:203], v[136:139]
	v_mfma_f32_16x16x32_bf16 v[116:119], v[108:111], v[212:215], v[116:119]
	v_mfma_f32_16x16x32_bf16 v[112:115], v[128:131], v[212:215], v[112:115]
	v_mfma_f32_16x16x32_bf16 v[92:95], v[108:111], v[220:223], v[92:95]
	v_mfma_f32_16x16x32_bf16 v[88:91], v[128:131], v[220:223], v[88:91]
	v_mfma_f32_16x16x32_bf16 v[76:79], v[108:111], v[228:231], v[76:79]
	v_mfma_f32_16x16x32_bf16 v[72:75], v[128:131], v[228:231], v[72:75]
	s_setprio 0
	s_setprio 1
	v_mfma_f32_16x16x32_bf16 v[132:135], v[180:183], v[196:199], v[132:135]
	v_mfma_f32_16x16x32_bf16 v[120:123], v[188:191], v[196:199], v[120:123]
	v_mfma_f32_16x16x32_bf16 v[100:103], v[180:183], v[208:211], v[100:103]
	v_mfma_f32_16x16x32_bf16 v[96:99], v[188:191], v[208:211], v[96:99]
	v_mfma_f32_16x16x32_bf16 v[84:87], v[180:183], v[216:219], v[84:87]
	v_mfma_f32_16x16x32_bf16 v[80:83], v[188:191], v[216:219], v[80:83]
	v_mfma_f32_16x16x32_bf16 v[68:71], v[180:183], v[224:227], v[68:71]
	v_mfma_f32_16x16x32_bf16 v[64:67], v[188:191], v[224:227], v[64:67]
	v_mfma_f32_16x16x32_bf16 v[132:135], v[184:187], v[200:203], v[132:135]
	v_mfma_f32_16x16x32_bf16 v[120:123], v[192:195], v[200:203], v[120:123]
	v_mfma_f32_16x16x32_bf16 v[100:103], v[184:187], v[212:215], v[100:103]
	v_mfma_f32_16x16x32_bf16 v[96:99], v[192:195], v[212:215], v[96:99]
	v_mfma_f32_16x16x32_bf16 v[84:87], v[184:187], v[220:223], v[84:87]
	v_mfma_f32_16x16x32_bf16 v[80:83], v[192:195], v[220:223], v[80:83]
	v_mfma_f32_16x16x32_bf16 v[68:71], v[184:187], v[228:231], v[68:71]
	v_mfma_f32_16x16x32_bf16 v[64:67], v[192:195], v[228:231], v[64:67]
	s_setprio 0
	s_barrier
; #define PG8_STAGE(bufoff, gbase, voff) do { _Pragma("unroll") for (int _i = 0; _i < 2; ++_i) \
;         __builtin_amdgcn_global_load_lds((const unsigned*)((const char*)(gbase) + (voff)[_i]), (LAS unsigned*)(lds + (bufoff) + ldsw + _i * 8192), 16, 0, 0); } while (0)
; #define PG8_LDA(dst, b, h) do { _Pragma("unroll") for (int m = 0; m < 4; ++m) _Pragma("unroll") for (int k = 0; k < 2; ++k) dst[m][k] = *(const LAS bf16x8*)(lds + PG8_SA(b, h) + aoff + m * 2048 + k * 1024); } while (0)
; #define PG8_WAIT_V(n) asm volatile("s_waitcnt vmcnt(" #n ")" ::: "memory")
; #define PG8_WAIT_L(n) asm volatile("s_waitcnt lgkmcnt(" #n ")" ::: "memory")
; #define PG8_BAR __builtin_amdgcn_s_barrier()
; #define PG8_SCHED __builtin_amdgcn_sched_barrier(0)
; template <class Epi, class Sched, bool SWAPD = false>
; __device__ __forceinline__ void gemm_phase(LAS unsigned char* lds, const Gemm g, const Sched& S, const Epi& E) {
;     ...
;             PG8_LDA(At, 1, 1); PG8_STAGE(PG8_SB(1, 0), b3, voffB); PG8_STAGE(PG8_SB(1, 1), b3 + hstepB, voffB); PG8_STAGE(PG8_SA(1, 0), a3, voffA);
;             PG8_WAIT_V(8); PG8_WAIT_L(0); PG8_BAR; PG8_MMA(1, 0, At, B0); PG8_MMA(1, 1, At, B1); PG8_BAR; PG8_SCHED;
;         }
;         if (wr == 0) PG8_BAR;
	s_add_i32 s44, s61, s21
	v_lshl_add_u64 v[172:173], v[172:173], 0, s[8:9]
	s_mov_b32 m0, s44
	ds_read_b128 v[196:199], v178 offset:49152
	ds_read_b128 v[200:203], v178 offset:50176
	ds_read_b128 v[208:211], v178 offset:51200
	ds_read_b128 v[212:215], v178 offset:52224
	ds_read_b128 v[216:219], v178 offset:53248
	ds_read_b128 v[220:223], v178 offset:54272
	ds_read_b128 v[224:227], v178 offset:55296
	ds_read_b128 v[228:231], v178 offset:56320
	global_load_lds_dwordx4 v[172:173], off
	s_add_i32 m0, s44, 0x2000
	s_add_u32 s42, s42, 0x40080
	v_lshl_add_u64 v[172:173], v[204:205], 0, s[8:9]
	s_addc_u32 s43, s43, 0
	s_add_i32 s44, s62, s21
	global_load_lds_dwordx4 v[172:173], off
	v_lshl_add_u64 v[172:173], s[42:43], 0, v[144:145]
	s_mov_b32 m0, s44
	s_nop 0
	global_load_lds_dwordx4 v[172:173], off
	v_lshl_add_u64 v[172:173], s[42:43], 0, v[146:147]
	s_add_i32 m0, s44, 0x2000
	s_nop 0
	global_load_lds_dwordx4 v[172:173], off
	v_lshl_add_u64 v[172:173], v[232:233], 0, s[8:9]
	s_mov_b32 m0, s52
	s_nop 0
	global_load_lds_dwordx4 v[172:173], off
	v_lshl_add_u64 v[172:173], v[234:235], 0, s[8:9]
	s_mov_b32 m0, s53
	s_nop 0
	global_load_lds_dwordx4 v[172:173], off
	s_waitcnt vmcnt(8) lgkmcnt(0)
	s_barrier
	s_setprio 1
	v_mfma_f32_16x16x32_bf16 v[60:63], v[104:107], v[196:199], v[60:63]
	v_mfma_f32_16x16x32_bf16 v[56:59], v[124:127], v[196:199], v[56:59]
	v_mfma_f32_16x16x32_bf16 v[44:47], v[104:107], v[208:211], v[44:47]
	v_mfma_f32_16x16x32_bf16 v[40:43], v[124:127], v[208:211], v[40:43]
	v_mfma_f32_16x16x32_bf16 v[28:31], v[104:107], v[216:219], v[28:31]
	v_mfma_f32_16x16x32_bf16 v[24:27], v[124:127], v[216:219], v[24:27]
	v_mfma_f32_16x16x32_bf16 v[12:15], v[104:107], v[224:227], v[12:15]
	v_mfma_f32_16x16x32_bf16 v[8:11], v[124:127], v[224:227], v[8:11]
	v_mfma_f32_16x16x32_bf16 v[60:63], v[108:111], v[200:203], v[60:63]
	v_mfma_f32_16x16x32_bf16 v[56:59], v[128:131], v[200:203], v[56:59]
	v_mfma_f32_16x16x32_bf16 v[44:47], v[108:111], v[212:215], v[44:47]
	v_mfma_f32_16x16x32_bf16 v[40:43], v[128:131], v[212:215], v[40:43]
	v_mfma_f32_16x16x32_bf16 v[28:31], v[108:111], v[220:223], v[28:31]
	v_mfma_f32_16x16x32_bf16 v[24:27], v[128:131], v[220:223], v[24:27]
	v_mfma_f32_16x16x32_bf16 v[12:15], v[108:111], v[228:231], v[12:15]
	v_mfma_f32_16x16x32_bf16 v[8:11], v[128:131], v[228:231], v[8:11]
	s_setprio 0
	s_setprio 1
	v_mfma_f32_16x16x32_bf16 v[52:55], v[180:183], v[196:199], v[52:55]
	v_mfma_f32_16x16x32_bf16 v[48:51], v[188:191], v[196:199], v[48:51]
	v_mfma_f32_16x16x32_bf16 v[36:39], v[180:183], v[208:211], v[36:39]
	v_mfma_f32_16x16x32_bf16 v[32:35], v[188:191], v[208:211], v[32:35]
	v_mfma_f32_16x16x32_bf16 v[20:23], v[180:183], v[216:219], v[20:23]
	v_mfma_f32_16x16x32_bf16 v[16:19], v[188:191], v[216:219], v[16:19]
	v_mfma_f32_16x16x32_bf16 v[4:7], v[180:183], v[224:227], v[4:7]
	v_mfma_f32_16x16x32_bf16 v[0:3], v[188:191], v[224:227], v[0:3]
	v_mfma_f32_16x16x32_bf16 v[52:55], v[184:187], v[200:203], v[52:55]
	v_mfma_f32_16x16x32_bf16 v[48:51], v[192:195], v[200:203], v[48:51]
	v_mfma_f32_16x16x32_bf16 v[36:39], v[184:187], v[212:215], v[36:39]
	v_mfma_f32_16x16x32_bf16 v[32:35], v[192:195], v[212:215], v[32:35]
	v_mfma_f32_16x16x32_bf16 v[20:23], v[184:187], v[220:223], v[20:23]
	v_mfma_f32_16x16x32_bf16 v[16:19], v[192:195], v[220:223], v[16:19]
	v_mfma_f32_16x16x32_bf16 v[4:7], v[184:187], v[228:231], v[4:7]
	v_mfma_f32_16x16x32_bf16 v[0:3], v[192:195], v[228:231], v[0:3]
	s_setprio 0
	s_barrier
	s_add_i32 s60, s60, 2
	s_add_u32 s40, s40, 0x100
	s_addc_u32 s41, s41, 0
	s_add_u32 s58, s58, 0x100
	s_addc_u32 s59, s59, 0
	s_cmp_gt_u32 s60, 13
	s_cbranch_scc0 .LBB0_1737
	s_and_b64 vcc, exec, s[12:13]
	s_cbranch_vccz .LBB0_1740
	s_barrier

; #define PG8_STAGE(bufoff, gbase, voff) do { _Pragma("unroll") for (int _i = 0; _i < 2; ++_i) \
;         __builtin_amdgcn_global_load_lds((const unsigned*)((const char*)(gbase) + (voff)[_i]), (LAS unsigned*)(lds + (bufoff) + ldsw + _i * 8192), 16, 0, 0); } while (0)
; #define PG8_LDA(dst, b, h) do { _Pragma("unroll") for (int m = 0; m < 4; ++m) _Pragma("unroll") for (int k = 0; k < 2; ++k) dst[m][k] = *(const LAS bf16x8*)(lds + PG8_SA(b, h) + aoff + m * 2048 + k * 1024); } while (0)
; #define PG8_LDB(dst, b, h) do { _Pragma("unroll") for (int n = 0; n < 2; ++n) _Pragma("unroll") for (int k = 0; k < 2; ++k) dst[n][k] = *(const LAS bf16x8*)(lds + PG8_SB(b, h) + boff + n * 2048 + k * 1024); } while (0)
; #define PG8_WAIT_V(n) asm volatile("s_waitcnt vmcnt(" #n ")" ::: "memory")
; #define PG8_WAIT_L(n) asm volatile("s_waitcnt lgkmcnt(" #n ")" ::: "memory")
; #define PG8_BAR __builtin_amdgcn_s_barrier()
; #define PG8_SCHED __builtin_amdgcn_sched_barrier(0)
; template <class Epi, class Sched, bool SWAPD = false>
; __device__ __forceinline__ void gemm_phase(LAS unsigned char* lds, const Gemm g, const Sched& S, const Epi& E) {
;     ...
;             const bool last = (t == nt - 2);
;             const char* a1 = cA + (size_t)(t + 1) * kstepA;
;             const char* a2 = last ? nA : cA + (size_t)(t + 2) * kstepA; const char* b2 = last ? nB : cB + (size_t)(t + 2) * kstep;
;             const char* a3 = a2 + kstepA; const char* b3 = b2 + kstep;
;             PG8_LDB(B0, 0, 0); PG8_LDB(B1, 0, 1); PG8_SCHED; PG8_LDA(At, 0, 0); PG8_STAGE(PG8_SA(1, 1), a1 + hstepA, voffA);
;             PG8_WAIT_V(8); PG8_WAIT_L(0); PG8_BAR; PG8_MMA(0, 0, At, B0); PG8_MMA(0, 1, At, B1); PG8_BAR; PG8_SCHED;
;             PG8_LDA(At, 0, 1); PG8_STAGE(PG8_SB(0, 0), b2, voffB); PG8_STAGE(PG8_SB(0, 1), b2 + hstepB, voffB); PG8_STAGE(PG8_SA(0, 0), a2, voffA);
;             PG8_WAIT_V(8); PG8_WAIT_L(0); PG8_BAR; PG8_MMA(1, 0, At, B0); PG8_MMA(1, 1, At, B1); PG8_BAR; PG8_SCHED;
.LBB0_1863:
	ds_read_b128 v[148:151], v145
	ds_read_b128 v[152:155], v145 offset:1024
	ds_read_b128 v[156:159], v145 offset:2048
	ds_read_b128 v[160:163], v145 offset:3072
	ds_read_b128 v[164:167], v146
	ds_read_b128 v[168:171], v146 offset:1024
	ds_read_b128 v[172:175], v146 offset:2048
	ds_read_b128 v[176:179], v146 offset:3072
	s_add_u32 s38, s36, 0xfffc0080
	s_addc_u32 s39, s37, -1
	s_cmp_eq_u32 s58, 12
	s_cselect_b32 s41, s21, s39
	s_cselect_b32 s40, s23, s38
	s_cselect_b32 s39, s54, s57
	s_cselect_b32 s38, s55, s56
	v_lshl_add_u64 v[140:141], s[36:37], 0, v[132:133]
	s_add_i32 m0, s35, 0xc000
	ds_read_b128 v[180:183], v147
	ds_read_b128 v[184:187], v147 offset:1024
	ds_read_b128 v[188:191], v147 offset:2048
	ds_read_b128 v[192:195], v147 offset:3072
	ds_read_b128 v[196:199], v147 offset:4096
	ds_read_b128 v[200:203], v147 offset:5120
	ds_read_b128 v[208:211], v147 offset:6144
	ds_read_b128 v[212:215], v147 offset:7168
	global_load_lds_dwordx4 v[140:141], off
	v_lshl_add_u64 v[140:141], s[36:37], 0, v[134:135]
	s_add_i32 m0, s35, 0xe000
	s_nop 0
	global_load_lds_dwordx4 v[140:141], off
	s_waitcnt vmcnt(8) lgkmcnt(0)
	s_barrier
	s_setprio 1
	v_mfma_f32_16x16x32_bf16 v[124:127], v[148:151], v[180:183], v[124:127]
	v_mfma_f32_16x16x32_bf16 v[116:119], v[156:159], v[180:183], v[116:119]
	v_mfma_f32_16x16x32_bf16 v[108:111], v[148:151], v[188:191], v[108:111]
	v_mfma_f32_16x16x32_bf16 v[100:103], v[156:159], v[188:191], v[100:103]
	v_mfma_f32_16x16x32_bf16 v[92:95], v[148:151], v[196:199], v[92:95]
	v_mfma_f32_16x16x32_bf16 v[84:87], v[156:159], v[196:199], v[84:87]
	v_mfma_f32_16x16x32_bf16 v[76:79], v[148:151], v[208:211], v[76:79]
	v_mfma_f32_16x16x32_bf16 v[68:71], v[156:159], v[208:211], v[68:71]
	v_mfma_f32_16x16x32_bf16 v[124:127], v[152:155], v[184:187], v[124:127]
	v_mfma_f32_16x16x32_bf16 v[116:119], v[160:163], v[184:187], v[116:119]
	v_mfma_f32_16x16x32_bf16 v[108:111], v[152:155], v[192:195], v[108:111]
	v_mfma_f32_16x16x32_bf16 v[100:103], v[160:163], v[192:195], v[100:103]
	v_mfma_f32_16x16x32_bf16 v[92:95], v[152:155], v[200:203], v[92:95]
	v_mfma_f32_16x16x32_bf16 v[84:87], v[160:163], v[200:203], v[84:87]
	v_mfma_f32_16x16x32_bf16 v[76:79], v[152:155], v[212:215], v[76:79]
	v_mfma_f32_16x16x32_bf16 v[68:71], v[160:163], v[212:215], v[68:71]
	s_setprio 0
	s_setprio 1
	v_mfma_f32_16x16x32_bf16 v[120:123], v[164:167], v[180:183], v[120:123]
	v_mfma_f32_16x16x32_bf16 v[112:115], v[172:175], v[180:183], v[112:115]
	v_mfma_f32_16x16x32_bf16 v[104:107], v[164:167], v[188:191], v[104:107]
	v_mfma_f32_16x16x32_bf16 v[96:99], v[172:175], v[188:191], v[96:99]
	v_mfma_f32_16x16x32_bf16 v[88:91], v[164:167], v[196:199], v[88:91]
	v_mfma_f32_16x16x32_bf16 v[80:83], v[172:175], v[196:199], v[80:83]
	v_mfma_f32_16x16x32_bf16 v[72:75], v[164:167], v[208:211], v[72:75]
	v_mfma_f32_16x16x32_bf16 v[64:67], v[172:175], v[208:211], v[64:67]
	v_mfma_f32_16x16x32_bf16 v[120:123], v[168:171], v[184:187], v[120:123]
	v_mfma_f32_16x16x32_bf16 v[112:115], v[176:179], v[184:187], v[112:115]
	v_mfma_f32_16x16x32_bf16 v[104:107], v[168:171], v[192:195], v[104:107]
	v_mfma_f32_16x16x32_bf16 v[96:99], v[176:179], v[192:195], v[96:99]
	v_mfma_f32_16x16x32_bf16 v[88:91], v[168:171], v[200:203], v[88:91]
	v_mfma_f32_16x16x32_bf16 v[80:83], v[176:179], v[200:203], v[80:83]
	v_mfma_f32_16x16x32_bf16 v[72:75], v[168:171], v[212:215], v[72:75]
	v_mfma_f32_16x16x32_bf16 v[64:67], v[176:179], v[212:215], v[64:67]
	s_setprio 0
	s_barrier
	s_add_i32 s59, s50, s42
	v_lshl_add_u64 v[140:141], s[38:39], 0, v[130:131]
	s_mov_b32 m0, s59
	ds_read_b128 v[180:183], v147 offset:16384
	ds_read_b128 v[184:187], v147 offset:17408
	ds_read_b128 v[188:191], v147 offset:18432
	ds_read_b128 v[192:195], v147 offset:19456
	ds_read_b128 v[196:199], v147 offset:20480
	ds_read_b128 v[200:203], v147 offset:21504
	ds_read_b128 v[208:211], v147 offset:22528
	ds_read_b128 v[212:215], v147 offset:23552
	global_load_lds_dwordx4 v[140:141], off
	s_add_i32 m0, s59, 0x2000
	s_add_u32 s60, s38, 0x40000
	v_lshl_add_u64 v[204:205], s[38:39], 0, v[128:129]
	s_addc_u32 s61, s39, 0
	s_add_i32 s59, s51, s42
	global_load_lds_dwordx4 v[204:205], off
	v_lshl_add_u64 v[216:217], s[60:61], 0, v[130:131]
	s_mov_b32 m0, s59
	v_lshl_add_u64 v[218:219], s[40:41], 0, v[128:129]
	global_load_lds_dwordx4 v[216:217], off
	v_lshl_add_u64 v[216:217], s[60:61], 0, v[128:129]
	s_add_i32 m0, s59, 0x2000
	s_nop 0
	global_load_lds_dwordx4 v[216:217], off
	v_lshl_add_u64 v[216:217], s[40:41], 0, v[130:131]
	s_mov_b32 m0, s35
	s_nop 0
	global_load_lds_dwordx4 v[216:217], off
	s_mov_b32 m0, s44
	s_nop 0
	global_load_lds_dwordx4 v[218:219], off
	s_waitcnt vmcnt(8) lgkmcnt(0)
	s_barrier
; #define PG8_STAGE(bufoff, gbase, voff) do { _Pragma("unroll") for (int _i = 0; _i < 2; ++_i) \
;         __builtin_amdgcn_global_load_lds((const unsigned*)((const char*)(gbase) + (voff)[_i]), (LAS unsigned*)(lds + (bufoff) + ldsw + _i * 8192), 16, 0, 0); } while (0)
; #define PG8_LDA(dst, b, h) do { _Pragma("unroll") for (int m = 0; m < 4; ++m) _Pragma("unroll") for (int k = 0; k < 2; ++k) dst[m][k] = *(const LAS bf16x8*)(lds + PG8_SA(b, h) + aoff + m * 2048 + k * 1024); } while (0)
; #define PG8_LDB(dst, b, h) do { _Pragma("unroll") for (int n = 0; n < 2; ++n) _Pragma("unroll") for (int k = 0; k < 2; ++k) dst[n][k] = *(const LAS bf16x8*)(lds + PG8_SB(b, h) + boff + n * 2048 + k * 1024); } while (0)
; #define PG8_WAIT_V(n) asm volatile("s_waitcnt vmcnt(" #n ")" ::: "memory")
; #define PG8_WAIT_L(n) asm volatile("s_waitcnt lgkmcnt(" #n ")" ::: "memory")
; #define PG8_BAR __builtin_amdgcn_s_barrier()
; #define PG8_SCHED __builtin_amdgcn_sched_barrier(0)
; template <class Epi, class Sched, bool SWAPD = false>
; __device__ __forceinline__ void gemm_phase(LAS unsigned char* lds, const Gemm g, const Sched& S, const Epi& E) {
;     ...
;             PG8_WAIT_V(8); PG8_WAIT_L(0); PG8_BAR; PG8_MMA(1, 0, At, B0); PG8_MMA(1, 1, At, B1); PG8_BAR; PG8_SCHED;
;             PG8_LDB(B0, 1, 0); PG8_LDB(B1, 1, 1); PG8_SCHED; PG8_LDA(At, 1, 0); PG8_STAGE(PG8_SA(0, 1), a2 + hstepA, voffA);
;             PG8_WAIT_V(8); PG8_WAIT_L(0); PG8_BAR; PG8_MMA(0, 0, At, B0); PG8_MMA(0, 1, At, B1); PG8_BAR; PG8_SCHED;
	s_setprio 1
	v_mfma_f32_16x16x32_bf16 v[60:63], v[148:151], v[180:183], v[60:63]
	v_mfma_f32_16x16x32_bf16 v[52:55], v[156:159], v[180:183], v[52:55]
	v_mfma_f32_16x16x32_bf16 v[44:47], v[148:151], v[188:191], v[44:47]
	v_mfma_f32_16x16x32_bf16 v[36:39], v[156:159], v[188:191], v[36:39]
	v_mfma_f32_16x16x32_bf16 v[28:31], v[148:151], v[196:199], v[28:31]
	v_mfma_f32_16x16x32_bf16 v[20:23], v[156:159], v[196:199], v[20:23]
	v_mfma_f32_16x16x32_bf16 v[12:15], v[148:151], v[208:211], v[12:15]
	v_mfma_f32_16x16x32_bf16 v[4:7], v[156:159], v[208:211], v[4:7]
	v_mfma_f32_16x16x32_bf16 v[60:63], v[152:155], v[184:187], v[60:63]
	v_mfma_f32_16x16x32_bf16 v[52:55], v[160:163], v[184:187], v[52:55]
	v_mfma_f32_16x16x32_bf16 v[44:47], v[152:155], v[192:195], v[44:47]
	v_mfma_f32_16x16x32_bf16 v[36:39], v[160:163], v[192:195], v[36:39]
	v_mfma_f32_16x16x32_bf16 v[28:31], v[152:155], v[200:203], v[28:31]
	v_mfma_f32_16x16x32_bf16 v[20:23], v[160:163], v[200:203], v[20:23]
	v_mfma_f32_16x16x32_bf16 v[12:15], v[152:155], v[212:215], v[12:15]
	v_mfma_f32_16x16x32_bf16 v[4:7], v[160:163], v[212:215], v[4:7]
	s_setprio 0
	s_setprio 1
	v_mfma_f32_16x16x32_bf16 v[56:59], v[164:167], v[180:183], v[56:59]
	v_mfma_f32_16x16x32_bf16 v[48:51], v[172:175], v[180:183], v[48:51]
	v_mfma_f32_16x16x32_bf16 v[40:43], v[164:167], v[188:191], v[40:43]
	v_mfma_f32_16x16x32_bf16 v[32:35], v[172:175], v[188:191], v[32:35]
	v_mfma_f32_16x16x32_bf16 v[24:27], v[164:167], v[196:199], v[24:27]
	v_mfma_f32_16x16x32_bf16 v[16:19], v[172:175], v[196:199], v[16:19]
	v_mfma_f32_16x16x32_bf16 v[8:11], v[164:167], v[208:211], v[8:11]
	v_mfma_f32_16x16x32_bf16 v[0:3], v[172:175], v[208:211], v[0:3]
	v_mfma_f32_16x16x32_bf16 v[56:59], v[168:171], v[184:187], v[56:59]
	v_mfma_f32_16x16x32_bf16 v[48:51], v[176:179], v[184:187], v[48:51]
	v_mfma_f32_16x16x32_bf16 v[40:43], v[168:171], v[192:195], v[40:43]
	v_mfma_f32_16x16x32_bf16 v[32:35], v[176:179], v[192:195], v[32:35]
	v_mfma_f32_16x16x32_bf16 v[24:27], v[168:171], v[200:203], v[24:27]
	v_mfma_f32_16x16x32_bf16 v[16:19], v[176:179], v[200:203], v[16:19]
	v_mfma_f32_16x16x32_bf16 v[8:11], v[168:171], v[212:215], v[8:11]
	v_mfma_f32_16x16x32_bf16 v[0:3], v[176:179], v[212:215], v[0:3]
	s_setprio 0
	s_barrier
	s_add_i32 s59, 0, 0x18000
	s_add_i32 s60, 0, 0x1c000
	v_add_u32_e32 v160, s59, v143
	v_add_u32_e32 v176, s60, v143
	ds_read_b128 v[148:151], v160
	ds_read_b128 v[152:155], v160 offset:1024
	ds_read_b128 v[156:159], v160 offset:2048
	ds_read_b128 v[160:163], v160 offset:3072
	ds_read_b128 v[164:167], v176
	ds_read_b128 v[168:171], v176 offset:1024
	ds_read_b128 v[172:175], v176 offset:2048
	ds_read_b128 v[176:179], v176 offset:3072
	s_add_u32 s40, s40, 0x40000
	s_addc_u32 s41, s41, 0
	s_mov_b32 m0, s45
	v_lshl_add_u64 v[220:221], s[40:41], 0, v[130:131]
	ds_read_b128 v[180:183], v147 offset:32768
	ds_read_b128 v[184:187], v147 offset:33792
	ds_read_b128 v[188:191], v147 offset:34816
	ds_read_b128 v[192:195], v147 offset:35840
	ds_read_b128 v[196:199], v147 offset:36864
	ds_read_b128 v[200:203], v147 offset:37888
	ds_read_b128 v[208:211], v147 offset:38912
	ds_read_b128 v[212:215], v147 offset:39936
	global_load_lds_dwordx4 v[220:221], off
	v_lshl_add_u64 v[220:221], s[40:41], 0, v[128:129]
	s_mov_b32 m0, s46
	s_nop 0
	global_load_lds_dwordx4 v[220:221], off
	s_waitcnt vmcnt(8) lgkmcnt(0)
	s_barrier
	s_setprio 1
	v_mfma_f32_16x16x32_bf16 v[124:127], v[148:151], v[180:183], v[124:127]
	v_mfma_f32_16x16x32_bf16 v[116:119], v[156:159], v[180:183], v[116:119]
	v_mfma_f32_16x16x32_bf16 v[108:111], v[148:151], v[188:191], v[108:111]
	v_mfma_f32_16x16x32_bf16 v[100:103], v[156:159], v[188:191], v[100:103]
	v_mfma_f32_16x16x32_bf16 v[92:95], v[148:151], v[196:199], v[92:95]
	v_mfma_f32_16x16x32_bf16 v[84:87], v[156:159], v[196:199], v[84:87]
	v_mfma_f32_16x16x32_bf16 v[76:79], v[148:151], v[208:211], v[76:79]
	v_mfma_f32_16x16x32_bf16 v[68:71], v[156:159], v[208:211], v[68:71]
	v_mfma_f32_16x16x32_bf16 v[124:127], v[152:155], v[184:187], v[124:127]
	v_mfma_f32_16x16x32_bf16 v[116:119], v[160:163], v[184:187], v[116:119]
	v_mfma_f32_16x16x32_bf16 v[108:111], v[152:155], v[192:195], v[108:111]
	v_mfma_f32_16x16x32_bf16 v[100:103], v[160:163], v[192:195], v[100:103]
	v_mfma_f32_16x16x32_bf16 v[92:95], v[152:155], v[200:203], v[92:95]
	v_mfma_f32_16x16x32_bf16 v[84:87], v[160:163], v[200:203], v[84:87]
	v_mfma_f32_16x16x32_bf16 v[76:79], v[152:155], v[212:215], v[76:79]
	v_mfma_f32_16x16x32_bf16 v[68:71], v[160:163], v[212:215], v[68:71]
	s_setprio 0
	s_setprio 1
	v_mfma_f32_16x16x32_bf16 v[120:123], v[164:167], v[180:183], v[120:123]
	v_mfma_f32_16x16x32_bf16 v[112:115], v[172:175], v[180:183], v[112:115]
	v_mfma_f32_16x16x32_bf16 v[104:107], v[164:167], v[188:191], v[104:107]
	v_mfma_f32_16x16x32_bf16 v[96:99], v[172:175], v[188:191], v[96:99]
	v_mfma_f32_16x16x32_bf16 v[88:91], v[164:167], v[196:199], v[88:91]
	v_mfma_f32_16x16x32_bf16 v[80:83], v[172:175], v[196:199], v[80:83]
	v_mfma_f32_16x16x32_bf16 v[72:75], v[164:167], v[208:211], v[72:75]
	v_mfma_f32_16x16x32_bf16 v[64:67], v[172:175], v[208:211], v[64:67]
	v_mfma_f32_16x16x32_bf16 v[120:123], v[168:171], v[184:187], v[120:123]
	v_mfma_f32_16x16x32_bf16 v[112:115], v[176:179], v[184:187], v[112:115]
	v_mfma_f32_16x16x32_bf16 v[104:107], v[168:171], v[192:195], v[104:107]
	v_mfma_f32_16x16x32_bf16 v[96:99], v[176:179], v[192:195], v[96:99]
	v_mfma_f32_16x16x32_bf16 v[88:91], v[168:171], v[200:203], v[88:91]
	v_mfma_f32_16x16x32_bf16 v[80:83], v[176:179], v[200:203], v[80:83]
	v_mfma_f32_16x16x32_bf16 v[72:75], v[168:171], v[212:215], v[72:75]
	v_mfma_f32_16x16x32_bf16 v[64:67], v[176:179], v[212:215], v[64:67]
	s_setprio 0
	s_barrier
; #define PG8_STAGE(bufoff, gbase, voff) do { _Pragma("unroll") for (int _i = 0; _i < 2; ++_i) \
;         __builtin_amdgcn_global_load_lds((const unsigned*)((const char*)(gbase) + (voff)[_i]), (LAS unsigned*)(lds + (bufoff) + ldsw + _i * 8192), 16, 0, 0); } while (0)
; #define PG8_LDA(dst, b, h) do { _Pragma("unroll") for (int m = 0; m < 4; ++m) _Pragma("unroll") for (int k = 0; k < 2; ++k) dst[m][k] = *(const LAS bf16x8*)(lds + PG8_SA(b, h) + aoff + m * 2048 + k * 1024); } while (0)
; #define PG8_WAIT_V(n) asm volatile("s_waitcnt vmcnt(" #n ")" ::: "memory")
; #define PG8_WAIT_L(n) asm volatile("s_waitcnt lgkmcnt(" #n ")" ::: "memory")
; #define PG8_BAR __builtin_amdgcn_s_barrier()
; #define PG8_SCHED __builtin_amdgcn_sched_barrier(0)
; template <class Epi, class Sched, bool SWAPD = false>
; __device__ __forceinline__ void gemm_phase(LAS unsigned char* lds, const Gemm g, const Sched& S, const Epi& E) {
;     ...
;             PG8_LDA(At, 1, 1); PG8_STAGE(PG8_SB(1, 0), b3, voffB); PG8_STAGE(PG8_SB(1, 1), b3 + hstepB, voffB); PG8_STAGE(PG8_SA(1, 0), a3, voffA);
;             PG8_WAIT_V(8); PG8_WAIT_L(0); PG8_BAR; PG8_MMA(1, 0, At, B0); PG8_MMA(1, 1, At, B1); PG8_BAR; PG8_SCHED;
;         }
;         if (wr == 0) PG8_BAR;
	s_add_i32 s40, s59, s42
	v_lshl_add_u64 v[140:141], v[140:141], 0, s[8:9]
	s_mov_b32 m0, s40
	ds_read_b128 v[180:183], v147 offset:49152
	ds_read_b128 v[184:187], v147 offset:50176
	ds_read_b128 v[188:191], v147 offset:51200
	ds_read_b128 v[192:195], v147 offset:52224
	ds_read_b128 v[196:199], v147 offset:53248
	ds_read_b128 v[200:203], v147 offset:54272
	ds_read_b128 v[208:211], v147 offset:55296
	ds_read_b128 v[212:215], v147 offset:56320
	global_load_lds_dwordx4 v[140:141], off
	s_add_i32 m0, s40, 0x2000
	s_add_u32 s38, s38, 0x40080
	v_lshl_add_u64 v[140:141], v[204:205], 0, s[8:9]
	s_addc_u32 s39, s39, 0
	s_add_i32 s40, s60, s42
	global_load_lds_dwordx4 v[140:141], off
	v_lshl_add_u64 v[140:141], s[38:39], 0, v[130:131]
	s_mov_b32 m0, s40
	s_nop 0
	global_load_lds_dwordx4 v[140:141], off
	v_lshl_add_u64 v[140:141], s[38:39], 0, v[128:129]
	s_add_i32 m0, s40, 0x2000
	s_nop 0
	global_load_lds_dwordx4 v[140:141], off
	v_lshl_add_u64 v[140:141], v[216:217], 0, s[8:9]
	s_mov_b32 m0, s48
	s_nop 0
	global_load_lds_dwordx4 v[140:141], off
	v_lshl_add_u64 v[140:141], v[218:219], 0, s[8:9]
	s_mov_b32 m0, s49
	s_nop 0
	global_load_lds_dwordx4 v[140:141], off
	s_waitcnt vmcnt(8) lgkmcnt(0)
	s_barrier
	s_setprio 1
	v_mfma_f32_16x16x32_bf16 v[60:63], v[148:151], v[180:183], v[60:63]
	v_mfma_f32_16x16x32_bf16 v[52:55], v[156:159], v[180:183], v[52:55]
	v_mfma_f32_16x16x32_bf16 v[44:47], v[148:151], v[188:191], v[44:47]
	v_mfma_f32_16x16x32_bf16 v[36:39], v[156:159], v[188:191], v[36:39]
	v_mfma_f32_16x16x32_bf16 v[28:31], v[148:151], v[196:199], v[28:31]
	v_mfma_f32_16x16x32_bf16 v[20:23], v[156:159], v[196:199], v[20:23]
	v_mfma_f32_16x16x32_bf16 v[12:15], v[148:151], v[208:211], v[12:15]
	v_mfma_f32_16x16x32_bf16 v[4:7], v[156:159], v[208:211], v[4:7]
	v_mfma_f32_16x16x32_bf16 v[60:63], v[152:155], v[184:187], v[60:63]
	v_mfma_f32_16x16x32_bf16 v[52:55], v[160:163], v[184:187], v[52:55]
	v_mfma_f32_16x16x32_bf16 v[44:47], v[152:155], v[192:195], v[44:47]
	v_mfma_f32_16x16x32_bf16 v[36:39], v[160:163], v[192:195], v[36:39]
	v_mfma_f32_16x16x32_bf16 v[28:31], v[152:155], v[200:203], v[28:31]
	v_mfma_f32_16x16x32_bf16 v[20:23], v[160:163], v[200:203], v[20:23]
	v_mfma_f32_16x16x32_bf16 v[12:15], v[152:155], v[212:215], v[12:15]
	v_mfma_f32_16x16x32_bf16 v[4:7], v[160:163], v[212:215], v[4:7]
	s_setprio 0
	s_setprio 1
	v_mfma_f32_16x16x32_bf16 v[56:59], v[164:167], v[180:183], v[56:59]
	v_mfma_f32_16x16x32_bf16 v[48:51], v[172:175], v[180:183], v[48:51]
	v_mfma_f32_16x16x32_bf16 v[40:43], v[164:167], v[188:191], v[40:43]
	v_mfma_f32_16x16x32_bf16 v[32:35], v[172:175], v[188:191], v[32:35]
	v_mfma_f32_16x16x32_bf16 v[24:27], v[164:167], v[196:199], v[24:27]
	v_mfma_f32_16x16x32_bf16 v[16:19], v[172:175], v[196:199], v[16:19]
	v_mfma_f32_16x16x32_bf16 v[8:11], v[164:167], v[208:211], v[8:11]
	v_mfma_f32_16x16x32_bf16 v[0:3], v[172:175], v[208:211], v[0:3]
	v_mfma_f32_16x16x32_bf16 v[56:59], v[168:171], v[184:187], v[56:59]
	v_mfma_f32_16x16x32_bf16 v[48:51], v[176:179], v[184:187], v[48:51]
	v_mfma_f32_16x16x32_bf16 v[40:43], v[168:171], v[192:195], v[40:43]
	v_mfma_f32_16x16x32_bf16 v[32:35], v[176:179], v[192:195], v[32:35]
	v_mfma_f32_16x16x32_bf16 v[24:27], v[168:171], v[200:203], v[24:27]
	v_mfma_f32_16x16x32_bf16 v[16:19], v[176:179], v[200:203], v[16:19]
	v_mfma_f32_16x16x32_bf16 v[8:11], v[168:171], v[212:215], v[8:11]
	v_mfma_f32_16x16x32_bf16 v[0:3], v[176:179], v[212:215], v[0:3]
	s_setprio 0
	s_barrier
	s_add_i32 s58, s58, 2
	s_add_u32 s36, s36, 0x100
	s_addc_u32 s37, s37, 0
	s_add_u32 s56, s56, 0x100
	s_addc_u32 s57, s57, 0
	s_cmp_gt_u32 s58, 13
	s_cbranch_scc0 .LBB0_1863
	s_and_b64 vcc, exec, s[10:11]
	s_cbranch_vccz .LBB0_1866
	s_barrier

; #define PG8_STAGE(bufoff, gbase, voff) do { _Pragma("unroll") for (int _i = 0; _i < 2; ++_i) \
;         __builtin_amdgcn_global_load_lds((const unsigned*)((const char*)(gbase) + (voff)[_i]), (LAS unsigned*)(lds + (bufoff) + ldsw + _i * 8192), 16, 0, 0); } while (0)
; #define PG8_LDA(dst, b, h) do { _Pragma("unroll") for (int m = 0; m < 4; ++m) _Pragma("unroll") for (int k = 0; k < 2; ++k) dst[m][k] = *(const LAS bf16x8*)(lds + PG8_SA(b, h) + aoff + m * 2048 + k * 1024); } while (0)
; #define PG8_LDB(dst, b, h) do { _Pragma("unroll") for (int n = 0; n < 2; ++n) _Pragma("unroll") for (int k = 0; k < 2; ++k) dst[n][k] = *(const LAS bf16x8*)(lds + PG8_SB(b, h) + boff + n * 2048 + k * 1024); } while (0)
; #define PG8_WAIT_V(n) asm volatile("s_waitcnt vmcnt(" #n ")" ::: "memory")
; #define PG8_WAIT_L(n) asm volatile("s_waitcnt lgkmcnt(" #n ")" ::: "memory")
; #define PG8_BAR __builtin_amdgcn_s_barrier()
; #define PG8_SCHED __builtin_amdgcn_sched_barrier(0)
; template <class Epi, class Sched, bool SWAPD = false>
; __device__ __forceinline__ void gemm_phase(LAS unsigned char* lds, const Gemm g, const Sched& S, const Epi& E) {
;     ...
;             const bool last = (t == nt - 2);
;             const char* a1 = cA + (size_t)(t + 1) * kstepA;
;             const char* a2 = last ? nA : cA + (size_t)(t + 2) * kstepA; const char* b2 = last ? nB : cB + (size_t)(t + 2) * kstep;
;             const char* a3 = a2 + kstepA; const char* b3 = b2 + kstep;
;             PG8_LDB(B0, 0, 0); PG8_LDB(B1, 0, 1); PG8_SCHED; PG8_LDA(At, 0, 0); PG8_STAGE(PG8_SA(1, 1), a1 + hstepA, voffA);
;             PG8_WAIT_V(8); PG8_WAIT_L(0); PG8_BAR; PG8_MMA(0, 0, At, B0); PG8_MMA(0, 1, At, B1); PG8_BAR; PG8_SCHED;
;             PG8_LDA(At, 0, 1); PG8_STAGE(PG8_SB(0, 0), b2, voffB); PG8_STAGE(PG8_SB(0, 1), b2 + hstepB, voffB); PG8_STAGE(PG8_SA(0, 0), a2, voffA);
;             PG8_WAIT_V(8); PG8_WAIT_L(0); PG8_BAR; PG8_MMA(1, 0, At, B0); PG8_MMA(1, 1, At, B1); PG8_BAR; PG8_SCHED;
.LBB0_1940:
	ds_read_b128 v[156:159], v168
	ds_read_b128 v[160:163], v168 offset:1024
	ds_read_b128 v[172:175], v168 offset:2048
	ds_read_b128 v[176:179], v168 offset:3072
	ds_read_b128 v[180:183], v169
	ds_read_b128 v[184:187], v169 offset:1024
	ds_read_b128 v[188:191], v169 offset:2048
	ds_read_b128 v[192:195], v169 offset:3072
	s_add_u32 s22, s20, 0x100
	s_addc_u32 s23, s21, 0
	s_cmp_eq_u32 s53, 40
	s_cselect_b32 s27, s47, s23
	s_cselect_b32 s26, s48, s22
	s_cselect_b32 s25, s49, s52
	s_cselect_b32 s24, s50, s51
	v_lshl_add_u64 v[164:165], s[20:21], 0, v[148:149]
	s_add_i32 m0, s31, 0xc000
	ds_read_b128 v[196:199], v170
	ds_read_b128 v[200:203], v170 offset:1024
	ds_read_b128 v[204:207], v170 offset:2048
	ds_read_b128 v[208:211], v170 offset:3072
	ds_read_b128 v[212:215], v170 offset:4096
	ds_read_b128 v[216:219], v170 offset:5120
	ds_read_b128 v[220:223], v170 offset:6144
	ds_read_b128 v[224:227], v170 offset:7168
	global_load_lds_dwordx4 v[164:165], off
	v_lshl_add_u64 v[164:165], s[20:21], 0, v[150:151]
	s_add_i32 m0, s31, 0xe000
	s_nop 0
	global_load_lds_dwordx4 v[164:165], off
	s_waitcnt vmcnt(8) lgkmcnt(0)
	s_barrier
	s_setprio 1
	v_mfma_f32_16x16x32_bf16 v[124:127], v[156:159], v[196:199], v[124:127]
	v_mfma_f32_16x16x32_bf16 v[120:123], v[172:175], v[196:199], v[120:123]
	v_mfma_f32_16x16x32_bf16 v[108:111], v[156:159], v[204:207], v[108:111]
	v_mfma_f32_16x16x32_bf16 v[104:107], v[172:175], v[204:207], v[104:107]
	v_mfma_f32_16x16x32_bf16 v[92:95], v[156:159], v[212:215], v[92:95]
	v_mfma_f32_16x16x32_bf16 v[88:91], v[172:175], v[212:215], v[88:91]
	v_mfma_f32_16x16x32_bf16 v[76:79], v[156:159], v[220:223], v[76:79]
	v_mfma_f32_16x16x32_bf16 v[72:75], v[172:175], v[220:223], v[72:75]
	v_mfma_f32_16x16x32_bf16 v[124:127], v[160:163], v[200:203], v[124:127]
	v_mfma_f32_16x16x32_bf16 v[120:123], v[176:179], v[200:203], v[120:123]
	v_mfma_f32_16x16x32_bf16 v[108:111], v[160:163], v[208:211], v[108:111]
	v_mfma_f32_16x16x32_bf16 v[104:107], v[176:179], v[208:211], v[104:107]
	v_mfma_f32_16x16x32_bf16 v[92:95], v[160:163], v[216:219], v[92:95]
	v_mfma_f32_16x16x32_bf16 v[88:91], v[176:179], v[216:219], v[88:91]
	v_mfma_f32_16x16x32_bf16 v[76:79], v[160:163], v[224:227], v[76:79]
	v_mfma_f32_16x16x32_bf16 v[72:75], v[176:179], v[224:227], v[72:75]
	s_setprio 0
	s_setprio 1
	v_mfma_f32_16x16x32_bf16 v[116:119], v[180:183], v[196:199], v[116:119]
	v_mfma_f32_16x16x32_bf16 v[112:115], v[188:191], v[196:199], v[112:115]
	v_mfma_f32_16x16x32_bf16 v[100:103], v[180:183], v[204:207], v[100:103]
	v_mfma_f32_16x16x32_bf16 v[96:99], v[188:191], v[204:207], v[96:99]
	v_mfma_f32_16x16x32_bf16 v[84:87], v[180:183], v[212:215], v[84:87]
	v_mfma_f32_16x16x32_bf16 v[80:83], v[188:191], v[212:215], v[80:83]
	v_mfma_f32_16x16x32_bf16 v[68:71], v[180:183], v[220:223], v[68:71]
	v_mfma_f32_16x16x32_bf16 v[64:67], v[188:191], v[220:223], v[64:67]
	v_mfma_f32_16x16x32_bf16 v[116:119], v[184:187], v[200:203], v[116:119]
	v_mfma_f32_16x16x32_bf16 v[112:115], v[192:195], v[200:203], v[112:115]
	v_mfma_f32_16x16x32_bf16 v[100:103], v[184:187], v[208:211], v[100:103]
	v_mfma_f32_16x16x32_bf16 v[96:99], v[192:195], v[208:211], v[96:99]
	v_mfma_f32_16x16x32_bf16 v[84:87], v[184:187], v[216:219], v[84:87]
	v_mfma_f32_16x16x32_bf16 v[80:83], v[192:195], v[216:219], v[80:83]
	v_mfma_f32_16x16x32_bf16 v[68:71], v[184:187], v[224:227], v[68:71]
	v_mfma_f32_16x16x32_bf16 v[64:67], v[192:195], v[224:227], v[64:67]
	s_setprio 0
	s_barrier
	s_add_i32 s20, s41, s30
	v_lshl_add_u64 v[164:165], s[24:25], 0, v[128:129]
	s_mov_b32 m0, s20
	ds_read_b128 v[196:199], v170 offset:16384
	ds_read_b128 v[200:203], v170 offset:17408
	ds_read_b128 v[204:207], v170 offset:18432
	ds_read_b128 v[208:211], v170 offset:19456
	ds_read_b128 v[212:215], v170 offset:20480
	ds_read_b128 v[216:219], v170 offset:21504
	ds_read_b128 v[220:223], v170 offset:22528
	ds_read_b128 v[224:227], v170 offset:23552
	global_load_lds_dwordx4 v[164:165], off
	s_add_i32 m0, s20, 0x2000
	s_add_u32 s20, s24, 0xb0000
	v_lshl_add_u64 v[228:229], s[24:25], 0, v[130:131]
	s_addc_u32 s21, s25, 0
	s_add_i32 s54, s42, s30
	global_load_lds_dwordx4 v[228:229], off
	v_lshl_add_u64 v[230:231], s[20:21], 0, v[128:129]
	s_mov_b32 m0, s54
	v_lshl_add_u64 v[232:233], s[26:27], 0, v[130:131]
	global_load_lds_dwordx4 v[230:231], off
	v_lshl_add_u64 v[230:231], s[20:21], 0, v[130:131]
	s_add_i32 m0, s54, 0x2000
	s_nop 0
	global_load_lds_dwordx4 v[230:231], off
	v_lshl_add_u64 v[230:231], s[26:27], 0, v[128:129]
	s_mov_b32 m0, s31
	s_nop 0
	global_load_lds_dwordx4 v[230:231], off
	s_mov_b32 m0, s33
	s_nop 0
	global_load_lds_dwordx4 v[232:233], off
	s_waitcnt vmcnt(8) lgkmcnt(0)
	s_barrier
; #define PG8_STAGE(bufoff, gbase, voff) do { _Pragma("unroll") for (int _i = 0; _i < 2; ++_i) \
;         __builtin_amdgcn_global_load_lds((const unsigned*)((const char*)(gbase) + (voff)[_i]), (LAS unsigned*)(lds + (bufoff) + ldsw + _i * 8192), 16, 0, 0); } while (0)
; #define PG8_LDA(dst, b, h) do { _Pragma("unroll") for (int m = 0; m < 4; ++m) _Pragma("unroll") for (int k = 0; k < 2; ++k) dst[m][k] = *(const LAS bf16x8*)(lds + PG8_SA(b, h) + aoff + m * 2048 + k * 1024); } while (0)
; #define PG8_LDB(dst, b, h) do { _Pragma("unroll") for (int n = 0; n < 2; ++n) _Pragma("unroll") for (int k = 0; k < 2; ++k) dst[n][k] = *(const LAS bf16x8*)(lds + PG8_SB(b, h) + boff + n * 2048 + k * 1024); } while (0)
; #define PG8_WAIT_V(n) asm volatile("s_waitcnt vmcnt(" #n ")" ::: "memory")
; #define PG8_WAIT_L(n) asm volatile("s_waitcnt lgkmcnt(" #n ")" ::: "memory")
; #define PG8_BAR __builtin_amdgcn_s_barrier()
; #define PG8_SCHED __builtin_amdgcn_sched_barrier(0)
; template <class Epi, class Sched, bool SWAPD = false>
; __device__ __forceinline__ void gemm_phase(LAS unsigned char* lds, const Gemm g, const Sched& S, const Epi& E) {
;     ...
;             PG8_WAIT_V(8); PG8_WAIT_L(0); PG8_BAR; PG8_MMA(1, 0, At, B0); PG8_MMA(1, 1, At, B1); PG8_BAR; PG8_SCHED;
;             PG8_LDB(B0, 1, 0); PG8_LDB(B1, 1, 1); PG8_SCHED; PG8_LDA(At, 1, 0); PG8_STAGE(PG8_SA(0, 1), a2 + hstepA, voffA);
;             PG8_WAIT_V(8); PG8_WAIT_L(0); PG8_BAR; PG8_MMA(0, 0, At, B0); PG8_MMA(0, 1, At, B1); PG8_BAR; PG8_SCHED;
	s_setprio 1
	v_mfma_f32_16x16x32_bf16 v[60:63], v[156:159], v[196:199], v[60:63]
	v_mfma_f32_16x16x32_bf16 v[56:59], v[172:175], v[196:199], v[56:59]
	v_mfma_f32_16x16x32_bf16 v[44:47], v[156:159], v[204:207], v[44:47]
	v_mfma_f32_16x16x32_bf16 v[40:43], v[172:175], v[204:207], v[40:43]
	v_mfma_f32_16x16x32_bf16 v[28:31], v[156:159], v[212:215], v[28:31]
	v_mfma_f32_16x16x32_bf16 v[24:27], v[172:175], v[212:215], v[24:27]
	v_mfma_f32_16x16x32_bf16 v[12:15], v[156:159], v[220:223], v[12:15]
	v_mfma_f32_16x16x32_bf16 v[8:11], v[172:175], v[220:223], v[8:11]
	v_mfma_f32_16x16x32_bf16 v[60:63], v[160:163], v[200:203], v[60:63]
	v_mfma_f32_16x16x32_bf16 v[56:59], v[176:179], v[200:203], v[56:59]
	v_mfma_f32_16x16x32_bf16 v[44:47], v[160:163], v[208:211], v[44:47]
	v_mfma_f32_16x16x32_bf16 v[40:43], v[176:179], v[208:211], v[40:43]
	v_mfma_f32_16x16x32_bf16 v[28:31], v[160:163], v[216:219], v[28:31]
	v_mfma_f32_16x16x32_bf16 v[24:27], v[176:179], v[216:219], v[24:27]
	v_mfma_f32_16x16x32_bf16 v[12:15], v[160:163], v[224:227], v[12:15]
	v_mfma_f32_16x16x32_bf16 v[8:11], v[176:179], v[224:227], v[8:11]
	s_setprio 0
	s_setprio 1
	v_mfma_f32_16x16x32_bf16 v[52:55], v[180:183], v[196:199], v[52:55]
	v_mfma_f32_16x16x32_bf16 v[48:51], v[188:191], v[196:199], v[48:51]
	v_mfma_f32_16x16x32_bf16 v[36:39], v[180:183], v[204:207], v[36:39]
	v_mfma_f32_16x16x32_bf16 v[32:35], v[188:191], v[204:207], v[32:35]
	v_mfma_f32_16x16x32_bf16 v[20:23], v[180:183], v[212:215], v[20:23]
	v_mfma_f32_16x16x32_bf16 v[16:19], v[188:191], v[212:215], v[16:19]
	v_mfma_f32_16x16x32_bf16 v[4:7], v[180:183], v[220:223], v[4:7]
	v_mfma_f32_16x16x32_bf16 v[0:3], v[188:191], v[220:223], v[0:3]
	v_mfma_f32_16x16x32_bf16 v[52:55], v[184:187], v[200:203], v[52:55]
	v_mfma_f32_16x16x32_bf16 v[48:51], v[192:195], v[200:203], v[48:51]
	v_mfma_f32_16x16x32_bf16 v[36:39], v[184:187], v[208:211], v[36:39]
	v_mfma_f32_16x16x32_bf16 v[32:35], v[192:195], v[208:211], v[32:35]
	v_mfma_f32_16x16x32_bf16 v[20:23], v[184:187], v[216:219], v[20:23]
	v_mfma_f32_16x16x32_bf16 v[16:19], v[192:195], v[216:219], v[16:19]
	v_mfma_f32_16x16x32_bf16 v[4:7], v[184:187], v[224:227], v[4:7]
	v_mfma_f32_16x16x32_bf16 v[0:3], v[192:195], v[224:227], v[0:3]
	s_setprio 0
	s_barrier
	s_add_i32 s54, 0, 0x18000
	v_add_u32_e32 v171, s54, v166
	s_add_i32 s55, 0, 0x1c000
	ds_read_b128 v[156:159], v171
	ds_read_b128 v[160:163], v171 offset:1024
	ds_read_b128 v[172:175], v171 offset:2048
	ds_read_b128 v[176:179], v171 offset:3072
	v_add_u32_e32 v171, s55, v166
	ds_read_b128 v[180:183], v171
	ds_read_b128 v[184:187], v171 offset:1024
	ds_read_b128 v[188:191], v171 offset:2048
	ds_read_b128 v[192:195], v171 offset:3072
	s_add_u32 s20, s26, 0xb0000
	s_addc_u32 s21, s27, 0
	s_mov_b32 m0, s34
	v_lshl_add_u64 v[234:235], s[20:21], 0, v[128:129]
	ds_read_b128 v[196:199], v170 offset:32768
	ds_read_b128 v[200:203], v170 offset:33792
	ds_read_b128 v[204:207], v170 offset:34816
	ds_read_b128 v[208:211], v170 offset:35840
	ds_read_b128 v[212:215], v170 offset:36864
	ds_read_b128 v[216:219], v170 offset:37888
	ds_read_b128 v[220:223], v170 offset:38912
	ds_read_b128 v[224:227], v170 offset:39936
	global_load_lds_dwordx4 v[234:235], off
	v_lshl_add_u64 v[234:235], s[20:21], 0, v[130:131]
	s_mov_b32 m0, s35
	s_nop 0
	global_load_lds_dwordx4 v[234:235], off
	s_waitcnt vmcnt(8) lgkmcnt(0)
	s_barrier
	s_setprio 1
	v_mfma_f32_16x16x32_bf16 v[124:127], v[156:159], v[196:199], v[124:127]
	v_mfma_f32_16x16x32_bf16 v[120:123], v[172:175], v[196:199], v[120:123]
	v_mfma_f32_16x16x32_bf16 v[108:111], v[156:159], v[204:207], v[108:111]
	v_mfma_f32_16x16x32_bf16 v[104:107], v[172:175], v[204:207], v[104:107]
	v_mfma_f32_16x16x32_bf16 v[92:95], v[156:159], v[212:215], v[92:95]
	v_mfma_f32_16x16x32_bf16 v[88:91], v[172:175], v[212:215], v[88:91]
	v_mfma_f32_16x16x32_bf16 v[76:79], v[156:159], v[220:223], v[76:79]
	v_mfma_f32_16x16x32_bf16 v[72:75], v[172:175], v[220:223], v[72:75]
	v_mfma_f32_16x16x32_bf16 v[124:127], v[160:163], v[200:203], v[124:127]
	v_mfma_f32_16x16x32_bf16 v[120:123], v[176:179], v[200:203], v[120:123]
	v_mfma_f32_16x16x32_bf16 v[108:111], v[160:163], v[208:211], v[108:111]
	v_mfma_f32_16x16x32_bf16 v[104:107], v[176:179], v[208:211], v[104:107]
	v_mfma_f32_16x16x32_bf16 v[92:95], v[160:163], v[216:219], v[92:95]
	v_mfma_f32_16x16x32_bf16 v[88:91], v[176:179], v[216:219], v[88:91]
	v_mfma_f32_16x16x32_bf16 v[76:79], v[160:163], v[224:227], v[76:79]
	v_mfma_f32_16x16x32_bf16 v[72:75], v[176:179], v[224:227], v[72:75]
	s_setprio 0
	s_setprio 1
	v_mfma_f32_16x16x32_bf16 v[116:119], v[180:183], v[196:199], v[116:119]
	v_mfma_f32_16x16x32_bf16 v[112:115], v[188:191], v[196:199], v[112:115]
	v_mfma_f32_16x16x32_bf16 v[100:103], v[180:183], v[204:207], v[100:103]
	v_mfma_f32_16x16x32_bf16 v[96:99], v[188:191], v[204:207], v[96:99]
	v_mfma_f32_16x16x32_bf16 v[84:87], v[180:183], v[212:215], v[84:87]
	v_mfma_f32_16x16x32_bf16 v[80:83], v[188:191], v[212:215], v[80:83]
	v_mfma_f32_16x16x32_bf16 v[68:71], v[180:183], v[220:223], v[68:71]
	v_mfma_f32_16x16x32_bf16 v[64:67], v[188:191], v[220:223], v[64:67]
	v_mfma_f32_16x16x32_bf16 v[116:119], v[184:187], v[200:203], v[116:119]
	v_mfma_f32_16x16x32_bf16 v[112:115], v[192:195], v[200:203], v[112:115]
	v_mfma_f32_16x16x32_bf16 v[100:103], v[184:187], v[208:211], v[100:103]
	v_mfma_f32_16x16x32_bf16 v[96:99], v[192:195], v[208:211], v[96:99]
	v_mfma_f32_16x16x32_bf16 v[84:87], v[184:187], v[216:219], v[84:87]
	v_mfma_f32_16x16x32_bf16 v[80:83], v[192:195], v[216:219], v[80:83]
	v_mfma_f32_16x16x32_bf16 v[68:71], v[184:187], v[224:227], v[68:71]
	v_mfma_f32_16x16x32_bf16 v[64:67], v[192:195], v[224:227], v[64:67]
	s_setprio 0
	s_barrier
; #define PG8_STAGE(bufoff, gbase, voff) do { _Pragma("unroll") for (int _i = 0; _i < 2; ++_i) \
;         __builtin_amdgcn_global_load_lds((const unsigned*)((const char*)(gbase) + (voff)[_i]), (LAS unsigned*)(lds + (bufoff) + ldsw + _i * 8192), 16, 0, 0); } while (0)
; #define PG8_LDA(dst, b, h) do { _Pragma("unroll") for (int m = 0; m < 4; ++m) _Pragma("unroll") for (int k = 0; k < 2; ++k) dst[m][k] = *(const LAS bf16x8*)(lds + PG8_SA(b, h) + aoff + m * 2048 + k * 1024); } while (0)
; #define PG8_WAIT_V(n) asm volatile("s_waitcnt vmcnt(" #n ")" ::: "memory")
; #define PG8_WAIT_L(n) asm volatile("s_waitcnt lgkmcnt(" #n ")" ::: "memory")
; #define PG8_BAR __builtin_amdgcn_s_barrier()
; #define PG8_SCHED __builtin_amdgcn_sched_barrier(0)
; template <class Epi, class Sched, bool SWAPD = false>
; __device__ __forceinline__ void gemm_phase(LAS unsigned char* lds, const Gemm g, const Sched& S, const Epi& E) {
;     ...
;             PG8_LDA(At, 1, 1); PG8_STAGE(PG8_SB(1, 0), b3, voffB); PG8_STAGE(PG8_SB(1, 1), b3 + hstepB, voffB); PG8_STAGE(PG8_SA(1, 0), a3, voffA);
;             PG8_WAIT_V(8); PG8_WAIT_L(0); PG8_BAR; PG8_MMA(1, 0, At, B0); PG8_MMA(1, 1, At, B1); PG8_BAR; PG8_SCHED;
;         }
;         if (wr == 0) PG8_BAR;
	s_add_i32 s20, s54, s30
	v_lshl_add_u64 v[164:165], v[164:165], 0, s[6:7]
	s_mov_b32 m0, s20
	ds_read_b128 v[196:199], v170 offset:49152
	ds_read_b128 v[200:203], v170 offset:50176
	ds_read_b128 v[204:207], v170 offset:51200
	ds_read_b128 v[208:211], v170 offset:52224
	ds_read_b128 v[212:215], v170 offset:53248
	ds_read_b128 v[216:219], v170 offset:54272
	ds_read_b128 v[220:223], v170 offset:55296
	ds_read_b128 v[224:227], v170 offset:56320
	global_load_lds_dwordx4 v[164:165], off
	s_add_i32 m0, s20, 0x2000
	s_add_u32 s20, s24, 0xb0080
	v_lshl_add_u64 v[164:165], v[228:229], 0, s[6:7]
	s_addc_u32 s21, s25, 0
	s_add_i32 s24, s55, s30
	global_load_lds_dwordx4 v[164:165], off
	v_lshl_add_u64 v[164:165], s[20:21], 0, v[128:129]
	s_mov_b32 m0, s24
	s_nop 0
	global_load_lds_dwordx4 v[164:165], off
	v_lshl_add_u64 v[164:165], s[20:21], 0, v[130:131]
	s_add_i32 m0, s24, 0x2000
	s_nop 0
	global_load_lds_dwordx4 v[164:165], off
	v_lshl_add_u64 v[164:165], v[230:231], 0, s[6:7]
	s_mov_b32 m0, s39
	s_nop 0
	global_load_lds_dwordx4 v[164:165], off
	v_lshl_add_u64 v[164:165], v[232:233], 0, s[6:7]
	s_mov_b32 m0, s40
	s_nop 0
	global_load_lds_dwordx4 v[164:165], off
	s_waitcnt vmcnt(8) lgkmcnt(0)
	s_barrier
	s_setprio 1
	v_mfma_f32_16x16x32_bf16 v[60:63], v[156:159], v[196:199], v[60:63]
	v_mfma_f32_16x16x32_bf16 v[56:59], v[172:175], v[196:199], v[56:59]
	v_mfma_f32_16x16x32_bf16 v[44:47], v[156:159], v[204:207], v[44:47]
	v_mfma_f32_16x16x32_bf16 v[40:43], v[172:175], v[204:207], v[40:43]
	v_mfma_f32_16x16x32_bf16 v[28:31], v[156:159], v[212:215], v[28:31]
	v_mfma_f32_16x16x32_bf16 v[24:27], v[172:175], v[212:215], v[24:27]
	v_mfma_f32_16x16x32_bf16 v[12:15], v[156:159], v[220:223], v[12:15]
	v_mfma_f32_16x16x32_bf16 v[8:11], v[172:175], v[220:223], v[8:11]
	v_mfma_f32_16x16x32_bf16 v[60:63], v[160:163], v[200:203], v[60:63]
	v_mfma_f32_16x16x32_bf16 v[56:59], v[176:179], v[200:203], v[56:59]
	v_mfma_f32_16x16x32_bf16 v[44:47], v[160:163], v[208:211], v[44:47]
	v_mfma_f32_16x16x32_bf16 v[40:43], v[176:179], v[208:211], v[40:43]
	v_mfma_f32_16x16x32_bf16 v[28:31], v[160:163], v[216:219], v[28:31]
	v_mfma_f32_16x16x32_bf16 v[24:27], v[176:179], v[216:219], v[24:27]
	v_mfma_f32_16x16x32_bf16 v[12:15], v[160:163], v[224:227], v[12:15]
	v_mfma_f32_16x16x32_bf16 v[8:11], v[176:179], v[224:227], v[8:11]
	s_setprio 0
	s_setprio 1
	v_mfma_f32_16x16x32_bf16 v[52:55], v[180:183], v[196:199], v[52:55]
	v_mfma_f32_16x16x32_bf16 v[48:51], v[188:191], v[196:199], v[48:51]
	v_mfma_f32_16x16x32_bf16 v[36:39], v[180:183], v[204:207], v[36:39]
	v_mfma_f32_16x16x32_bf16 v[32:35], v[188:191], v[204:207], v[32:35]
	v_mfma_f32_16x16x32_bf16 v[20:23], v[180:183], v[212:215], v[20:23]
	v_mfma_f32_16x16x32_bf16 v[16:19], v[188:191], v[212:215], v[16:19]
	v_mfma_f32_16x16x32_bf16 v[4:7], v[180:183], v[220:223], v[4:7]
	v_mfma_f32_16x16x32_bf16 v[0:3], v[188:191], v[220:223], v[0:3]
	v_mfma_f32_16x16x32_bf16 v[52:55], v[184:187], v[200:203], v[52:55]
	v_mfma_f32_16x16x32_bf16 v[48:51], v[192:195], v[200:203], v[48:51]
	v_mfma_f32_16x16x32_bf16 v[36:39], v[184:187], v[208:211], v[36:39]
	v_mfma_f32_16x16x32_bf16 v[32:35], v[192:195], v[208:211], v[32:35]
	v_mfma_f32_16x16x32_bf16 v[20:23], v[184:187], v[216:219], v[20:23]
	v_mfma_f32_16x16x32_bf16 v[16:19], v[192:195], v[216:219], v[16:19]
	v_mfma_f32_16x16x32_bf16 v[4:7], v[184:187], v[224:227], v[4:7]
	v_mfma_f32_16x16x32_bf16 v[0:3], v[192:195], v[224:227], v[0:3]
	s_setprio 0
	s_barrier
	s_add_i32 s53, s53, 2
	s_add_u32 s51, s51, 0x100
	s_addc_u32 s52, s52, 0
	s_cmp_gt_u32 s53, 41
	s_mov_b64 s[20:21], s[22:23]
	s_cbranch_scc0 .LBB0_1940
	s_and_b64 vcc, exec, s[8:9]
	s_cbranch_vccz .LBB0_1943
	s_barrier
